# H + grid barrier release path one hop shorter: last cross-XCD arriver bumps every XCD release word itself, other leaders no longer relay
# speedup vs baseline: 1.0096x; 1.0096x over previous
; __device__ __forceinline__ unsigned xb_ld(unsigned* p)              { return __hip_atomic_load(p, __ATOMIC_RELAXED, __HIP_MEMORY_SCOPE_AGENT); }
; __device__ __forceinline__ unsigned xb_add(unsigned* p, unsigned v) { return __hip_atomic_fetch_add(p, v, __ATOMIC_RELAXED, __HIP_MEMORY_SCOPE_AGENT); }
; #define XB_SPIN(cond, bar) do { unsigned _sp = 0; while (cond) { __builtin_amdgcn_s_sleep(1); \
;     if ((++_sp & 255u) == 0u) { if (xb_ld(&(bar)[XB_TMO])) break; if (_sp > XB_SPIN_CAP) { atomicAdd(&(bar)[XB_TMO], 1u); break; } } } } while (0)
; __device__ __forceinline__ void xcd_barrier(const XcdBarrier& b) {
;     ...
;         const unsigned old = xb_add(&bar[XB_XSUB(b.x)], 1u);
;         const unsigned gen = old / nloc;
;         if (old + 1u == (gen + 1u) * nloc) {
;             __builtin_amdgcn_fence(__ATOMIC_RELEASE, "agent");
;             asm volatile("s_waitcnt vmcnt(0)" ::: "memory");
;             const unsigned og = xb_add(&bar[XB_TOP], 1u);
;             const unsigned tg = og / nx;
;             if (og + 1u == (tg + 1u) * nx) xb_add(&bar[XB_TOPGEN], 1u);
;             else XB_SPIN(xb_ld(&bar[XB_TOPGEN]) == tg, bar);
.LBB0_163:
	s_or_b64 exec, exec, s[8:9]
	v_cvt_f32_u32_e32 v3, v0
	s_waitcnt vmcnt(0)
	v_readfirstlane_b32 s3, v2
	s_add_u32 s8, s82, 0x7500
	s_addc_u32 s9, s83, 0
	v_rcp_iflag_f32_e32 v3, v3
	v_add_u32_e32 v1, s3, v1
	v_add_u32_e32 v4, 1, v1
	s_mov_b64 s[10:11], -1
	v_mul_f32_e32 v2, 0x4f7ffffe, v3
	v_cvt_u32_f32_e32 v2, v2
	v_sub_u32_e32 v3, 0, v0
	v_mul_lo_u32 v3, v3, v2
	v_mul_hi_u32 v3, v2, v3
	v_add_u32_e32 v2, v2, v3
	v_mul_hi_u32 v2, v1, v2
	v_mul_lo_u32 v3, v2, v0
	v_sub_u32_e32 v1, v1, v3
	v_add_u32_e32 v5, 1, v2
	v_cmp_ge_u32_e32 vcc, v1, v0
	v_sub_u32_e32 v3, v1, v0
	s_nop 0
	v_cndmask_b32_e32 v2, v2, v5, vcc
	v_cndmask_b32_e32 v1, v1, v3, vcc
	v_add_u32_e32 v3, 1, v2
	v_cmp_ge_u32_e32 vcc, v1, v0
	s_nop 1
	v_cndmask_b32_e32 v2, v2, v3, vcc
	v_mul_lo_u32 v1, v0, v2
	v_add_u32_e32 v0, v1, v0
	v_cmp_ne_u32_e32 vcc, v4, v0
	v_mov_b64_e32 v[0:1], s[8:9]
	s_cbranch_vccnz .Lbar_notlast_1
	v_mov_b32_e32 v3, 0x6400
	v_mov_b32_e32 v5, 1
	global_atomic_add v3, v5, s[82:83]
	global_atomic_add v3, v5, s[82:83] offset:256
	global_atomic_add v3, v5, s[82:83] offset:512
	global_atomic_add v3, v5, s[82:83] offset:768
	global_atomic_add v3, v5, s[82:83] offset:1024
	global_atomic_add v3, v5, s[82:83] offset:1280
	global_atomic_add v3, v5, s[82:83] offset:1536
	global_atomic_add v3, v5, s[82:83] offset:1792
	global_atomic_add v3, v5, s[82:83] offset:2048
	global_atomic_add v3, v5, s[82:83] offset:2304
	global_atomic_add v3, v5, s[82:83] offset:2560
	global_atomic_add v3, v5, s[82:83] offset:2816
	global_atomic_add v3, v5, s[82:83] offset:3072
	global_atomic_add v3, v5, s[82:83] offset:3328
	global_atomic_add v3, v5, s[82:83] offset:3584
	global_atomic_add v3, v5, s[82:83] offset:3840
.Lbar_notlast_1:
	s_and_saveexec_b64 s[6:7], vcc
	s_cbranch_execz .LBB0_175
	v_mov_b32_e32 v0, 0
	global_load_dword v1, v0, s[8:9] sc1
	s_mov_b64 s[28:29], 0
	s_waitcnt vmcnt(0)
	v_cmp_eq_u32_e32 vcc, v1, v2
	s_and_saveexec_b64 s[26:27], vcc
	s_cbranch_execz .LBB0_174
	s_add_u32 s10, s82, 0x4200
	s_addc_u32 s11, s83, 0
	s_mov_b32 s3, 1
	s_branch .LBB0_167

; __device__ __forceinline__ unsigned xb_add(unsigned* p, unsigned v) { return __hip_atomic_fetch_add(p, v, __ATOMIC_RELAXED, __HIP_MEMORY_SCOPE_AGENT); }
; __device__ __forceinline__ void xcd_barrier(const XcdBarrier& b) {
;     ...
;             __builtin_amdgcn_fence(__ATOMIC_ACQUIRE, "agent");
;             xb_add(&bar[XB_XGEN(b.x)], 1u);
;             asm volatile("s_waitcnt vmcnt(0)" ::: "memory");
.LBB0_177:
	s_or_b64 exec, exec, s[6:7]
	s_mov_b64 s[6:7], exec
	v_mbcnt_lo_u32_b32 v0, s6, 0
	v_mbcnt_hi_u32_b32 v0, s7, v0
	v_cmp_eq_u32_e32 vcc, 0, v0
	s_waitcnt vmcnt(0)
	buffer_inv sc1
	s_and_saveexec_b64 s[8:9], vcc
	s_cbranch_execz .LBB0_179
	s_bcnt1_i32_b64 s3, s[6:7]
	v_mov_b32_e32 v0, 0x2000
	v_mov_b32_e32 v1, s3
	s_nop 0

; #define PG8_STAGE(bufoff, gbase, voff) do { _Pragma("unroll") for (int _i = 0; _i < 2; ++_i) \
;         __builtin_amdgcn_global_load_lds((const unsigned*)((const char*)(gbase) + (voff)[_i]), (PG8_LAS unsigned*)(lds + (bufoff) + ldsw + _i * 8192), 16, 0, 0); } while (0)
; #define PG8_LDA(dst, b, h) do { _Pragma("unroll") for (int m = 0; m < 4; ++m) _Pragma("unroll") for (int k = 0; k < 2; ++k) dst[m][k] = *(const PG8_LAS bf16x8*)(lds + PG8_SA(b, h) + aoff + m * 2048 + k * 1024); } while (0)
; #define PG8_LDB(dst, b, h) do { _Pragma("unroll") for (int n = 0; n < 2; ++n) _Pragma("unroll") for (int k = 0; k < 2; ++k) dst[n][k] = *(const PG8_LAS bf16x8*)(lds + PG8_SB(b, h) + boff + n * 2048 + k * 1024); } while (0)
; #define PG8_MMA(ai, bj, At, Bt) do { __builtin_amdgcn_s_setprio(1); _Pragma("unroll") for (int m = 0; m < 4; ++m) _Pragma("unroll") for (int n = 0; n < 2; ++n) _Pragma("unroll") for (int k = 0; k < 2; ++k) \
;         acc[ai][bj][m][n] = __builtin_amdgcn_mfma_f32_16x16x32_bf16(Bt[n][k], At[m][k], acc[ai][bj][m][n], 0, 0, 0); __builtin_amdgcn_s_setprio(0); } while (0)
; template <class Epi, class Sched, bool ALIGN_EPI = false, bool SP2 = false, bool MIDHOOK = false>
; __device__ __forceinline__ void gemm_phase(PG8_LAS unsigned char* lds, const Gemm g, const Sched& S, const Epi& E) {
;     ...
;     f32x4 acc[2][2][4][2];
; #pragma unroll
;     for (int a = 0; a < 2; ++a)
; #pragma unroll
;         for (int b = 0; b < 2; ++b)
; #pragma unroll
;             for (int m = 0; m < 4; ++m)
; #pragma unroll
;                 for (int n = 0; n < 2; ++n) acc[a][b][m][n] = (f32x4){0.f, 0.f, 0.f, 0.f};
;     ...
;         for (int t = 0; t < nt; t += 2) {
;             if constexpr (MIDHOOK) { if (t == nt / 2) E.mid(acc, cur, wr, wc, fr, fq); }
;             const bool last = (t == nt - 2);
;             const char* a1 = cA + (size_t)(t + 1) * kstep;
;             const char* a2 = last ? nA : cA + (size_t)(t + 2) * kstep; const char* b2 = last ? nB : cB + (size_t)(t + 2) * kstep;
;             const char* a3 = a2 + kstep; const char* b3 = b2 + kstep;
;             if (last && has_next) S.a_ready(nxt);
;             if constexpr (SP2) {
;             PG8_LDB(B0, 0, 0); PG8_LDB(B1, 0, 1); PG8_SCHED; PG8_LDA(At, 0, 0); PG8_STAGE(PG8_SA(1, 1), a1 + hstep, voffA);
;             PG8_WAIT_V(8); PG8_WAIT_L(0); PG8_BAR; PG8_MMA(0, 0, At, B0); PG8_MMA(0, 1, At, B1); PG8_BAR; PG8_SCHED;
.LBB0_190:
	s_ashr_i32 s41, s40, 31
	s_lshl_b64 s[42:43], s[40:41], 19
	v_readlane_b32 s12, v243, 48
	v_readlane_b32 s13, v243, 49
	s_add_u32 s42, s12, s42
	s_addc_u32 s43, s13, s43
	s_and_b64 s[44:45], s[0:1], exec
	s_cselect_b32 s5, s43, s7
	s_cselect_b32 s41, s42, s6
	s_ashr_i32 s39, s38, 31
	s_lshl_b64 s[44:45], s[38:39], 19
	s_add_u32 s44, s24, s44
	s_addc_u32 s45, s25, s45
	s_and_b64 s[48:49], s[0:1], exec
	s_cselect_b32 s39, s45, s9
	s_cselect_b32 s62, s44, s8
	s_add_u32 s6, s6, 0x40080
	s_addc_u32 s7, s7, 0
	s_add_u32 s63, s8, 0x100
	v_mov_b32_e32 v0, 0
	s_addc_u32 s64, s9, 0
	s_mov_b32 s65, -2
	v_mov_b32_e32 v1, v0
	v_mov_b32_e32 v2, v0
	v_mov_b32_e32 v3, v0
	v_mov_b32_e32 v8, v0
	v_mov_b32_e32 v9, v0
	v_mov_b32_e32 v10, v0
	v_mov_b32_e32 v11, v0
	v_mov_b32_e32 v16, v0
	v_mov_b32_e32 v17, v0
	v_mov_b32_e32 v18, v0
	v_mov_b32_e32 v19, v0
	v_mov_b32_e32 v24, v0
	v_mov_b32_e32 v25, v0
	v_mov_b32_e32 v26, v0
	v_mov_b32_e32 v27, v0
	v_mov_b32_e32 v32, v0
	v_mov_b32_e32 v33, v0
	v_mov_b32_e32 v34, v0
	v_mov_b32_e32 v35, v0
	v_mov_b32_e32 v40, v0
	v_mov_b32_e32 v41, v0
	v_mov_b32_e32 v42, v0
	v_mov_b32_e32 v43, v0
	v_mov_b32_e32 v48, v0
	v_mov_b32_e32 v49, v0
	v_mov_b32_e32 v50, v0
	v_mov_b32_e32 v51, v0
	v_mov_b32_e32 v56, v0
	v_mov_b32_e32 v57, v0
	v_mov_b32_e32 v58, v0
	v_mov_b32_e32 v59, v0
	v_mov_b32_e32 v4, v0
	v_mov_b32_e32 v5, v0
	v_mov_b32_e32 v6, v0
	v_mov_b32_e32 v7, v0
	v_mov_b32_e32 v12, v0
	v_mov_b32_e32 v13, v0
	v_mov_b32_e32 v14, v0
	v_mov_b32_e32 v15, v0
	v_mov_b32_e32 v20, v0
	v_mov_b32_e32 v21, v0
	v_mov_b32_e32 v22, v0
	v_mov_b32_e32 v23, v0
	v_mov_b32_e32 v28, v0
	v_mov_b32_e32 v29, v0
	v_mov_b32_e32 v30, v0
	v_mov_b32_e32 v31, v0
	v_mov_b32_e32 v36, v0
	v_mov_b32_e32 v37, v0
	v_mov_b32_e32 v38, v0
	v_mov_b32_e32 v39, v0
	v_mov_b32_e32 v44, v0
	v_mov_b32_e32 v45, v0
	v_mov_b32_e32 v46, v0
	v_mov_b32_e32 v47, v0
	v_mov_b32_e32 v52, v0
	v_mov_b32_e32 v53, v0
	v_mov_b32_e32 v54, v0
	v_mov_b32_e32 v55, v0
	v_mov_b32_e32 v60, v0
	v_mov_b32_e32 v61, v0
	v_mov_b32_e32 v62, v0
	v_mov_b32_e32 v63, v0
	v_mov_b32_e32 v64, v0
	v_mov_b32_e32 v65, v0
	v_mov_b32_e32 v66, v0
	v_mov_b32_e32 v67, v0
	v_mov_b32_e32 v72, v0
	v_mov_b32_e32 v73, v0
	v_mov_b32_e32 v74, v0
	v_mov_b32_e32 v75, v0
	v_mov_b32_e32 v80, v0
	v_mov_b32_e32 v81, v0
	v_mov_b32_e32 v82, v0
	v_mov_b32_e32 v83, v0
	v_mov_b32_e32 v88, v0
	v_mov_b32_e32 v89, v0
	v_mov_b32_e32 v90, v0
	v_mov_b32_e32 v91, v0
	v_mov_b32_e32 v96, v0
	v_mov_b32_e32 v97, v0
	v_mov_b32_e32 v98, v0
	v_mov_b32_e32 v99, v0
	v_mov_b32_e32 v104, v0
	v_mov_b32_e32 v105, v0
	v_mov_b32_e32 v106, v0
	v_mov_b32_e32 v107, v0
	v_mov_b32_e32 v112, v0
	v_mov_b32_e32 v113, v0
	v_mov_b32_e32 v114, v0
	v_mov_b32_e32 v115, v0
	v_mov_b32_e32 v120, v0
	v_mov_b32_e32 v121, v0
	v_mov_b32_e32 v122, v0
	v_mov_b32_e32 v123, v0
	v_mov_b32_e32 v68, v0
	v_mov_b32_e32 v69, v0
	v_mov_b32_e32 v70, v0
	v_mov_b32_e32 v71, v0
	v_mov_b32_e32 v76, v0
	v_mov_b32_e32 v77, v0
	v_mov_b32_e32 v78, v0
	v_mov_b32_e32 v79, v0
	v_mov_b32_e32 v84, v0
	v_mov_b32_e32 v85, v0
	v_mov_b32_e32 v86, v0
	v_mov_b32_e32 v87, v0
	v_mov_b32_e32 v92, v0
	v_mov_b32_e32 v93, v0
	v_mov_b32_e32 v94, v0
	v_mov_b32_e32 v95, v0
	v_mov_b32_e32 v100, v0
	v_mov_b32_e32 v101, v0
	v_mov_b32_e32 v102, v0
	v_mov_b32_e32 v103, v0
	v_mov_b32_e32 v108, v0
	v_mov_b32_e32 v109, v0
	v_mov_b32_e32 v110, v0
	v_mov_b32_e32 v111, v0
	v_mov_b32_e32 v116, v0
	v_mov_b32_e32 v117, v0
	v_mov_b32_e32 v118, v0
	v_mov_b32_e32 v119, v0
	v_mov_b32_e32 v124, v0
	v_mov_b32_e32 v125, v0
	v_mov_b32_e32 v126, v0
	v_mov_b32_e32 v127, v0
	s_nop 0
	s_nop 0
	s_nop 0
.LBB0_191:
	ds_read_b128 v[128:131], v180
	s_waitcnt vmcnt(0)
	ds_read_b128 v[132:135], v180 offset:1024
	ds_read_b128 v[136:139], v180 offset:2048
	ds_read_b128 v[168:171], v180 offset:3072
	ds_read_b128 v[172:175], v181
	ds_read_b128 v[184:187], v181 offset:1024
	ds_read_b128 v[188:191], v181 offset:2048
	ds_read_b128 v[192:195], v181 offset:3072
	s_add_u32 s8, s6, 0xfffc0080
	s_addc_u32 s9, s7, -1
	s_cmp_eq_u32 s65, 12
	s_cselect_b32 s49, s5, s9
	s_cselect_b32 s48, s41, s8
	s_cselect_b32 s9, s39, s64
	s_cselect_b32 s8, s62, s63
	v_lshl_add_u64 v[230:231], s[6:7], 0, v[156:157]
	s_add_i32 m0, s47, 0xc000
	ds_read_b128 v[196:199], v182
	ds_read_b128 v[200:203], v182 offset:1024
	ds_read_b128 v[204:207], v182 offset:2048
	ds_read_b128 v[208:211], v182 offset:3072
	ds_read_b128 v[212:215], v182 offset:4096
	ds_read_b128 v[216:219], v182 offset:5120
	ds_read_b128 v[222:225], v182 offset:6144
	ds_read_b128 v[226:229], v182 offset:7168
	global_load_lds_dwordx4 v[230:231], off
	v_lshl_add_u64 v[230:231], s[6:7], 0, v[158:159]
	s_add_i32 m0, s47, 0xe000
	s_nop 0
	global_load_lds_dwordx4 v[230:231], off
	s_waitcnt vmcnt(8)
	s_waitcnt lgkmcnt(0)
	s_barrier
; #define PG8_STAGE(bufoff, gbase, voff) do { _Pragma("unroll") for (int _i = 0; _i < 2; ++_i) \
;         __builtin_amdgcn_global_load_lds((const unsigned*)((const char*)(gbase) + (voff)[_i]), (PG8_LAS unsigned*)(lds + (bufoff) + ldsw + _i * 8192), 16, 0, 0); } while (0)
; #define PG8_LDA(dst, b, h) do { _Pragma("unroll") for (int m = 0; m < 4; ++m) _Pragma("unroll") for (int k = 0; k < 2; ++k) dst[m][k] = *(const PG8_LAS bf16x8*)(lds + PG8_SA(b, h) + aoff + m * 2048 + k * 1024); } while (0)
; #define PG8_LDB(dst, b, h) do { _Pragma("unroll") for (int n = 0; n < 2; ++n) _Pragma("unroll") for (int k = 0; k < 2; ++k) dst[n][k] = *(const PG8_LAS bf16x8*)(lds + PG8_SB(b, h) + boff + n * 2048 + k * 1024); } while (0)
; #define PG8_MMA(ai, bj, At, Bt) do { __builtin_amdgcn_s_setprio(1); _Pragma("unroll") for (int m = 0; m < 4; ++m) _Pragma("unroll") for (int n = 0; n < 2; ++n) _Pragma("unroll") for (int k = 0; k < 2; ++k) \
;         acc[ai][bj][m][n] = __builtin_amdgcn_mfma_f32_16x16x32_bf16(Bt[n][k], At[m][k], acc[ai][bj][m][n], 0, 0, 0); __builtin_amdgcn_s_setprio(0); } while (0)
; #define PG8_WAIT_V(n) asm volatile("s_waitcnt vmcnt(" #n ")" ::: "memory")
; #define PG8_WAIT_L(n) asm volatile("s_waitcnt lgkmcnt(" #n ")" ::: "memory")
; #define PG8_BAR __builtin_amdgcn_s_barrier()
; #define PG8_SCHED __builtin_amdgcn_sched_barrier(0)
; template <class Epi, class Sched, bool ALIGN_EPI = false, bool SP2 = false, bool MIDHOOK = false>
; __device__ __forceinline__ void gemm_phase(PG8_LAS unsigned char* lds, const Gemm g, const Sched& S, const Epi& E) {
;     ...
;             PG8_LDB(B0, 0, 0); PG8_LDB(B1, 0, 1); PG8_SCHED; PG8_LDA(At, 0, 0); PG8_STAGE(PG8_SA(1, 1), a1 + hstep, voffA);
;             PG8_WAIT_V(8); PG8_WAIT_L(0); PG8_BAR; PG8_MMA(0, 0, At, B0); PG8_MMA(0, 1, At, B1); PG8_BAR; PG8_SCHED;
;             PG8_LDA(At, 0, 1); PG8_STAGE(PG8_SB(0, 0), b2, voffB); PG8_STAGE(PG8_SB(0, 1), b2 + hstep, voffB); PG8_STAGE(PG8_SA(0, 0), a2, voffA);
;             PG8_WAIT_V(8); PG8_WAIT_L(0); PG8_BAR; PG8_MMA(1, 0, At, B0); PG8_MMA(1, 1, At, B1); PG8_BAR; PG8_SCHED;
	s_setprio 1
	s_waitcnt lgkmcnt(0)
	v_mfma_f32_16x16x32_bf16 v[124:127], v[128:131], v[196:199], v[124:127]
	v_mfma_f32_16x16x32_bf16 v[116:119], v[136:139], v[196:199], v[116:119]
	v_mfma_f32_16x16x32_bf16 v[108:111], v[128:131], v[204:207], v[108:111]
	v_mfma_f32_16x16x32_bf16 v[100:103], v[136:139], v[204:207], v[100:103]
	v_mfma_f32_16x16x32_bf16 v[92:95], v[128:131], v[212:215], v[92:95]
	v_mfma_f32_16x16x32_bf16 v[84:87], v[136:139], v[212:215], v[84:87]
	v_mfma_f32_16x16x32_bf16 v[76:79], v[128:131], v[222:225], v[76:79]
	v_mfma_f32_16x16x32_bf16 v[68:71], v[136:139], v[222:225], v[68:71]
	v_mfma_f32_16x16x32_bf16 v[124:127], v[132:135], v[200:203], v[124:127]
	v_mfma_f32_16x16x32_bf16 v[116:119], v[168:171], v[200:203], v[116:119]
	v_mfma_f32_16x16x32_bf16 v[108:111], v[132:135], v[208:211], v[108:111]
	v_mfma_f32_16x16x32_bf16 v[100:103], v[168:171], v[208:211], v[100:103]
	v_mfma_f32_16x16x32_bf16 v[92:95], v[132:135], v[216:219], v[92:95]
	v_mfma_f32_16x16x32_bf16 v[84:87], v[168:171], v[216:219], v[84:87]
	v_mfma_f32_16x16x32_bf16 v[76:79], v[132:135], v[226:229], v[76:79]
	v_mfma_f32_16x16x32_bf16 v[68:71], v[168:171], v[226:229], v[68:71]
	s_setprio 0
	s_setprio 1
	v_mfma_f32_16x16x32_bf16 v[120:123], v[172:175], v[196:199], v[120:123]
	v_mfma_f32_16x16x32_bf16 v[112:115], v[188:191], v[196:199], v[112:115]
	v_mfma_f32_16x16x32_bf16 v[104:107], v[172:175], v[204:207], v[104:107]
	v_mfma_f32_16x16x32_bf16 v[96:99], v[188:191], v[204:207], v[96:99]
	v_mfma_f32_16x16x32_bf16 v[88:91], v[172:175], v[212:215], v[88:91]
	v_mfma_f32_16x16x32_bf16 v[80:83], v[188:191], v[212:215], v[80:83]
	v_mfma_f32_16x16x32_bf16 v[72:75], v[172:175], v[222:225], v[72:75]
	v_mfma_f32_16x16x32_bf16 v[64:67], v[188:191], v[222:225], v[64:67]
	v_mfma_f32_16x16x32_bf16 v[120:123], v[184:187], v[200:203], v[120:123]
	v_mfma_f32_16x16x32_bf16 v[112:115], v[192:195], v[200:203], v[112:115]
	v_mfma_f32_16x16x32_bf16 v[104:107], v[184:187], v[208:211], v[104:107]
	v_mfma_f32_16x16x32_bf16 v[96:99], v[192:195], v[208:211], v[96:99]
	v_mfma_f32_16x16x32_bf16 v[88:91], v[184:187], v[216:219], v[88:91]
	v_mfma_f32_16x16x32_bf16 v[80:83], v[192:195], v[216:219], v[80:83]
	v_mfma_f32_16x16x32_bf16 v[72:75], v[184:187], v[226:229], v[72:75]
	v_mfma_f32_16x16x32_bf16 v[64:67], v[192:195], v[226:229], v[64:67]
	s_setprio 0
	s_barrier
	s_add_i32 s66, s58, s3
	v_lshl_add_u64 v[230:231], s[8:9], 0, v[142:143]
	s_mov_b32 m0, s66
	ds_read_b128 v[196:199], v182 offset:16384
	ds_read_b128 v[200:203], v182 offset:17408
	ds_read_b128 v[204:207], v182 offset:18432
	ds_read_b128 v[208:211], v182 offset:19456
	ds_read_b128 v[212:215], v182 offset:20480
	ds_read_b128 v[216:219], v182 offset:21504
	ds_read_b128 v[222:225], v182 offset:22528
	ds_read_b128 v[226:229], v182 offset:23552
	global_load_lds_dwordx4 v[230:231], off
	s_add_i32 m0, s66, 0x2000
	s_add_u32 s66, s8, 0x40000
	v_lshl_add_u64 v[232:233], s[8:9], 0, v[146:147]
	s_addc_u32 s67, s9, 0
	s_add_i32 s68, s59, s3
	global_load_lds_dwordx4 v[232:233], off
	v_lshl_add_u64 v[234:235], s[66:67], 0, v[142:143]
	s_mov_b32 m0, s68
	v_lshl_add_u64 v[236:237], s[48:49], 0, v[144:145]
	global_load_lds_dwordx4 v[234:235], off
	v_lshl_add_u64 v[234:235], s[66:67], 0, v[146:147]
	s_add_i32 m0, s68, 0x2000
	s_nop 0
	global_load_lds_dwordx4 v[234:235], off
	v_lshl_add_u64 v[234:235], s[48:49], 0, v[140:141]
	s_mov_b32 m0, s47
	s_nop 0
	global_load_lds_dwordx4 v[234:235], off
	s_mov_b32 m0, s50
	s_nop 0
	global_load_lds_dwordx4 v[236:237], off
	s_waitcnt vmcnt(8)
	s_waitcnt lgkmcnt(0)
	s_barrier
	s_setprio 1
	s_waitcnt lgkmcnt(0)
	v_mfma_f32_16x16x32_bf16 v[60:63], v[128:131], v[196:199], v[60:63]
	v_mfma_f32_16x16x32_bf16 v[52:55], v[136:139], v[196:199], v[52:55]
	v_mfma_f32_16x16x32_bf16 v[44:47], v[128:131], v[204:207], v[44:47]
	v_mfma_f32_16x16x32_bf16 v[36:39], v[136:139], v[204:207], v[36:39]
	v_mfma_f32_16x16x32_bf16 v[28:31], v[128:131], v[212:215], v[28:31]
	v_mfma_f32_16x16x32_bf16 v[20:23], v[136:139], v[212:215], v[20:23]
	v_mfma_f32_16x16x32_bf16 v[12:15], v[128:131], v[222:225], v[12:15]
	v_mfma_f32_16x16x32_bf16 v[4:7], v[136:139], v[222:225], v[4:7]
	v_mfma_f32_16x16x32_bf16 v[60:63], v[132:135], v[200:203], v[60:63]
	v_mfma_f32_16x16x32_bf16 v[52:55], v[168:171], v[200:203], v[52:55]
	v_mfma_f32_16x16x32_bf16 v[44:47], v[132:135], v[208:211], v[44:47]
	v_mfma_f32_16x16x32_bf16 v[36:39], v[168:171], v[208:211], v[36:39]
	v_mfma_f32_16x16x32_bf16 v[28:31], v[132:135], v[216:219], v[28:31]
	v_mfma_f32_16x16x32_bf16 v[20:23], v[168:171], v[216:219], v[20:23]
	v_mfma_f32_16x16x32_bf16 v[12:15], v[132:135], v[226:229], v[12:15]
	v_mfma_f32_16x16x32_bf16 v[4:7], v[168:171], v[226:229], v[4:7]
	s_setprio 0
	s_setprio 1
	v_mfma_f32_16x16x32_bf16 v[56:59], v[172:175], v[196:199], v[56:59]
	v_mfma_f32_16x16x32_bf16 v[48:51], v[188:191], v[196:199], v[48:51]
	v_mfma_f32_16x16x32_bf16 v[40:43], v[172:175], v[204:207], v[40:43]
	v_mfma_f32_16x16x32_bf16 v[32:35], v[188:191], v[204:207], v[32:35]
	v_mfma_f32_16x16x32_bf16 v[24:27], v[172:175], v[212:215], v[24:27]
	v_mfma_f32_16x16x32_bf16 v[16:19], v[188:191], v[212:215], v[16:19]
	v_mfma_f32_16x16x32_bf16 v[8:11], v[172:175], v[222:225], v[8:11]
	v_mfma_f32_16x16x32_bf16 v[0:3], v[188:191], v[222:225], v[0:3]
	v_mfma_f32_16x16x32_bf16 v[56:59], v[184:187], v[200:203], v[56:59]
	v_mfma_f32_16x16x32_bf16 v[48:51], v[192:195], v[200:203], v[48:51]
	v_mfma_f32_16x16x32_bf16 v[40:43], v[184:187], v[208:211], v[40:43]
	v_mfma_f32_16x16x32_bf16 v[32:35], v[192:195], v[208:211], v[32:35]
	v_mfma_f32_16x16x32_bf16 v[24:27], v[184:187], v[216:219], v[24:27]
	v_mfma_f32_16x16x32_bf16 v[16:19], v[192:195], v[216:219], v[16:19]
	v_mfma_f32_16x16x32_bf16 v[8:11], v[184:187], v[226:229], v[8:11]
	v_mfma_f32_16x16x32_bf16 v[0:3], v[192:195], v[226:229], v[0:3]
	s_setprio 0
	s_barrier
; #define PG8_STAGE(bufoff, gbase, voff) do { _Pragma("unroll") for (int _i = 0; _i < 2; ++_i) \
;         __builtin_amdgcn_global_load_lds((const unsigned*)((const char*)(gbase) + (voff)[_i]), (PG8_LAS unsigned*)(lds + (bufoff) + ldsw + _i * 8192), 16, 0, 0); } while (0)
; #define PG8_LDA(dst, b, h) do { _Pragma("unroll") for (int m = 0; m < 4; ++m) _Pragma("unroll") for (int k = 0; k < 2; ++k) dst[m][k] = *(const PG8_LAS bf16x8*)(lds + PG8_SA(b, h) + aoff + m * 2048 + k * 1024); } while (0)
; #define PG8_LDB(dst, b, h) do { _Pragma("unroll") for (int n = 0; n < 2; ++n) _Pragma("unroll") for (int k = 0; k < 2; ++k) dst[n][k] = *(const PG8_LAS bf16x8*)(lds + PG8_SB(b, h) + boff + n * 2048 + k * 1024); } while (0)
; #define PG8_MMA(ai, bj, At, Bt) do { __builtin_amdgcn_s_setprio(1); _Pragma("unroll") for (int m = 0; m < 4; ++m) _Pragma("unroll") for (int n = 0; n < 2; ++n) _Pragma("unroll") for (int k = 0; k < 2; ++k) \
;         acc[ai][bj][m][n] = __builtin_amdgcn_mfma_f32_16x16x32_bf16(Bt[n][k], At[m][k], acc[ai][bj][m][n], 0, 0, 0); __builtin_amdgcn_s_setprio(0); } while (0)
; #define PG8_WAIT_V(n) asm volatile("s_waitcnt vmcnt(" #n ")" ::: "memory")
; #define PG8_WAIT_L(n) asm volatile("s_waitcnt lgkmcnt(" #n ")" ::: "memory")
; #define PG8_BAR __builtin_amdgcn_s_barrier()
; #define PG8_SCHED __builtin_amdgcn_sched_barrier(0)
; template <class Epi, class Sched, bool ALIGN_EPI = false, bool SP2 = false, bool MIDHOOK = false>
; __device__ __forceinline__ void gemm_phase(PG8_LAS unsigned char* lds, const Gemm g, const Sched& S, const Epi& E) {
;     ...
;             PG8_LDB(B0, 1, 0); PG8_LDB(B1, 1, 1); PG8_SCHED; PG8_LDA(At, 1, 0); PG8_STAGE(PG8_SA(0, 1), a2 + hstep, voffA);
;             PG8_WAIT_V(8); PG8_WAIT_L(0); PG8_BAR; PG8_MMA(0, 0, At, B0); PG8_MMA(0, 1, At, B1); PG8_BAR; PG8_SCHED;
	s_add_i32 s66, 0, 0x18000
	v_add_u32_e32 v148, s66, v177
	s_add_i32 s67, 0, 0x1c000
	ds_read_b128 v[128:131], v148
	ds_read_b128 v[132:135], v148 offset:1024
	ds_read_b128 v[136:139], v148 offset:2048
	ds_read_b128 v[168:171], v148 offset:3072
	v_add_u32_e32 v148, s67, v177
	ds_read_b128 v[172:175], v148
	ds_read_b128 v[184:187], v148 offset:1024
	ds_read_b128 v[188:191], v148 offset:2048
	ds_read_b128 v[192:195], v148 offset:3072
	s_add_u32 s48, s48, 0x40000
	s_addc_u32 s49, s49, 0
	s_mov_b32 m0, s51
	v_lshl_add_u64 v[238:239], s[48:49], 0, v[140:141]
	ds_read_b128 v[196:199], v182 offset:32768
	ds_read_b128 v[200:203], v182 offset:33792
	ds_read_b128 v[204:207], v182 offset:34816
	ds_read_b128 v[208:211], v182 offset:35840
	ds_read_b128 v[212:215], v182 offset:36864
	ds_read_b128 v[216:219], v182 offset:37888
	ds_read_b128 v[222:225], v182 offset:38912
	ds_read_b128 v[226:229], v182 offset:39936
	global_load_lds_dwordx4 v[238:239], off
	v_lshl_add_u64 v[238:239], s[48:49], 0, v[144:145]
	s_mov_b32 m0, s52
	s_nop 0
	global_load_lds_dwordx4 v[238:239], off
	s_waitcnt vmcnt(8)
	s_waitcnt lgkmcnt(0)
	s_barrier
	s_setprio 1
	s_waitcnt lgkmcnt(0)
	v_mfma_f32_16x16x32_bf16 v[124:127], v[128:131], v[196:199], v[124:127]
	v_mfma_f32_16x16x32_bf16 v[116:119], v[136:139], v[196:199], v[116:119]
	v_mfma_f32_16x16x32_bf16 v[108:111], v[128:131], v[204:207], v[108:111]
	v_mfma_f32_16x16x32_bf16 v[100:103], v[136:139], v[204:207], v[100:103]
	v_mfma_f32_16x16x32_bf16 v[92:95], v[128:131], v[212:215], v[92:95]
	v_mfma_f32_16x16x32_bf16 v[84:87], v[136:139], v[212:215], v[84:87]
	v_mfma_f32_16x16x32_bf16 v[76:79], v[128:131], v[222:225], v[76:79]
	v_mfma_f32_16x16x32_bf16 v[68:71], v[136:139], v[222:225], v[68:71]
	v_mfma_f32_16x16x32_bf16 v[124:127], v[132:135], v[200:203], v[124:127]
	v_mfma_f32_16x16x32_bf16 v[116:119], v[168:171], v[200:203], v[116:119]
	v_mfma_f32_16x16x32_bf16 v[108:111], v[132:135], v[208:211], v[108:111]
	v_mfma_f32_16x16x32_bf16 v[100:103], v[168:171], v[208:211], v[100:103]
	v_mfma_f32_16x16x32_bf16 v[92:95], v[132:135], v[216:219], v[92:95]
	v_mfma_f32_16x16x32_bf16 v[84:87], v[168:171], v[216:219], v[84:87]
	v_mfma_f32_16x16x32_bf16 v[76:79], v[132:135], v[226:229], v[76:79]
	v_mfma_f32_16x16x32_bf16 v[68:71], v[168:171], v[226:229], v[68:71]
	s_setprio 0
	s_setprio 1
	v_mfma_f32_16x16x32_bf16 v[120:123], v[172:175], v[196:199], v[120:123]
	v_mfma_f32_16x16x32_bf16 v[112:115], v[188:191], v[196:199], v[112:115]
	v_mfma_f32_16x16x32_bf16 v[104:107], v[172:175], v[204:207], v[104:107]
	v_mfma_f32_16x16x32_bf16 v[96:99], v[188:191], v[204:207], v[96:99]
	v_mfma_f32_16x16x32_bf16 v[88:91], v[172:175], v[212:215], v[88:91]
	v_mfma_f32_16x16x32_bf16 v[80:83], v[188:191], v[212:215], v[80:83]
	v_mfma_f32_16x16x32_bf16 v[72:75], v[172:175], v[222:225], v[72:75]
	v_mfma_f32_16x16x32_bf16 v[64:67], v[188:191], v[222:225], v[64:67]
	v_mfma_f32_16x16x32_bf16 v[120:123], v[184:187], v[200:203], v[120:123]
	v_mfma_f32_16x16x32_bf16 v[112:115], v[192:195], v[200:203], v[112:115]
	v_mfma_f32_16x16x32_bf16 v[104:107], v[184:187], v[208:211], v[104:107]
	v_mfma_f32_16x16x32_bf16 v[96:99], v[192:195], v[208:211], v[96:99]
	v_mfma_f32_16x16x32_bf16 v[88:91], v[184:187], v[216:219], v[88:91]
	v_mfma_f32_16x16x32_bf16 v[80:83], v[192:195], v[216:219], v[80:83]
	v_mfma_f32_16x16x32_bf16 v[72:75], v[184:187], v[226:229], v[72:75]
	v_mfma_f32_16x16x32_bf16 v[64:67], v[192:195], v[226:229], v[64:67]
	s_setprio 0
	s_barrier
; #define PG8_STAGE(bufoff, gbase, voff) do { _Pragma("unroll") for (int _i = 0; _i < 2; ++_i) \
;         __builtin_amdgcn_global_load_lds((const unsigned*)((const char*)(gbase) + (voff)[_i]), (PG8_LAS unsigned*)(lds + (bufoff) + ldsw + _i * 8192), 16, 0, 0); } while (0)
; #define PG8_LDA(dst, b, h) do { _Pragma("unroll") for (int m = 0; m < 4; ++m) _Pragma("unroll") for (int k = 0; k < 2; ++k) dst[m][k] = *(const PG8_LAS bf16x8*)(lds + PG8_SA(b, h) + aoff + m * 2048 + k * 1024); } while (0)
; #define PG8_BAR __builtin_amdgcn_s_barrier()
; template <class Epi, class Sched, bool ALIGN_EPI = false, bool SP2 = false, bool MIDHOOK = false>
; __device__ __forceinline__ void gemm_phase(PG8_LAS unsigned char* lds, const Gemm g, const Sched& S, const Epi& E) {
;     ...
;             PG8_LDA(At, 1, 1); PG8_STAGE(PG8_SB(1, 0), b3, voffB); PG8_STAGE(PG8_SB(1, 1), b3 + hstep, voffB); PG8_STAGE(PG8_SA(1, 0), a3, voffA);
;             PG8_WAIT_V(8); PG8_WAIT_L(0); PG8_BAR; PG8_MMA(1, 0, At, B0); PG8_MMA(1, 1, At, B1); PG8_BAR; PG8_SCHED;
;             } else {
;             PG8_LDB(B0, 0, 0); PG8_SCHED; PG8_LDA(At, 0, 0); PG8_STAGE(PG8_SA(1, 1), a1 + hstep, voffA);
;             PG8_WAIT_L(8); PG8_BAR; PG8_WAIT_L(0); PG8_MMA(0, 0, At, B0); PG8_BAR; PG8_SCHED;
;             PG8_LDB(B1, 0, 1); PG8_STAGE(PG8_SB(0, 0), b2, voffB);
;             PG8_BAR; PG8_WAIT_L(0); PG8_MMA(0, 1, At, B1); PG8_BAR;
;             PG8_LDA(At, 0, 1); PG8_STAGE(PG8_SA(0, 0), a2, voffA);
;             PG8_BAR; PG8_WAIT_L(0); PG8_MMA(1, 0, At, B0); PG8_BAR; PG8_SCHED;
;             PG8_STAGE(PG8_SB(0, 1), b2 + hstep, voffB);
;             PG8_WAIT_V(6); PG8_BAR; PG8_MMA(1, 1, At, B1); PG8_BAR;
;             PG8_LDB(B0, 1, 0); PG8_SCHED; PG8_LDA(At, 1, 0); PG8_STAGE(PG8_SA(0, 1), a2 + hstep, voffA);
;             PG8_WAIT_L(8); PG8_BAR; PG8_WAIT_L(0); PG8_MMA(0, 0, At, B0); PG8_BAR; PG8_SCHED;
;             PG8_LDB(B1, 1, 1); PG8_STAGE(PG8_SB(1, 0), b3, voffB);
;             PG8_BAR; PG8_WAIT_L(0); PG8_MMA(0, 1, At, B1); PG8_BAR;
;             PG8_LDA(At, 1, 1); PG8_STAGE(PG8_SA(1, 0), a3, voffA);
;             PG8_BAR; PG8_WAIT_L(0); PG8_MMA(1, 0, At, B0); PG8_BAR; PG8_SCHED;
;             PG8_STAGE(PG8_SB(1, 1), b3 + hstep, voffB);
;             PG8_WAIT_V(6); PG8_BAR; PG8_MMA(1, 1, At, B1); PG8_BAR;
;             }
;         }
;         if constexpr (ALIGN_EPI) { if (wr == 0) PG8_BAR; }
	s_add_i32 s48, s66, s3
	v_lshl_add_u64 v[230:231], v[230:231], 0, s[34:35]
	s_mov_b32 m0, s48
	ds_read_b128 v[196:199], v182 offset:49152
	ds_read_b128 v[200:203], v182 offset:50176
	ds_read_b128 v[204:207], v182 offset:51200
	ds_read_b128 v[208:211], v182 offset:52224
	ds_read_b128 v[212:215], v182 offset:53248
	ds_read_b128 v[216:219], v182 offset:54272
	ds_read_b128 v[222:225], v182 offset:55296
	ds_read_b128 v[226:229], v182 offset:56320
	global_load_lds_dwordx4 v[230:231], off
	s_add_i32 m0, s48, 0x2000
	s_add_u32 s8, s8, 0x40080
	v_lshl_add_u64 v[230:231], v[232:233], 0, s[34:35]
	s_addc_u32 s9, s9, 0
	s_add_i32 s48, s67, s3
	global_load_lds_dwordx4 v[230:231], off
	v_lshl_add_u64 v[230:231], s[8:9], 0, v[142:143]
	s_mov_b32 m0, s48
	s_nop 0
	global_load_lds_dwordx4 v[230:231], off
	v_lshl_add_u64 v[230:231], s[8:9], 0, v[146:147]
	s_add_i32 m0, s48, 0x2000
	s_nop 0
	global_load_lds_dwordx4 v[230:231], off
	v_lshl_add_u64 v[230:231], v[234:235], 0, s[34:35]
	s_mov_b32 m0, s54
	s_nop 0
	global_load_lds_dwordx4 v[230:231], off
	v_lshl_add_u64 v[230:231], v[236:237], 0, s[34:35]
	s_mov_b32 m0, s55
	s_nop 0
	global_load_lds_dwordx4 v[230:231], off
	s_waitcnt vmcnt(8)
	s_waitcnt lgkmcnt(0)
	s_barrier
	s_setprio 1
	s_waitcnt lgkmcnt(0)
	v_mfma_f32_16x16x32_bf16 v[60:63], v[128:131], v[196:199], v[60:63]
	v_mfma_f32_16x16x32_bf16 v[52:55], v[136:139], v[196:199], v[52:55]
	v_mfma_f32_16x16x32_bf16 v[44:47], v[128:131], v[204:207], v[44:47]
	v_mfma_f32_16x16x32_bf16 v[36:39], v[136:139], v[204:207], v[36:39]
	v_mfma_f32_16x16x32_bf16 v[28:31], v[128:131], v[212:215], v[28:31]
	v_mfma_f32_16x16x32_bf16 v[20:23], v[136:139], v[212:215], v[20:23]
	v_mfma_f32_16x16x32_bf16 v[12:15], v[128:131], v[222:225], v[12:15]
	v_mfma_f32_16x16x32_bf16 v[4:7], v[136:139], v[222:225], v[4:7]
	v_mfma_f32_16x16x32_bf16 v[60:63], v[132:135], v[200:203], v[60:63]
	v_mfma_f32_16x16x32_bf16 v[52:55], v[168:171], v[200:203], v[52:55]
	v_mfma_f32_16x16x32_bf16 v[44:47], v[132:135], v[208:211], v[44:47]
	v_mfma_f32_16x16x32_bf16 v[36:39], v[168:171], v[208:211], v[36:39]
	v_mfma_f32_16x16x32_bf16 v[28:31], v[132:135], v[216:219], v[28:31]
	v_mfma_f32_16x16x32_bf16 v[20:23], v[168:171], v[216:219], v[20:23]
	v_mfma_f32_16x16x32_bf16 v[12:15], v[132:135], v[226:229], v[12:15]
	v_mfma_f32_16x16x32_bf16 v[4:7], v[168:171], v[226:229], v[4:7]
	s_setprio 0
	s_setprio 1
	v_mfma_f32_16x16x32_bf16 v[56:59], v[172:175], v[196:199], v[56:59]
	v_mfma_f32_16x16x32_bf16 v[48:51], v[188:191], v[196:199], v[48:51]
	v_mfma_f32_16x16x32_bf16 v[40:43], v[172:175], v[204:207], v[40:43]
	v_mfma_f32_16x16x32_bf16 v[32:35], v[188:191], v[204:207], v[32:35]
	v_mfma_f32_16x16x32_bf16 v[24:27], v[172:175], v[212:215], v[24:27]
	v_mfma_f32_16x16x32_bf16 v[16:19], v[188:191], v[212:215], v[16:19]
	v_mfma_f32_16x16x32_bf16 v[8:11], v[172:175], v[222:225], v[8:11]
	v_mfma_f32_16x16x32_bf16 v[0:3], v[188:191], v[222:225], v[0:3]
	v_mfma_f32_16x16x32_bf16 v[56:59], v[184:187], v[200:203], v[56:59]
	v_mfma_f32_16x16x32_bf16 v[48:51], v[192:195], v[200:203], v[48:51]
	v_mfma_f32_16x16x32_bf16 v[40:43], v[184:187], v[208:211], v[40:43]
	v_mfma_f32_16x16x32_bf16 v[32:35], v[192:195], v[208:211], v[32:35]
	v_mfma_f32_16x16x32_bf16 v[24:27], v[184:187], v[216:219], v[24:27]
	v_mfma_f32_16x16x32_bf16 v[16:19], v[192:195], v[216:219], v[16:19]
	v_mfma_f32_16x16x32_bf16 v[8:11], v[184:187], v[226:229], v[8:11]
	v_mfma_f32_16x16x32_bf16 v[0:3], v[192:195], v[226:229], v[0:3]
	s_setprio 0
	s_barrier
	s_add_i32 s65, s65, 2
	s_add_u32 s6, s6, 0x100
	s_addc_u32 s7, s7, 0
	s_add_u32 s63, s63, 0x100
	s_addc_u32 s64, s64, 0
	s_cmp_gt_u32 s65, 13
	s_cbranch_scc0 .LBB0_191
	s_and_b64 vcc, exec, s[36:37]
	s_cbranch_vccz .LBB0_194
	s_barrier

; __device__ __forceinline__ unsigned xb_ld(unsigned* p)              { return __hip_atomic_load(p, __ATOMIC_RELAXED, __HIP_MEMORY_SCOPE_AGENT); }
; __device__ __forceinline__ unsigned xb_add(unsigned* p, unsigned v) { return __hip_atomic_fetch_add(p, v, __ATOMIC_RELAXED, __HIP_MEMORY_SCOPE_AGENT); }
; #define XB_SPIN(cond, bar) do { unsigned _sp = 0; while (cond) { __builtin_amdgcn_s_sleep(1); \
;     if ((++_sp & 255u) == 0u) { if (xb_ld(&(bar)[XB_TMO])) break; if (_sp > XB_SPIN_CAP) { atomicAdd(&(bar)[XB_TMO], 1u); break; } } } } while (0)
; __device__ __forceinline__ void xcd_barrier(const XcdBarrier& b) {
;     ...
;         const unsigned old = xb_add(&bar[XB_XSUB(b.x)], 1u);
;         const unsigned gen = old / nloc;
;         if (old + 1u == (gen + 1u) * nloc) {
;             __builtin_amdgcn_fence(__ATOMIC_RELEASE, "agent");
;             asm volatile("s_waitcnt vmcnt(0)" ::: "memory");
;             const unsigned og = xb_add(&bar[XB_TOP], 1u);
;             const unsigned tg = og / nx;
;             if (og + 1u == (tg + 1u) * nx) xb_add(&bar[XB_TOPGEN], 1u);
;             else XB_SPIN(xb_ld(&bar[XB_TOPGEN]) == tg, bar);
.LBB0_415:
	s_or_b64 exec, exec, s[8:9]
	v_cvt_f32_u32_e32 v3, v0
	s_waitcnt vmcnt(0)
	v_readfirstlane_b32 s3, v2
	s_add_u32 s8, s82, 0x7500
	s_addc_u32 s9, s83, 0
	v_rcp_iflag_f32_e32 v3, v3
	v_add_u32_e32 v1, s3, v1
	v_add_u32_e32 v4, 1, v1
	s_mov_b64 s[24:25], -1
	v_mul_f32_e32 v2, 0x4f7ffffe, v3
	v_cvt_u32_f32_e32 v2, v2
	v_sub_u32_e32 v3, 0, v0
	v_mul_lo_u32 v3, v3, v2
	v_mul_hi_u32 v3, v2, v3
	v_add_u32_e32 v2, v2, v3
	v_mul_hi_u32 v2, v1, v2
	v_mul_lo_u32 v3, v2, v0
	v_sub_u32_e32 v1, v1, v3
	v_add_u32_e32 v5, 1, v2
	v_cmp_ge_u32_e32 vcc, v1, v0
	v_sub_u32_e32 v3, v1, v0
	s_nop 0
	v_cndmask_b32_e32 v2, v2, v5, vcc
	v_cndmask_b32_e32 v1, v1, v3, vcc
	v_add_u32_e32 v3, 1, v2
	v_cmp_ge_u32_e32 vcc, v1, v0
	s_nop 1
	v_cndmask_b32_e32 v2, v2, v3, vcc
	v_mul_lo_u32 v1, v0, v2
	v_add_u32_e32 v0, v1, v0
	v_cmp_ne_u32_e32 vcc, v4, v0
	v_mov_b64_e32 v[0:1], s[8:9]
	s_cbranch_vccnz .Lbar_notlast_2
	v_mov_b32_e32 v3, 0x6400
	v_mov_b32_e32 v5, 1
	global_atomic_add v3, v5, s[82:83]
	global_atomic_add v3, v5, s[82:83] offset:256
	global_atomic_add v3, v5, s[82:83] offset:512
	global_atomic_add v3, v5, s[82:83] offset:768
	global_atomic_add v3, v5, s[82:83] offset:1024
	global_atomic_add v3, v5, s[82:83] offset:1280
	global_atomic_add v3, v5, s[82:83] offset:1536
	global_atomic_add v3, v5, s[82:83] offset:1792
	global_atomic_add v3, v5, s[82:83] offset:2048
	global_atomic_add v3, v5, s[82:83] offset:2304
	global_atomic_add v3, v5, s[82:83] offset:2560
	global_atomic_add v3, v5, s[82:83] offset:2816
	global_atomic_add v3, v5, s[82:83] offset:3072
	global_atomic_add v3, v5, s[82:83] offset:3328
	global_atomic_add v3, v5, s[82:83] offset:3584
	global_atomic_add v3, v5, s[82:83] offset:3840
.Lbar_notlast_2:
	s_and_saveexec_b64 s[6:7], vcc
	s_cbranch_execz .LBB0_427
	v_mov_b32_e32 v0, 0
	global_load_dword v1, v0, s[8:9] sc1
	s_mov_b64 s[30:31], 0
	s_waitcnt vmcnt(0)
	v_cmp_eq_u32_e32 vcc, v1, v2
	s_and_saveexec_b64 s[28:29], vcc
	s_cbranch_execz .LBB0_426
	s_add_u32 s24, s82, 0x4200
	s_addc_u32 s25, s83, 0
	s_mov_b32 s3, 1
	s_branch .LBB0_419

; __device__ __forceinline__ unsigned xb_ld(unsigned* p)              { return __hip_atomic_load(p, __ATOMIC_RELAXED, __HIP_MEMORY_SCOPE_AGENT); }
; __device__ __forceinline__ unsigned xb_add(unsigned* p, unsigned v) { return __hip_atomic_fetch_add(p, v, __ATOMIC_RELAXED, __HIP_MEMORY_SCOPE_AGENT); }
; #define XB_SPIN(cond, bar) do { unsigned _sp = 0; while (cond) { __builtin_amdgcn_s_sleep(1); \
;     if ((++_sp & 255u) == 0u) { if (xb_ld(&(bar)[XB_TMO])) break; if (_sp > XB_SPIN_CAP) { atomicAdd(&(bar)[XB_TMO], 1u); break; } } } } while (0)
; __device__ __forceinline__ void xcd_barrier(const XcdBarrier& b) {
;     ...
;         const unsigned old = xb_add(&bar[XB_XSUB(b.x)], 1u);
;         const unsigned gen = old / nloc;
;         if (old + 1u == (gen + 1u) * nloc) {
;             __builtin_amdgcn_fence(__ATOMIC_RELEASE, "agent");
;             asm volatile("s_waitcnt vmcnt(0)" ::: "memory");
;             const unsigned og = xb_add(&bar[XB_TOP], 1u);
;             const unsigned tg = og / nx;
;             if (og + 1u == (tg + 1u) * nx) xb_add(&bar[XB_TOPGEN], 1u);
;             else XB_SPIN(xb_ld(&bar[XB_TOPGEN]) == tg, bar);
.LBB0_580:
	s_or_b64 exec, exec, s[6:7]
	v_cvt_f32_u32_e32 v3, v0
	s_waitcnt vmcnt(0)
	v_readfirstlane_b32 s4, v2
	s_add_u32 s6, s82, 0x7500
	s_addc_u32 s7, s83, 0
	v_rcp_iflag_f32_e32 v3, v3
	v_add_u32_e32 v1, s4, v1
	v_add_u32_e32 v4, 1, v1
	s_mov_b64 s[8:9], -1
	v_mul_f32_e32 v2, 0x4f7ffffe, v3
	v_cvt_u32_f32_e32 v2, v2
	v_sub_u32_e32 v3, 0, v0
	v_mul_lo_u32 v3, v3, v2
	v_mul_hi_u32 v3, v2, v3
	v_add_u32_e32 v2, v2, v3
	v_mul_hi_u32 v2, v1, v2
	v_mul_lo_u32 v3, v2, v0
	v_sub_u32_e32 v1, v1, v3
	v_add_u32_e32 v5, 1, v2
	v_cmp_ge_u32_e32 vcc, v1, v0
	v_sub_u32_e32 v3, v1, v0
	s_nop 0
	v_cndmask_b32_e32 v2, v2, v5, vcc
	v_cndmask_b32_e32 v1, v1, v3, vcc
	v_add_u32_e32 v3, 1, v2
	v_cmp_ge_u32_e32 vcc, v1, v0
	s_nop 1
	v_cndmask_b32_e32 v2, v2, v3, vcc
	v_mul_lo_u32 v1, v0, v2
	v_add_u32_e32 v0, v1, v0
	v_cmp_ne_u32_e32 vcc, v4, v0
	v_mov_b64_e32 v[0:1], s[6:7]
	s_cbranch_vccnz .Lbar_notlast_3
	v_mov_b32_e32 v3, 0x6400
	v_mov_b32_e32 v5, 1
	global_atomic_add v3, v5, s[82:83]
	global_atomic_add v3, v5, s[82:83] offset:256
	global_atomic_add v3, v5, s[82:83] offset:512
	global_atomic_add v3, v5, s[82:83] offset:768
	global_atomic_add v3, v5, s[82:83] offset:1024
	global_atomic_add v3, v5, s[82:83] offset:1280
	global_atomic_add v3, v5, s[82:83] offset:1536
	global_atomic_add v3, v5, s[82:83] offset:1792
	global_atomic_add v3, v5, s[82:83] offset:2048
	global_atomic_add v3, v5, s[82:83] offset:2304
	global_atomic_add v3, v5, s[82:83] offset:2560
	global_atomic_add v3, v5, s[82:83] offset:2816
	global_atomic_add v3, v5, s[82:83] offset:3072
	global_atomic_add v3, v5, s[82:83] offset:3328
	global_atomic_add v3, v5, s[82:83] offset:3584
	global_atomic_add v3, v5, s[82:83] offset:3840
.Lbar_notlast_3:
	s_and_saveexec_b64 s[4:5], vcc
	s_cbranch_execz .LBB0_592
	v_mov_b32_e32 v0, 0
	global_load_dword v1, v0, s[6:7] sc1
	s_mov_b64 s[12:13], 0
	s_waitcnt vmcnt(0)
	v_cmp_eq_u32_e32 vcc, v1, v2
	s_and_saveexec_b64 s[10:11], vcc
	s_cbranch_execz .LBB0_591
	s_add_u32 s8, s82, 0x4200
	s_addc_u32 s9, s83, 0
	s_mov_b32 s22, 1
	s_branch .LBB0_584

; __device__ __forceinline__ unsigned xb_add(unsigned* p, unsigned v) { return __hip_atomic_fetch_add(p, v, __ATOMIC_RELAXED, __HIP_MEMORY_SCOPE_AGENT); }
; __device__ __forceinline__ void xcd_barrier(const XcdBarrier& b) {
;     ...
;             __builtin_amdgcn_fence(__ATOMIC_ACQUIRE, "agent");
;             xb_add(&bar[XB_XGEN(b.x)], 1u);
;             asm volatile("s_waitcnt vmcnt(0)" ::: "memory");
.LBB0_594:
	s_or_b64 exec, exec, s[4:5]
	s_mov_b64 s[4:5], exec
	v_mbcnt_lo_u32_b32 v0, s4, 0
	v_mbcnt_hi_u32_b32 v0, s5, v0
	v_cmp_eq_u32_e32 vcc, 0, v0
	s_waitcnt vmcnt(0)
	buffer_inv sc1
	s_and_saveexec_b64 s[6:7], vcc
	s_cbranch_execz .LBB0_596
	s_bcnt1_i32_b64 s4, s[4:5]
	v_mov_b32_e32 v0, 0x2000
	v_mov_b32_e32 v1, s4
	s_nop 0

;     __device__ bool next(int i, Unit& u) const { if (i != 0) return false; return so.next(round, u); }
;     __device__ __forceinline__ bool next(int i, Unit& u) const { if (i > 0 || !on) return false; u.pm = pm; u.pn = 0; return true; }
; template <class Epi, class Sched, bool ALIGN_EPI = false, bool SP2 = false, bool MIDHOOK = false>
; __device__ __forceinline__ void gemm_phase(PG8_LAS unsigned char* lds, const Gemm g, const Sched& S, const Epi& E) {
;     ...
;         const bool has_next = S.next(ui + 1, nxt);
;         const char* nA = has_next ? (const char*)g.A + (size_t)nxt.pm * tstep : cA; const char* nB = has_next ? (const char*)g.Bt + (size_t)nxt.pn * tstep : cB;
;         for (int t = 0; t < nt; t += 2) {
;             if constexpr (MIDHOOK) { if (t == nt / 2) E.mid(acc, cur, wr, wc, fr, fq); }
;             const bool last = (t == nt - 2);
;             const char* a1 = cA + (size_t)(t + 1) * kstep;
;             const char* a2 = last ? nA : cA + (size_t)(t + 2) * kstep; const char* b2 = last ? nB : cB + (size_t)(t + 2) * kstep;
;     ...
; #pragma unroll
;         for (int a = 0; a < 2; ++a)
; #pragma unroll
;             for (int b = 0; b < 2; ++b)
; #pragma unroll
;                 for (int m = 0; m < 4; ++m)
; #pragma unroll
;                     for (int n = 0; n < 2; ++n) acc[a][b][m][n] = (f32x4){0.f, 0.f, 0.f, 0.f};
;         cur = nxt; cA = nA; cB = nB; ++ui;
.LBB0_3840:
	s_ashr_i32 s19, s18, 31
	s_lshl_b64 s[20:21], s[18:19], 19
	s_add_u32 s20, s68, s20
	s_addc_u32 s21, s69, s21
	s_and_b64 s[22:23], s[0:1], exec
	s_cselect_b32 s19, s21, s25
	s_cselect_b32 s46, s20, s24
	s_ashr_i32 s17, s16, 31
	s_lshl_b64 s[22:23], s[16:17], 19
	v_readlane_b32 s30, v243, 24
	v_readlane_b32 s31, v243, 25
	s_add_u32 s22, s30, s22
	s_addc_u32 s23, s31, s23
	s_and_b64 s[30:31], s[0:1], exec
	v_mov_b32_e32 v2, v0
	v_mov_b32_e32 v3, v0
	s_cselect_b32 s17, s23, s29
	s_cselect_b32 s47, s22, s28
	s_add_u32 s48, s28, 0x100
	v_mov_b32_e32 v1, v0
	v_mov_b64_e32 v[6:7], v[2:3]
	v_mov_b64_e32 v[10:11], v[2:3]
	v_mov_b64_e32 v[22:23], v[2:3]
	v_mov_b64_e32 v[26:27], v[2:3]
	v_mov_b64_e32 v[38:39], v[2:3]
	v_mov_b64_e32 v[42:43], v[2:3]
	v_mov_b64_e32 v[54:55], v[2:3]
	v_mov_b64_e32 v[58:59], v[2:3]
	v_mov_b64_e32 v[14:15], v[2:3]
	v_mov_b64_e32 v[18:19], v[2:3]
	v_mov_b64_e32 v[30:31], v[2:3]
	v_mov_b64_e32 v[34:35], v[2:3]
	v_mov_b64_e32 v[46:47], v[2:3]
	v_mov_b64_e32 v[50:51], v[2:3]
	v_mov_b64_e32 v[62:63], v[2:3]
	v_mov_b64_e32 v[66:67], v[2:3]
	v_mov_b64_e32 v[70:71], v[2:3]
	v_mov_b64_e32 v[74:75], v[2:3]
	v_mov_b64_e32 v[86:87], v[2:3]
	v_mov_b64_e32 v[90:91], v[2:3]
	v_mov_b64_e32 v[102:103], v[2:3]
	v_mov_b64_e32 v[106:107], v[2:3]
	v_mov_b64_e32 v[118:119], v[2:3]
	v_mov_b64_e32 v[122:123], v[2:3]
	v_mov_b64_e32 v[78:79], v[2:3]
	v_mov_b64_e32 v[82:83], v[2:3]
	v_mov_b64_e32 v[94:95], v[2:3]
	v_mov_b64_e32 v[98:99], v[2:3]
	v_mov_b64_e32 v[110:111], v[2:3]
	v_mov_b64_e32 v[114:115], v[2:3]
	v_mov_b64_e32 v[126:127], v[2:3]
	v_mov_b64_e32 v[130:131], v[2:3]
	v_lshl_add_u32 v204, s26, 8, v223
	v_lshl_add_u32 v206, s27, 8, v225
	v_lshl_add_u64 v[208:209], s[24:25], 0, v[196:197]
	v_lshl_add_u64 v[210:211], s[24:25], 0, v[198:199]
	s_addc_u32 s49, s29, 0
	s_mov_b32 s50, -2
	s_mov_b64 s[26:27], 0
	v_mov_b64_e32 v[4:5], v[0:1]
	v_mov_b64_e32 v[8:9], v[0:1]
	v_mov_b64_e32 v[20:21], v[0:1]
	v_mov_b64_e32 v[24:25], v[0:1]
	v_mov_b64_e32 v[36:37], v[0:1]
	v_mov_b64_e32 v[40:41], v[0:1]
	v_mov_b64_e32 v[52:53], v[0:1]
	v_mov_b64_e32 v[56:57], v[0:1]
	v_mov_b64_e32 v[12:13], v[0:1]
	v_mov_b64_e32 v[16:17], v[0:1]
	v_mov_b64_e32 v[28:29], v[0:1]
	v_mov_b64_e32 v[32:33], v[0:1]
	v_mov_b64_e32 v[44:45], v[0:1]
	v_mov_b64_e32 v[48:49], v[0:1]
	v_mov_b64_e32 v[60:61], v[0:1]
	v_mov_b64_e32 v[64:65], v[0:1]
	v_mov_b64_e32 v[68:69], v[0:1]
	v_mov_b64_e32 v[72:73], v[0:1]
	v_mov_b64_e32 v[84:85], v[0:1]
	v_mov_b64_e32 v[88:89], v[0:1]
	v_mov_b64_e32 v[100:101], v[0:1]
	v_mov_b64_e32 v[104:105], v[0:1]
	v_mov_b64_e32 v[116:117], v[0:1]
	v_mov_b64_e32 v[120:121], v[0:1]
	v_mov_b64_e32 v[76:77], v[0:1]
	v_mov_b64_e32 v[80:81], v[0:1]
	v_mov_b64_e32 v[92:93], v[0:1]
	v_mov_b64_e32 v[96:97], v[0:1]
	v_mov_b64_e32 v[108:109], v[0:1]
	v_mov_b64_e32 v[112:113], v[0:1]
	v_mov_b64_e32 v[124:125], v[0:1]
	v_mov_b64_e32 v[128:129], v[0:1]
	s_branch .LBB0_3842
	s_nop 0
	s_nop 0
	s_nop 0
	s_nop 0
	s_nop 0
	s_nop 0
	s_nop 0
	s_nop 0
	s_nop 0
	s_nop 0
	s_nop 0
	s_nop 0
	s_nop 0
	s_nop 0

; __device__ __forceinline__ unsigned xb_ld(unsigned* p)              { return __hip_atomic_load(p, __ATOMIC_RELAXED, __HIP_MEMORY_SCOPE_AGENT); }
; __device__ __forceinline__ unsigned xb_add(unsigned* p, unsigned v) { return __hip_atomic_fetch_add(p, v, __ATOMIC_RELAXED, __HIP_MEMORY_SCOPE_AGENT); }
; #define XB_SPIN(cond, bar) do { unsigned _sp = 0; while (cond) { __builtin_amdgcn_s_sleep(1); \
;     if ((++_sp & 255u) == 0u) { if (xb_ld(&(bar)[XB_TMO])) break; if (_sp > XB_SPIN_CAP) { atomicAdd(&(bar)[XB_TMO], 1u); break; } } } } while (0)
; __device__ __forceinline__ void xcd_barrier(const XcdBarrier& b) {
;     ...
;         const unsigned old = xb_add(&bar[XB_XSUB(b.x)], 1u);
;         const unsigned gen = old / nloc;
;         if (old + 1u == (gen + 1u) * nloc) {
;             __builtin_amdgcn_fence(__ATOMIC_RELEASE, "agent");
;             asm volatile("s_waitcnt vmcnt(0)" ::: "memory");
;             const unsigned og = xb_add(&bar[XB_TOP], 1u);
;             const unsigned tg = og / nx;
;             if (og + 1u == (tg + 1u) * nx) xb_add(&bar[XB_TOPGEN], 1u);
;             else XB_SPIN(xb_ld(&bar[XB_TOPGEN]) == tg, bar);
.LBB0_3885:
	s_or_b64 exec, exec, s[8:9]
	v_cvt_f32_u32_e32 v3, v0
	s_waitcnt vmcnt(0)
	v_readfirstlane_b32 s6, v2
	s_add_u32 s8, s82, 0x7500
	s_addc_u32 s9, s83, 0
	v_rcp_iflag_f32_e32 v3, v3
	v_add_u32_e32 v1, s6, v1
	v_add_u32_e32 v4, 1, v1
	s_mov_b64 s[10:11], -1
	v_mul_f32_e32 v2, 0x4f7ffffe, v3
	v_cvt_u32_f32_e32 v2, v2
	v_sub_u32_e32 v3, 0, v0
	v_mul_lo_u32 v3, v3, v2
	v_mul_hi_u32 v3, v2, v3
	v_add_u32_e32 v2, v2, v3
	v_mul_hi_u32 v2, v1, v2
	v_mul_lo_u32 v3, v2, v0
	v_sub_u32_e32 v1, v1, v3
	v_add_u32_e32 v5, 1, v2
	v_cmp_ge_u32_e32 vcc, v1, v0
	v_sub_u32_e32 v3, v1, v0
	s_nop 0
	v_cndmask_b32_e32 v2, v2, v5, vcc
	v_cndmask_b32_e32 v1, v1, v3, vcc
	v_add_u32_e32 v3, 1, v2
	v_cmp_ge_u32_e32 vcc, v1, v0
	s_nop 1
	v_cndmask_b32_e32 v2, v2, v3, vcc
	v_mul_lo_u32 v1, v0, v2
	v_add_u32_e32 v0, v1, v0
	v_cmp_ne_u32_e32 vcc, v4, v0
	v_mov_b64_e32 v[0:1], s[8:9]
	s_cbranch_vccnz .Lbar_notlast_6
	v_mov_b32_e32 v3, 0x6400
	v_mov_b32_e32 v5, 1
	global_atomic_add v3, v5, s[82:83]
	global_atomic_add v3, v5, s[82:83] offset:256
	global_atomic_add v3, v5, s[82:83] offset:512
	global_atomic_add v3, v5, s[82:83] offset:768
	global_atomic_add v3, v5, s[82:83] offset:1024
	global_atomic_add v3, v5, s[82:83] offset:1280
	global_atomic_add v3, v5, s[82:83] offset:1536
	global_atomic_add v3, v5, s[82:83] offset:1792
	global_atomic_add v3, v5, s[82:83] offset:2048
	global_atomic_add v3, v5, s[82:83] offset:2304
	global_atomic_add v3, v5, s[82:83] offset:2560
	global_atomic_add v3, v5, s[82:83] offset:2816
	global_atomic_add v3, v5, s[82:83] offset:3072
	global_atomic_add v3, v5, s[82:83] offset:3328
	global_atomic_add v3, v5, s[82:83] offset:3584
	global_atomic_add v3, v5, s[82:83] offset:3840
.Lbar_notlast_6:
	s_and_saveexec_b64 s[6:7], vcc
	s_cbranch_execz .LBB0_3897
	v_mov_b32_e32 v0, 0
	global_load_dword v1, v0, s[8:9] sc1
	s_mov_b64 s[14:15], 0
	s_waitcnt vmcnt(0)
	v_cmp_eq_u32_e32 vcc, v1, v2
	s_and_saveexec_b64 s[12:13], vcc
	s_cbranch_execz .LBB0_3896
	s_add_u32 s10, s82, 0x4200
	s_addc_u32 s11, s83, 0
	s_mov_b32 s24, 1
	s_branch .LBB0_3889

; __device__ __forceinline__ unsigned xb_add(unsigned* p, unsigned v) { return __hip_atomic_fetch_add(p, v, __ATOMIC_RELAXED, __HIP_MEMORY_SCOPE_AGENT); }
; __device__ __forceinline__ void xcd_barrier(const XcdBarrier& b) {
;     ...
;             __builtin_amdgcn_fence(__ATOMIC_ACQUIRE, "agent");
;             xb_add(&bar[XB_XGEN(b.x)], 1u);
;             asm volatile("s_waitcnt vmcnt(0)" ::: "memory");
.LBB0_3899:
	s_or_b64 exec, exec, s[6:7]
	s_mov_b64 s[6:7], exec
	v_mbcnt_lo_u32_b32 v0, s6, 0
	v_mbcnt_hi_u32_b32 v0, s7, v0
	v_cmp_eq_u32_e32 vcc, 0, v0
	s_waitcnt vmcnt(0)
	buffer_inv sc1
	s_and_saveexec_b64 s[8:9], vcc
	s_cbranch_execz .LBB0_3901
	s_bcnt1_i32_b64 s6, s[6:7]
	v_mov_b32_e32 v0, 0x2000
	v_mov_b32_e32 v1, s6
	s_nop 0

; #define PG8_STAGE(bufoff, gbase, voff) do { _Pragma("unroll") for (int _i = 0; _i < 2; ++_i) \
;         __builtin_amdgcn_global_load_lds((const unsigned*)((const char*)(gbase) + (voff)[_i]), (PG8_LAS unsigned*)(lds + (bufoff) + ldsw + _i * 8192), 16, 0, 0); } while (0)
; #define PG8_WAIT_V(n) asm volatile("s_waitcnt vmcnt(" #n ")" ::: "memory")
; #define PG8_BAR __builtin_amdgcn_s_barrier()
; template <class Epi, class Sched, bool ALIGN_EPI = false, bool SP2 = false, bool MIDHOOK = false>
; __device__ __forceinline__ void gemm_phase(PG8_LAS unsigned char* lds, const Gemm g, const Sched& S, const Epi& E) {
;     ...
;     f32x4 acc[2][2][4][2];
; #pragma unroll
;     for (int a = 0; a < 2; ++a)
; #pragma unroll
;         for (int b = 0; b < 2; ++b)
; #pragma unroll
;             for (int m = 0; m < 4; ++m)
; #pragma unroll
;                 for (int n = 0; n < 2; ++n) acc[a][b][m][n] = (f32x4){0.f, 0.f, 0.f, 0.f};
;     bf16x8 At[4][2], B0[2][2], B1[2][2];
;     const char* cA = (const char*)g.A + (size_t)cur.pm * tstep; const char* cB = (const char*)g.Bt + (size_t)cur.pn * tstep;
;     S.a_ready(cur);
;     if constexpr (SP2) {
;         PG8_STAGE(PG8_SB(0, 0), cB, voffB); PG8_STAGE(PG8_SB(0, 1), cB + hstep, voffB); PG8_STAGE(PG8_SA(0, 0), cA, voffA); PG8_STAGE(PG8_SA(0, 1), cA + hstep, voffA);
;         if (wr == 1) PG8_BAR;
;         PG8_WAIT_V(2); PG8_BAR;
;         PG8_STAGE(PG8_SB(1, 0), cB + kstep, voffB); PG8_STAGE(PG8_SA(1, 0), cA + kstep, voffA); PG8_STAGE(PG8_SB(1, 1), cB + hstep + kstep, voffB);
;         PG8_WAIT_V(6); PG8_BAR;
.LBB0_3911:
	s_mov_b64 s[12:13], 0x80
	s_add_i32 m0, s26, 0x18000
	v_lshl_add_u64 v[6:7], v[6:7], 0, s[12:13]
	s_and_b32 s11, s84, 3
	s_waitcnt vmcnt(2)
	s_barrier
	global_load_lds_dwordx4 v[6:7], off
	v_lshl_add_u64 v[4:5], v[4:5], 0, s[12:13]
	s_add_i32 m0, s26, 0x1a000
	s_add_i32 s31, s26, 0x8000
	s_add_i32 s33, s26, 0xa000
	global_load_lds_dwordx4 v[4:5], off
	v_lshl_add_u64 v[2:3], v[2:3], 0, s[12:13]
	s_mov_b32 m0, s31
	s_add_u32 s36, s6, 0x40080
	global_load_lds_dwordx4 v[2:3], off
	v_lshl_add_u64 v[0:1], v[0:1], 0, s[12:13]
	s_mov_b32 m0, s33
	s_addc_u32 s37, s7, 0
	global_load_lds_dwordx4 v[0:1], off
	s_add_i32 m0, s26, 0x1c000
	v_lshl_add_u64 v[0:1], s[36:37], 0, v[130:131]
	global_load_lds_dwordx4 v[0:1], off
	v_lshl_add_u64 v[0:1], s[36:37], 0, v[134:135]
	s_add_i32 m0, s26, 0x1e000
	s_add_u32 s22, s80, s22
	global_load_lds_dwordx4 v[0:1], off
	v_lshlrev_b32_e32 v0, 14, v8
	v_and_b32_e32 v0, 0xffff8000, v0
	v_lshl_add_u32 v0, v9, 11, v0
	v_and_b32_e32 v1, 1, v8
	v_lshl_or_b32 v0, v1, 6, v0
	v_lshl_add_u32 v0, v10, 1, v0
	v_mov_b32_e32 v1, v131
	s_addc_u32 s23, s81, s23
	s_mov_b64 s[34:35], 0x40080
	v_lshl_add_u64 v[0:1], s[22:23], 0, v[0:1]
	v_lshl_add_u64 v[136:137], v[0:1], 0, s[34:35]
	v_lshlrev_b32_e32 v0, 14, v11
	v_and_b32_e32 v0, 0xffff8000, v0
	v_lshl_add_u32 v0, v12, 11, v0
	v_and_b32_e32 v1, 1, v11
	v_lshl_or_b32 v0, v1, 6, v0
	v_and_b32_e32 v15, 15, v140
	v_and_b32_e32 v16, 48, v140
	v_lshl_add_u32 v0, v13, 1, v0
	v_mov_b32_e32 v1, v131
	s_add_u32 s16, s82, s16
	v_lshl_or_b32 v146, s30, 6, v15
	v_and_b32_e32 v14, 0xfffffc00, v14
	v_lshl_or_b32 v15, v15, 6, v16
	v_lshlrev_b32_e32 v16, 2, v140
	v_lshl_add_u64 v[0:1], s[22:23], 0, v[0:1]
	s_addc_u32 s17, s83, s17
	v_lshl_add_u32 v17, s30, 13, v14
	v_and_b32_e32 v16, 32, v16
	v_lshl_add_u32 v14, s11, 12, v14
	v_lshl_add_u64 v[138:139], v[0:1], 0, s[34:35]
	s_add_u32 s34, s16, 0xe00100
	v_bitop3_b32 v14, v15, v14, v16 bitop3:0xde
	s_waitcnt vmcnt(6)
	s_addc_u32 s35, s17, 0
	s_add_i32 s39, 0, 0x10000
	s_add_i32 s41, 0, 0x14000
	s_add_i32 s43, 0, 0x18000
	s_add_i32 s45, 0, 0x1c000
	v_bitop3_b32 v17, v15, v17, v16 bitop3:0xde
	v_add_u32_e32 v141, s39, v14
	v_add_u32_e32 v142, s41, v14
	s_add_i32 s39, s39, s24
	s_add_i32 s41, s41, s24
	v_add_u32_e32 v144, s43, v14
	v_add_u32_e32 v145, s45, v14
	s_add_i32 s43, s43, s24
	s_add_i32 s45, s45, s24
	s_mov_b32 s36, -2
	s_mov_b64 s[16:17], 0
	v_add_u32_e32 v143, 0, v17
	s_add_i32 s37, s26, 0xc000
	s_add_i32 s38, s26, 0xe000
	s_add_i32 s40, s39, 0x2000
	s_add_i32 s42, s41, 0x2000
	s_add_i32 s44, s43, 0x2000
	s_add_i32 s46, s45, 0x2000
	v_mov_b32_e32 v72, v131
	v_mov_b32_e32 v73, v131
	v_mov_b32_e32 v74, v131
	v_mov_b32_e32 v75, v131
	v_mov_b32_e32 v76, v131
	v_mov_b32_e32 v77, v131
	v_mov_b32_e32 v78, v131
	v_mov_b32_e32 v79, v131
	v_mov_b32_e32 v56, v131
	v_mov_b32_e32 v57, v131
	v_mov_b32_e32 v58, v131
	v_mov_b32_e32 v59, v131
	v_mov_b32_e32 v60, v131
	v_mov_b32_e32 v61, v131
	v_mov_b32_e32 v62, v131
	v_mov_b32_e32 v63, v131
	v_mov_b32_e32 v40, v131
	v_mov_b32_e32 v41, v131
	v_mov_b32_e32 v42, v131
	v_mov_b32_e32 v43, v131
	v_mov_b32_e32 v44, v131
	v_mov_b32_e32 v45, v131
	v_mov_b32_e32 v46, v131
	v_mov_b32_e32 v47, v131
	v_mov_b32_e32 v32, v131
	v_mov_b32_e32 v33, v131
	v_mov_b32_e32 v34, v131
	v_mov_b32_e32 v35, v131
	v_mov_b32_e32 v36, v131
	v_mov_b32_e32 v37, v131
	v_mov_b32_e32 v38, v131
	v_mov_b32_e32 v39, v131
	v_mov_b32_e32 v112, v131
	v_mov_b32_e32 v113, v131
	v_mov_b32_e32 v114, v131
	v_mov_b32_e32 v115, v131
	v_mov_b32_e32 v116, v131
	v_mov_b32_e32 v117, v131
	v_mov_b32_e32 v118, v131
	v_mov_b32_e32 v119, v131
	v_mov_b32_e32 v120, v131
	v_mov_b32_e32 v121, v131
	v_mov_b32_e32 v122, v131
	v_mov_b32_e32 v123, v131
	v_mov_b32_e32 v124, v131
	v_mov_b32_e32 v125, v131
	v_mov_b32_e32 v126, v131
	v_mov_b32_e32 v127, v131
	v_mov_b32_e32 v104, v131
	v_mov_b32_e32 v105, v131
	v_mov_b32_e32 v106, v131
	v_mov_b32_e32 v107, v131
	v_mov_b32_e32 v108, v131
	v_mov_b32_e32 v109, v131
	v_mov_b32_e32 v110, v131
	v_mov_b32_e32 v111, v131
	v_mov_b32_e32 v96, v131
	v_mov_b32_e32 v97, v131
	v_mov_b32_e32 v98, v131
	v_mov_b32_e32 v99, v131
	v_mov_b32_e32 v100, v131
	v_mov_b32_e32 v101, v131
	v_mov_b32_e32 v102, v131
	v_mov_b32_e32 v103, v131
	v_mov_b32_e32 v24, v131
	v_mov_b32_e32 v25, v131
	v_mov_b32_e32 v26, v131
	v_mov_b32_e32 v27, v131
	v_mov_b32_e32 v28, v131
	v_mov_b32_e32 v29, v131
	v_mov_b32_e32 v30, v131
	v_mov_b32_e32 v31, v131
	v_mov_b32_e32 v16, v131
	v_mov_b32_e32 v17, v131
	v_mov_b32_e32 v18, v131
	v_mov_b32_e32 v19, v131
	v_mov_b32_e32 v20, v131
	v_mov_b32_e32 v21, v131
	v_mov_b32_e32 v22, v131
	v_mov_b32_e32 v23, v131
	v_mov_b32_e32 v8, v131
	v_mov_b32_e32 v9, v131
	v_mov_b32_e32 v10, v131
	v_mov_b32_e32 v11, v131
	v_mov_b32_e32 v12, v131
	v_mov_b32_e32 v13, v131
	v_mov_b32_e32 v14, v131
	v_mov_b32_e32 v15, v131
	v_mov_b32_e32 v0, v131
	v_mov_b32_e32 v1, v131
	v_mov_b32_e32 v2, v131
	v_mov_b32_e32 v3, v131
	v_mov_b32_e32 v4, v131
	v_mov_b32_e32 v5, v131
	v_mov_b32_e32 v6, v131
	v_mov_b32_e32 v7, v131
	v_mov_b32_e32 v88, v131
	v_mov_b32_e32 v89, v131
	v_mov_b32_e32 v90, v131
	v_mov_b32_e32 v91, v131
	v_mov_b32_e32 v92, v131
	v_mov_b32_e32 v93, v131
	v_mov_b32_e32 v94, v131
	v_mov_b32_e32 v95, v131
	v_mov_b32_e32 v80, v131
	v_mov_b32_e32 v81, v131
	v_mov_b32_e32 v82, v131
	v_mov_b32_e32 v83, v131
	v_mov_b32_e32 v84, v131
	v_mov_b32_e32 v85, v131
	v_mov_b32_e32 v86, v131
	v_mov_b32_e32 v87, v131
	v_mov_b32_e32 v64, v131
	v_mov_b32_e32 v65, v131
	v_mov_b32_e32 v66, v131
	v_mov_b32_e32 v67, v131
	v_mov_b32_e32 v68, v131
	v_mov_b32_e32 v69, v131
	v_mov_b32_e32 v70, v131
	v_mov_b32_e32 v71, v131
	v_mov_b32_e32 v48, v131
	v_mov_b32_e32 v49, v131
	v_mov_b32_e32 v50, v131
	v_mov_b32_e32 v51, v131
	v_mov_b32_e32 v52, v131
	v_mov_b32_e32 v53, v131
	v_mov_b32_e32 v54, v131
	v_mov_b32_e32 v55, v131
	s_barrier
	s_nop 0
	s_nop 0
	s_nop 0
; #define PG8_STAGE(bufoff, gbase, voff) do { _Pragma("unroll") for (int _i = 0; _i < 2; ++_i) \
;         __builtin_amdgcn_global_load_lds((const unsigned*)((const char*)(gbase) + (voff)[_i]), (PG8_LAS unsigned*)(lds + (bufoff) + ldsw + _i * 8192), 16, 0, 0); } while (0)
; #define PG8_LDA(dst, b, h) do { _Pragma("unroll") for (int m = 0; m < 4; ++m) _Pragma("unroll") for (int k = 0; k < 2; ++k) dst[m][k] = *(const PG8_LAS bf16x8*)(lds + PG8_SA(b, h) + aoff + m * 2048 + k * 1024); } while (0)
; #define PG8_LDB(dst, b, h) do { _Pragma("unroll") for (int n = 0; n < 2; ++n) _Pragma("unroll") for (int k = 0; k < 2; ++k) dst[n][k] = *(const PG8_LAS bf16x8*)(lds + PG8_SB(b, h) + boff + n * 2048 + k * 1024); } while (0)
; #define PG8_MMA(ai, bj, At, Bt) do { __builtin_amdgcn_s_setprio(1); _Pragma("unroll") for (int m = 0; m < 4; ++m) _Pragma("unroll") for (int n = 0; n < 2; ++n) _Pragma("unroll") for (int k = 0; k < 2; ++k) \
;         acc[ai][bj][m][n] = __builtin_amdgcn_mfma_f32_16x16x32_bf16(Bt[n][k], At[m][k], acc[ai][bj][m][n], 0, 0, 0); __builtin_amdgcn_s_setprio(0); } while (0)
; #define PG8_WAIT_V(n) asm volatile("s_waitcnt vmcnt(" #n ")" ::: "memory")
; #define PG8_WAIT_L(n) asm volatile("s_waitcnt lgkmcnt(" #n ")" ::: "memory")
; #define PG8_BAR __builtin_amdgcn_s_barrier()
; #define PG8_SCHED __builtin_amdgcn_sched_barrier(0)
; template <class Epi, class Sched, bool ALIGN_EPI = false, bool SP2 = false, bool MIDHOOK = false>
; __device__ __forceinline__ void gemm_phase(PG8_LAS unsigned char* lds, const Gemm g, const Sched& S, const Epi& E) {
;     ...
;             PG8_LDB(B0, 0, 0); PG8_LDB(B1, 0, 1); PG8_SCHED; PG8_LDA(At, 0, 0); PG8_STAGE(PG8_SA(1, 1), a1 + hstep, voffA);
;             PG8_WAIT_V(8); PG8_WAIT_L(0); PG8_BAR; PG8_MMA(0, 0, At, B0); PG8_MMA(0, 1, At, B1); PG8_BAR; PG8_SCHED;
;             PG8_LDA(At, 0, 1); PG8_STAGE(PG8_SB(0, 0), b2, voffB); PG8_STAGE(PG8_SB(0, 1), b2 + hstep, voffB); PG8_STAGE(PG8_SA(0, 0), a2, voffA);
;             PG8_WAIT_V(8); PG8_WAIT_L(0); PG8_BAR; PG8_MMA(1, 0, At, B0); PG8_MMA(1, 1, At, B1); PG8_BAR; PG8_SCHED;
.LBB0_3912:
	ds_read_b128 v[148:151], v141
	ds_read_b128 v[158:161], v141 offset:1024
	ds_read_b128 v[162:165], v141 offset:2048
	ds_read_b128 v[166:169], v141 offset:3072
	ds_read_b128 v[170:173], v142
	ds_read_b128 v[174:177], v142 offset:1024
	ds_read_b128 v[178:181], v142 offset:2048
	ds_read_b128 v[182:185], v142 offset:3072
	s_add_u32 s22, s8, s16
	s_addc_u32 s23, s9, s17
	s_add_u32 s22, s22, 0x100
	s_addc_u32 s23, s23, 0
	s_add_u32 s47, s34, s16
	s_addc_u32 s48, s35, s17
	s_cmpk_eq_i32 s16, 0x700
	s_cselect_b32 s25, s9, s23
	s_cselect_b32 s24, s8, s22
	s_cselect_b32 s23, s7, s48
	s_cselect_b32 s22, s6, s47
	s_mov_b32 m0, s37
	v_lshl_add_u64 v[152:153], v[136:137], 0, s[16:17]
	ds_read_b128 v[186:189], v143
	ds_read_b128 v[190:193], v143 offset:1024
	ds_read_b128 v[194:197], v143 offset:2048
	ds_read_b128 v[198:201], v143 offset:3072
	ds_read_b128 v[202:205], v143 offset:4096
	ds_read_b128 v[206:209], v143 offset:5120
	ds_read_b128 v[210:213], v143 offset:6144
	ds_read_b128 v[214:217], v143 offset:7168
	global_load_lds_dwordx4 v[152:153], off
	v_lshl_add_u64 v[152:153], v[138:139], 0, s[16:17]
	s_mov_b32 m0, s38
	s_nop 0
	global_load_lds_dwordx4 v[152:153], off
	s_waitcnt vmcnt(8)
	s_waitcnt lgkmcnt(0)
	s_barrier
	s_setprio 1
	s_waitcnt lgkmcnt(0)
	v_mfma_f32_16x16x32_bf16 v[52:55], v[148:151], v[186:189], v[52:55]
	v_mfma_f32_16x16x32_bf16 v[48:51], v[162:165], v[186:189], v[48:51]
	v_mfma_f32_16x16x32_bf16 v[68:71], v[148:151], v[194:197], v[68:71]
	v_mfma_f32_16x16x32_bf16 v[64:67], v[162:165], v[194:197], v[64:67]
	v_mfma_f32_16x16x32_bf16 v[84:87], v[148:151], v[202:205], v[84:87]
	v_mfma_f32_16x16x32_bf16 v[80:83], v[162:165], v[202:205], v[80:83]
	v_mfma_f32_16x16x32_bf16 v[92:95], v[148:151], v[210:213], v[92:95]
	v_mfma_f32_16x16x32_bf16 v[88:91], v[162:165], v[210:213], v[88:91]
	v_mfma_f32_16x16x32_bf16 v[52:55], v[158:161], v[190:193], v[52:55]
	v_mfma_f32_16x16x32_bf16 v[48:51], v[166:169], v[190:193], v[48:51]
	v_mfma_f32_16x16x32_bf16 v[68:71], v[158:161], v[198:201], v[68:71]
	v_mfma_f32_16x16x32_bf16 v[64:67], v[166:169], v[198:201], v[64:67]
	v_mfma_f32_16x16x32_bf16 v[84:87], v[158:161], v[206:209], v[84:87]
	v_mfma_f32_16x16x32_bf16 v[80:83], v[166:169], v[206:209], v[80:83]
	v_mfma_f32_16x16x32_bf16 v[92:95], v[158:161], v[214:217], v[92:95]
	v_mfma_f32_16x16x32_bf16 v[88:91], v[166:169], v[214:217], v[88:91]
	s_setprio 0
	s_setprio 1
	v_mfma_f32_16x16x32_bf16 v[4:7], v[170:173], v[186:189], v[4:7]
	v_mfma_f32_16x16x32_bf16 v[0:3], v[178:181], v[186:189], v[0:3]
	v_mfma_f32_16x16x32_bf16 v[12:15], v[170:173], v[194:197], v[12:15]
	v_mfma_f32_16x16x32_bf16 v[8:11], v[178:181], v[194:197], v[8:11]
	v_mfma_f32_16x16x32_bf16 v[20:23], v[170:173], v[202:205], v[20:23]
	v_mfma_f32_16x16x32_bf16 v[16:19], v[178:181], v[202:205], v[16:19]
	v_mfma_f32_16x16x32_bf16 v[28:31], v[170:173], v[210:213], v[28:31]
	v_mfma_f32_16x16x32_bf16 v[24:27], v[178:181], v[210:213], v[24:27]
	v_mfma_f32_16x16x32_bf16 v[4:7], v[174:177], v[190:193], v[4:7]
	v_mfma_f32_16x16x32_bf16 v[0:3], v[182:185], v[190:193], v[0:3]
	v_mfma_f32_16x16x32_bf16 v[12:15], v[174:177], v[198:201], v[12:15]
	v_mfma_f32_16x16x32_bf16 v[8:11], v[182:185], v[198:201], v[8:11]
	v_mfma_f32_16x16x32_bf16 v[20:23], v[174:177], v[206:209], v[20:23]
	v_mfma_f32_16x16x32_bf16 v[16:19], v[182:185], v[206:209], v[16:19]
	v_mfma_f32_16x16x32_bf16 v[28:31], v[174:177], v[214:217], v[28:31]
	v_mfma_f32_16x16x32_bf16 v[24:27], v[182:185], v[214:217], v[24:27]
	s_setprio 0
	s_barrier
	s_mov_b32 m0, s39
	v_lshl_add_u64 v[152:153], s[22:23], 0, v[130:131]
	s_add_u32 s48, s22, 0x40000
	ds_read_b128 v[186:189], v143 offset:16384
	ds_read_b128 v[190:193], v143 offset:17408
	ds_read_b128 v[194:197], v143 offset:18432
	ds_read_b128 v[198:201], v143 offset:19456
	ds_read_b128 v[202:205], v143 offset:20480
	ds_read_b128 v[206:209], v143 offset:21504
	ds_read_b128 v[210:213], v143 offset:22528
	ds_read_b128 v[214:217], v143 offset:23552
	global_load_lds_dwordx4 v[152:153], off
	v_lshl_add_u64 v[218:219], s[22:23], 0, v[134:135]
	s_mov_b32 m0, s40
	s_addc_u32 s49, s23, 0
	global_load_lds_dwordx4 v[218:219], off
	v_lshl_add_u64 v[222:223], s[48:49], 0, v[130:131]
	s_mov_b32 m0, s41
	v_lshl_add_u64 v[224:225], s[24:25], 0, v[132:133]
	global_load_lds_dwordx4 v[222:223], off
	v_lshl_add_u64 v[222:223], s[48:49], 0, v[134:135]
	s_mov_b32 m0, s42
	s_nop 0
	global_load_lds_dwordx4 v[222:223], off
	v_lshl_add_u64 v[222:223], s[24:25], 0, v[128:129]
	s_mov_b32 m0, s26
	s_nop 0
	global_load_lds_dwordx4 v[222:223], off
	s_mov_b32 m0, s27
	s_nop 0
	global_load_lds_dwordx4 v[224:225], off
	s_waitcnt vmcnt(8)
	s_waitcnt lgkmcnt(0)
	s_barrier
; #define PG8_STAGE(bufoff, gbase, voff) do { _Pragma("unroll") for (int _i = 0; _i < 2; ++_i) \
;         __builtin_amdgcn_global_load_lds((const unsigned*)((const char*)(gbase) + (voff)[_i]), (PG8_LAS unsigned*)(lds + (bufoff) + ldsw + _i * 8192), 16, 0, 0); } while (0)
; #define PG8_LDA(dst, b, h) do { _Pragma("unroll") for (int m = 0; m < 4; ++m) _Pragma("unroll") for (int k = 0; k < 2; ++k) dst[m][k] = *(const PG8_LAS bf16x8*)(lds + PG8_SA(b, h) + aoff + m * 2048 + k * 1024); } while (0)
; #define PG8_LDB(dst, b, h) do { _Pragma("unroll") for (int n = 0; n < 2; ++n) _Pragma("unroll") for (int k = 0; k < 2; ++k) dst[n][k] = *(const PG8_LAS bf16x8*)(lds + PG8_SB(b, h) + boff + n * 2048 + k * 1024); } while (0)
; #define PG8_MMA(ai, bj, At, Bt) do { __builtin_amdgcn_s_setprio(1); _Pragma("unroll") for (int m = 0; m < 4; ++m) _Pragma("unroll") for (int n = 0; n < 2; ++n) _Pragma("unroll") for (int k = 0; k < 2; ++k) \
;         acc[ai][bj][m][n] = __builtin_amdgcn_mfma_f32_16x16x32_bf16(Bt[n][k], At[m][k], acc[ai][bj][m][n], 0, 0, 0); __builtin_amdgcn_s_setprio(0); } while (0)
; #define PG8_WAIT_V(n) asm volatile("s_waitcnt vmcnt(" #n ")" ::: "memory")
; #define PG8_WAIT_L(n) asm volatile("s_waitcnt lgkmcnt(" #n ")" ::: "memory")
; #define PG8_BAR __builtin_amdgcn_s_barrier()
; #define PG8_SCHED __builtin_amdgcn_sched_barrier(0)
; template <class Epi, class Sched, bool ALIGN_EPI = false, bool SP2 = false, bool MIDHOOK = false>
; __device__ __forceinline__ void gemm_phase(PG8_LAS unsigned char* lds, const Gemm g, const Sched& S, const Epi& E) {
;     ...
;             PG8_WAIT_V(8); PG8_WAIT_L(0); PG8_BAR; PG8_MMA(1, 0, At, B0); PG8_MMA(1, 1, At, B1); PG8_BAR; PG8_SCHED;
;             PG8_LDB(B0, 1, 0); PG8_LDB(B1, 1, 1); PG8_SCHED; PG8_LDA(At, 1, 0); PG8_STAGE(PG8_SA(0, 1), a2 + hstep, voffA);
;             PG8_WAIT_V(8); PG8_WAIT_L(0); PG8_BAR; PG8_MMA(0, 0, At, B0); PG8_MMA(0, 1, At, B1); PG8_BAR; PG8_SCHED;
	s_setprio 1
	s_waitcnt lgkmcnt(0)
	v_mfma_f32_16x16x32_bf16 v[100:103], v[148:151], v[186:189], v[100:103]
	v_mfma_f32_16x16x32_bf16 v[96:99], v[162:165], v[186:189], v[96:99]
	v_mfma_f32_16x16x32_bf16 v[108:111], v[148:151], v[194:197], v[108:111]
	v_mfma_f32_16x16x32_bf16 v[104:107], v[162:165], v[194:197], v[104:107]
	v_mfma_f32_16x16x32_bf16 v[124:127], v[148:151], v[202:205], v[124:127]
	v_mfma_f32_16x16x32_bf16 v[120:123], v[162:165], v[202:205], v[120:123]
	v_mfma_f32_16x16x32_bf16 v[116:119], v[148:151], v[210:213], v[116:119]
	v_mfma_f32_16x16x32_bf16 v[112:115], v[162:165], v[210:213], v[112:115]
	v_mfma_f32_16x16x32_bf16 v[100:103], v[158:161], v[190:193], v[100:103]
	v_mfma_f32_16x16x32_bf16 v[96:99], v[166:169], v[190:193], v[96:99]
	v_mfma_f32_16x16x32_bf16 v[108:111], v[158:161], v[198:201], v[108:111]
	v_mfma_f32_16x16x32_bf16 v[104:107], v[166:169], v[198:201], v[104:107]
	v_mfma_f32_16x16x32_bf16 v[124:127], v[158:161], v[206:209], v[124:127]
	v_mfma_f32_16x16x32_bf16 v[120:123], v[166:169], v[206:209], v[120:123]
	v_mfma_f32_16x16x32_bf16 v[116:119], v[158:161], v[214:217], v[116:119]
	v_mfma_f32_16x16x32_bf16 v[112:115], v[166:169], v[214:217], v[112:115]
	s_setprio 0
	s_setprio 1
	v_mfma_f32_16x16x32_bf16 v[36:39], v[170:173], v[186:189], v[36:39]
	v_mfma_f32_16x16x32_bf16 v[32:35], v[178:181], v[186:189], v[32:35]
	v_mfma_f32_16x16x32_bf16 v[44:47], v[170:173], v[194:197], v[44:47]
	v_mfma_f32_16x16x32_bf16 v[40:43], v[178:181], v[194:197], v[40:43]
	v_mfma_f32_16x16x32_bf16 v[60:63], v[170:173], v[202:205], v[60:63]
	v_mfma_f32_16x16x32_bf16 v[56:59], v[178:181], v[202:205], v[56:59]
	v_mfma_f32_16x16x32_bf16 v[76:79], v[170:173], v[210:213], v[76:79]
	v_mfma_f32_16x16x32_bf16 v[72:75], v[178:181], v[210:213], v[72:75]
	v_mfma_f32_16x16x32_bf16 v[36:39], v[174:177], v[190:193], v[36:39]
	v_mfma_f32_16x16x32_bf16 v[32:35], v[182:185], v[190:193], v[32:35]
	v_mfma_f32_16x16x32_bf16 v[44:47], v[174:177], v[198:201], v[44:47]
	v_mfma_f32_16x16x32_bf16 v[40:43], v[182:185], v[198:201], v[40:43]
	v_mfma_f32_16x16x32_bf16 v[60:63], v[174:177], v[206:209], v[60:63]
	v_mfma_f32_16x16x32_bf16 v[56:59], v[182:185], v[206:209], v[56:59]
	v_mfma_f32_16x16x32_bf16 v[76:79], v[174:177], v[214:217], v[76:79]
	v_mfma_f32_16x16x32_bf16 v[72:75], v[182:185], v[214:217], v[72:75]
	s_setprio 0
	s_barrier
	ds_read_b128 v[148:151], v144
	ds_read_b128 v[158:161], v144 offset:1024
	ds_read_b128 v[162:165], v144 offset:2048
	ds_read_b128 v[166:169], v144 offset:3072
	ds_read_b128 v[170:173], v145
	ds_read_b128 v[174:177], v145 offset:1024
	ds_read_b128 v[178:181], v145 offset:2048
	ds_read_b128 v[182:185], v145 offset:3072
	s_add_u32 s24, s24, 0x40000
	s_addc_u32 s25, s25, 0
	s_mov_b32 m0, s28
	v_lshl_add_u64 v[226:227], s[24:25], 0, v[128:129]
	ds_read_b128 v[186:189], v143 offset:32768
	ds_read_b128 v[190:193], v143 offset:33792
	ds_read_b128 v[194:197], v143 offset:34816
	ds_read_b128 v[198:201], v143 offset:35840
	ds_read_b128 v[202:205], v143 offset:36864
	ds_read_b128 v[206:209], v143 offset:37888
	ds_read_b128 v[210:213], v143 offset:38912
	ds_read_b128 v[214:217], v143 offset:39936
	global_load_lds_dwordx4 v[226:227], off
	v_lshl_add_u64 v[226:227], s[24:25], 0, v[132:133]
	s_mov_b32 m0, s29
	s_nop 0
	global_load_lds_dwordx4 v[226:227], off
	s_waitcnt vmcnt(8)
	s_waitcnt lgkmcnt(0)
	s_barrier
	s_setprio 1
	s_waitcnt lgkmcnt(0)
	v_mfma_f32_16x16x32_bf16 v[52:55], v[148:151], v[186:189], v[52:55]
	v_mfma_f32_16x16x32_bf16 v[48:51], v[162:165], v[186:189], v[48:51]
	v_mfma_f32_16x16x32_bf16 v[68:71], v[148:151], v[194:197], v[68:71]
	v_mfma_f32_16x16x32_bf16 v[64:67], v[162:165], v[194:197], v[64:67]
	v_mfma_f32_16x16x32_bf16 v[84:87], v[148:151], v[202:205], v[84:87]
	v_mfma_f32_16x16x32_bf16 v[80:83], v[162:165], v[202:205], v[80:83]
	v_mfma_f32_16x16x32_bf16 v[92:95], v[148:151], v[210:213], v[92:95]
	v_mfma_f32_16x16x32_bf16 v[88:91], v[162:165], v[210:213], v[88:91]
	v_mfma_f32_16x16x32_bf16 v[52:55], v[158:161], v[190:193], v[52:55]
	v_mfma_f32_16x16x32_bf16 v[48:51], v[166:169], v[190:193], v[48:51]
	v_mfma_f32_16x16x32_bf16 v[68:71], v[158:161], v[198:201], v[68:71]
	v_mfma_f32_16x16x32_bf16 v[64:67], v[166:169], v[198:201], v[64:67]
	v_mfma_f32_16x16x32_bf16 v[84:87], v[158:161], v[206:209], v[84:87]
	v_mfma_f32_16x16x32_bf16 v[80:83], v[166:169], v[206:209], v[80:83]
	v_mfma_f32_16x16x32_bf16 v[92:95], v[158:161], v[214:217], v[92:95]
	v_mfma_f32_16x16x32_bf16 v[88:91], v[166:169], v[214:217], v[88:91]
	s_setprio 0
	s_setprio 1
	v_mfma_f32_16x16x32_bf16 v[4:7], v[170:173], v[186:189], v[4:7]
	v_mfma_f32_16x16x32_bf16 v[0:3], v[178:181], v[186:189], v[0:3]
	v_mfma_f32_16x16x32_bf16 v[12:15], v[170:173], v[194:197], v[12:15]
	v_mfma_f32_16x16x32_bf16 v[8:11], v[178:181], v[194:197], v[8:11]
	v_mfma_f32_16x16x32_bf16 v[20:23], v[170:173], v[202:205], v[20:23]
	v_mfma_f32_16x16x32_bf16 v[16:19], v[178:181], v[202:205], v[16:19]
	v_mfma_f32_16x16x32_bf16 v[28:31], v[170:173], v[210:213], v[28:31]
	v_mfma_f32_16x16x32_bf16 v[24:27], v[178:181], v[210:213], v[24:27]
	v_mfma_f32_16x16x32_bf16 v[4:7], v[174:177], v[190:193], v[4:7]
	v_mfma_f32_16x16x32_bf16 v[0:3], v[182:185], v[190:193], v[0:3]
	v_mfma_f32_16x16x32_bf16 v[12:15], v[174:177], v[198:201], v[12:15]
	v_mfma_f32_16x16x32_bf16 v[8:11], v[182:185], v[198:201], v[8:11]
	v_mfma_f32_16x16x32_bf16 v[20:23], v[174:177], v[206:209], v[20:23]
	v_mfma_f32_16x16x32_bf16 v[16:19], v[182:185], v[206:209], v[16:19]
	v_mfma_f32_16x16x32_bf16 v[28:31], v[174:177], v[214:217], v[28:31]
	v_mfma_f32_16x16x32_bf16 v[24:27], v[182:185], v[214:217], v[24:27]
	s_setprio 0
	s_barrier
; #define PG8_STAGE(bufoff, gbase, voff) do { _Pragma("unroll") for (int _i = 0; _i < 2; ++_i) \
;         __builtin_amdgcn_global_load_lds((const unsigned*)((const char*)(gbase) + (voff)[_i]), (PG8_LAS unsigned*)(lds + (bufoff) + ldsw + _i * 8192), 16, 0, 0); } while (0)
; #define PG8_LDA(dst, b, h) do { _Pragma("unroll") for (int m = 0; m < 4; ++m) _Pragma("unroll") for (int k = 0; k < 2; ++k) dst[m][k] = *(const PG8_LAS bf16x8*)(lds + PG8_SA(b, h) + aoff + m * 2048 + k * 1024); } while (0)
; #define PG8_MMA(ai, bj, At, Bt) do { __builtin_amdgcn_s_setprio(1); _Pragma("unroll") for (int m = 0; m < 4; ++m) _Pragma("unroll") for (int n = 0; n < 2; ++n) _Pragma("unroll") for (int k = 0; k < 2; ++k) \
;         acc[ai][bj][m][n] = __builtin_amdgcn_mfma_f32_16x16x32_bf16(Bt[n][k], At[m][k], acc[ai][bj][m][n], 0, 0, 0); __builtin_amdgcn_s_setprio(0); } while (0)
; #define PG8_WAIT_V(n) asm volatile("s_waitcnt vmcnt(" #n ")" ::: "memory")
; #define PG8_WAIT_L(n) asm volatile("s_waitcnt lgkmcnt(" #n ")" ::: "memory")
; #define PG8_BAR __builtin_amdgcn_s_barrier()
; #define PG8_SCHED __builtin_amdgcn_sched_barrier(0)
; template <class Epi, class Sched, bool ALIGN_EPI = false, bool SP2 = false, bool MIDHOOK = false>
; __device__ __forceinline__ void gemm_phase(PG8_LAS unsigned char* lds, const Gemm g, const Sched& S, const Epi& E) {
;     ...
;             PG8_LDA(At, 1, 1); PG8_STAGE(PG8_SB(1, 0), b3, voffB); PG8_STAGE(PG8_SB(1, 1), b3 + hstep, voffB); PG8_STAGE(PG8_SA(1, 0), a3, voffA);
;             PG8_WAIT_V(8); PG8_WAIT_L(0); PG8_BAR; PG8_MMA(1, 0, At, B0); PG8_MMA(1, 1, At, B1); PG8_BAR; PG8_SCHED;
;     ...
;     PG8_WAIT_V(0);
;     if constexpr (!ALIGN_EPI) { if (wr == 0) PG8_BAR; }
	s_mov_b32 m0, s43
	v_lshl_add_u64 v[152:153], v[152:153], 0, s[12:13]
	s_add_u32 s22, s22, 0x40080
	ds_read_b128 v[186:189], v143 offset:49152
	ds_read_b128 v[190:193], v143 offset:50176
	ds_read_b128 v[194:197], v143 offset:51200
	ds_read_b128 v[198:201], v143 offset:52224
	ds_read_b128 v[202:205], v143 offset:53248
	ds_read_b128 v[206:209], v143 offset:54272
	ds_read_b128 v[210:213], v143 offset:55296
	ds_read_b128 v[214:217], v143 offset:56320
	global_load_lds_dwordx4 v[152:153], off
	v_lshl_add_u64 v[152:153], v[218:219], 0, s[12:13]
	s_mov_b32 m0, s44
	s_addc_u32 s23, s23, 0
	global_load_lds_dwordx4 v[152:153], off
	v_lshl_add_u64 v[152:153], s[22:23], 0, v[130:131]
	s_mov_b32 m0, s45
	s_nop 0
	global_load_lds_dwordx4 v[152:153], off
	v_lshl_add_u64 v[152:153], s[22:23], 0, v[134:135]
	s_mov_b32 m0, s46
	s_nop 0
	global_load_lds_dwordx4 v[152:153], off
	v_lshl_add_u64 v[152:153], v[222:223], 0, s[12:13]
	s_mov_b32 m0, s31
	s_nop 0
	global_load_lds_dwordx4 v[152:153], off
	v_lshl_add_u64 v[152:153], v[224:225], 0, s[12:13]
	s_mov_b32 m0, s33
	s_nop 0
	global_load_lds_dwordx4 v[152:153], off
	s_waitcnt vmcnt(8)
	s_waitcnt lgkmcnt(0)
	s_barrier
	s_setprio 1
	s_waitcnt lgkmcnt(0)
	v_mfma_f32_16x16x32_bf16 v[100:103], v[148:151], v[186:189], v[100:103]
	v_mfma_f32_16x16x32_bf16 v[96:99], v[162:165], v[186:189], v[96:99]
	v_mfma_f32_16x16x32_bf16 v[108:111], v[148:151], v[194:197], v[108:111]
	v_mfma_f32_16x16x32_bf16 v[104:107], v[162:165], v[194:197], v[104:107]
	v_mfma_f32_16x16x32_bf16 v[124:127], v[148:151], v[202:205], v[124:127]
	v_mfma_f32_16x16x32_bf16 v[120:123], v[162:165], v[202:205], v[120:123]
	v_mfma_f32_16x16x32_bf16 v[116:119], v[148:151], v[210:213], v[116:119]
	v_mfma_f32_16x16x32_bf16 v[112:115], v[162:165], v[210:213], v[112:115]
	v_mfma_f32_16x16x32_bf16 v[100:103], v[158:161], v[190:193], v[100:103]
	v_mfma_f32_16x16x32_bf16 v[96:99], v[166:169], v[190:193], v[96:99]
	v_mfma_f32_16x16x32_bf16 v[108:111], v[158:161], v[198:201], v[108:111]
	v_mfma_f32_16x16x32_bf16 v[104:107], v[166:169], v[198:201], v[104:107]
	v_mfma_f32_16x16x32_bf16 v[124:127], v[158:161], v[206:209], v[124:127]
	v_mfma_f32_16x16x32_bf16 v[120:123], v[166:169], v[206:209], v[120:123]
	v_mfma_f32_16x16x32_bf16 v[116:119], v[158:161], v[214:217], v[116:119]
	v_mfma_f32_16x16x32_bf16 v[112:115], v[166:169], v[214:217], v[112:115]
	s_setprio 0
	s_setprio 1
	v_mfma_f32_16x16x32_bf16 v[36:39], v[170:173], v[186:189], v[36:39]
	v_mfma_f32_16x16x32_bf16 v[32:35], v[178:181], v[186:189], v[32:35]
	v_mfma_f32_16x16x32_bf16 v[44:47], v[170:173], v[194:197], v[44:47]
	v_mfma_f32_16x16x32_bf16 v[40:43], v[178:181], v[194:197], v[40:43]
	v_mfma_f32_16x16x32_bf16 v[60:63], v[170:173], v[202:205], v[60:63]
	v_mfma_f32_16x16x32_bf16 v[56:59], v[178:181], v[202:205], v[56:59]
	v_mfma_f32_16x16x32_bf16 v[76:79], v[170:173], v[210:213], v[76:79]
	v_mfma_f32_16x16x32_bf16 v[72:75], v[178:181], v[210:213], v[72:75]
	v_mfma_f32_16x16x32_bf16 v[36:39], v[174:177], v[190:193], v[36:39]
	v_mfma_f32_16x16x32_bf16 v[32:35], v[182:185], v[190:193], v[32:35]
	v_mfma_f32_16x16x32_bf16 v[44:47], v[174:177], v[198:201], v[44:47]
	v_mfma_f32_16x16x32_bf16 v[40:43], v[182:185], v[198:201], v[40:43]
	v_mfma_f32_16x16x32_bf16 v[60:63], v[174:177], v[206:209], v[60:63]
	v_mfma_f32_16x16x32_bf16 v[56:59], v[182:185], v[206:209], v[56:59]
	v_mfma_f32_16x16x32_bf16 v[76:79], v[174:177], v[214:217], v[76:79]
	v_mfma_f32_16x16x32_bf16 v[72:75], v[182:185], v[214:217], v[72:75]
	s_setprio 0
	s_barrier
	s_add_i32 s36, s36, 2
	s_add_u32 s16, s16, 0x100
	s_addc_u32 s17, s17, 0
	s_cmp_lt_u32 s36, 14
	s_cbranch_scc1 .LBB0_3912
	s_waitcnt vmcnt(0)
	s_cmp_gt_u32 s84, 3
	s_cbranch_scc1 .LBB0_3915
	s_barrier

; __device__ __forceinline__ unsigned xb_ld(unsigned* p)              { return __hip_atomic_load(p, __ATOMIC_RELAXED, __HIP_MEMORY_SCOPE_AGENT); }
; __device__ __forceinline__ unsigned xb_add(unsigned* p, unsigned v) { return __hip_atomic_fetch_add(p, v, __ATOMIC_RELAXED, __HIP_MEMORY_SCOPE_AGENT); }
; #define XB_SPIN(cond, bar) do { unsigned _sp = 0; while (cond) { __builtin_amdgcn_s_sleep(1); \
;     if ((++_sp & 255u) == 0u) { if (xb_ld(&(bar)[XB_TMO])) break; if (_sp > XB_SPIN_CAP) { atomicAdd(&(bar)[XB_TMO], 1u); break; } } } } while (0)
; __device__ __forceinline__ void xcd_barrier(const XcdBarrier& b) {
;     ...
;         const unsigned old = xb_add(&bar[XB_XSUB(b.x)], 1u);
;         const unsigned gen = old / nloc;
;         if (old + 1u == (gen + 1u) * nloc) {
;             __builtin_amdgcn_fence(__ATOMIC_RELEASE, "agent");
;             asm volatile("s_waitcnt vmcnt(0)" ::: "memory");
;             const unsigned og = xb_add(&bar[XB_TOP], 1u);
;             const unsigned tg = og / nx;
;             if (og + 1u == (tg + 1u) * nx) xb_add(&bar[XB_TOPGEN], 1u);
;             else XB_SPIN(xb_ld(&bar[XB_TOPGEN]) == tg, bar);
.LBB0_4071:
	s_or_b64 exec, exec, s[18:19]
	v_cvt_f32_u32_e32 v3, v0
	s_waitcnt vmcnt(0)
	v_readfirstlane_b32 s10, v2
	s_add_u32 s18, s82, 0x7500
	s_addc_u32 s19, s83, 0
	v_rcp_iflag_f32_e32 v3, v3
	v_add_u32_e32 v1, s10, v1
	v_add_u32_e32 v4, 1, v1
	s_mov_b64 s[20:21], -1
	v_mul_f32_e32 v2, 0x4f7ffffe, v3
	v_cvt_u32_f32_e32 v2, v2
	v_sub_u32_e32 v3, 0, v0
	v_mul_lo_u32 v3, v3, v2
	v_mul_hi_u32 v3, v2, v3
	v_add_u32_e32 v2, v2, v3
	v_mul_hi_u32 v2, v1, v2
	v_mul_lo_u32 v3, v2, v0
	v_sub_u32_e32 v1, v1, v3
	v_add_u32_e32 v5, 1, v2
	v_cmp_ge_u32_e32 vcc, v1, v0
	v_sub_u32_e32 v3, v1, v0
	s_nop 0
	v_cndmask_b32_e32 v2, v2, v5, vcc
	v_cndmask_b32_e32 v1, v1, v3, vcc
	v_add_u32_e32 v3, 1, v2
	v_cmp_ge_u32_e32 vcc, v1, v0
	s_nop 1
	v_cndmask_b32_e32 v2, v2, v3, vcc
	v_mul_lo_u32 v1, v0, v2
	v_add_u32_e32 v0, v1, v0
	v_cmp_ne_u32_e32 vcc, v4, v0
	v_mov_b64_e32 v[0:1], s[18:19]
	s_cbranch_vccnz .Lbar_notlast_7
	v_mov_b32_e32 v3, 0x6400
	v_mov_b32_e32 v5, 1
	global_atomic_add v3, v5, s[82:83]
	global_atomic_add v3, v5, s[82:83] offset:256
	global_atomic_add v3, v5, s[82:83] offset:512
	global_atomic_add v3, v5, s[82:83] offset:768
	global_atomic_add v3, v5, s[82:83] offset:1024
	global_atomic_add v3, v5, s[82:83] offset:1280
	global_atomic_add v3, v5, s[82:83] offset:1536
	global_atomic_add v3, v5, s[82:83] offset:1792
	global_atomic_add v3, v5, s[82:83] offset:2048
	global_atomic_add v3, v5, s[82:83] offset:2304
	global_atomic_add v3, v5, s[82:83] offset:2560
	global_atomic_add v3, v5, s[82:83] offset:2816
	global_atomic_add v3, v5, s[82:83] offset:3072
	global_atomic_add v3, v5, s[82:83] offset:3328
	global_atomic_add v3, v5, s[82:83] offset:3584
	global_atomic_add v3, v5, s[82:83] offset:3840
.Lbar_notlast_7:
	s_and_saveexec_b64 s[10:11], vcc
	s_cbranch_execz .LBB0_4083
	v_mov_b32_e32 v0, 0
	global_load_dword v1, v0, s[18:19] sc1
	s_mov_b64 s[24:25], 0
	s_waitcnt vmcnt(0)
	v_cmp_eq_u32_e32 vcc, v1, v2
	s_and_saveexec_b64 s[22:23], vcc
	s_cbranch_execz .LBB0_4082
	s_add_u32 s20, s82, 0x4200
	s_addc_u32 s21, s83, 0
	s_mov_b32 s17, 1
	s_branch .LBB0_4075

; __device__ __forceinline__ unsigned xb_add(unsigned* p, unsigned v) { return __hip_atomic_fetch_add(p, v, __ATOMIC_RELAXED, __HIP_MEMORY_SCOPE_AGENT); }
; __device__ __forceinline__ void xcd_barrier(const XcdBarrier& b) {
;     ...
;             __builtin_amdgcn_fence(__ATOMIC_ACQUIRE, "agent");
;             xb_add(&bar[XB_XGEN(b.x)], 1u);
;             asm volatile("s_waitcnt vmcnt(0)" ::: "memory");
.LBB0_4085:
	s_or_b64 exec, exec, s[10:11]
	s_mov_b64 s[10:11], exec
	v_mbcnt_lo_u32_b32 v0, s10, 0
	v_mbcnt_hi_u32_b32 v0, s11, v0
	v_cmp_eq_u32_e32 vcc, 0, v0
	s_waitcnt vmcnt(0)
	buffer_inv sc1
	s_and_saveexec_b64 s[18:19], vcc
	s_cbranch_execz .LBB0_4087
	s_bcnt1_i32_b64 s10, s[10:11]
	v_mov_b32_e32 v0, 0x2000
	v_mov_b32_e32 v1, s10
	s_nop 0

; #define PG8_STAGE(bufoff, gbase, voff) do { _Pragma("unroll") for (int _i = 0; _i < 2; ++_i) \
;         __builtin_amdgcn_global_load_lds((const unsigned*)((const char*)(gbase) + (voff)[_i]), (PG8_LAS unsigned*)(lds + (bufoff) + ldsw + _i * 8192), 16, 0, 0); } while (0)
; #define PG8_LDA(dst, b, h) do { _Pragma("unroll") for (int m = 0; m < 4; ++m) _Pragma("unroll") for (int k = 0; k < 2; ++k) dst[m][k] = *(const PG8_LAS bf16x8*)(lds + PG8_SA(b, h) + aoff + m * 2048 + k * 1024); } while (0)
; #define PG8_LDB(dst, b, h) do { _Pragma("unroll") for (int n = 0; n < 2; ++n) _Pragma("unroll") for (int k = 0; k < 2; ++k) dst[n][k] = *(const PG8_LAS bf16x8*)(lds + PG8_SB(b, h) + boff + n * 2048 + k * 1024); } while (0)
; #define PG8_WAIT_V(n) asm volatile("s_waitcnt vmcnt(" #n ")" ::: "memory")
; #define PG8_WAIT_L(n) asm volatile("s_waitcnt lgkmcnt(" #n ")" ::: "memory")
; #define PG8_BAR __builtin_amdgcn_s_barrier()
; #define PG8_SCHED __builtin_amdgcn_sched_barrier(0)
; template <class Epi, class Sched, bool ALIGN_EPI = false, bool SP2 = false, bool MIDHOOK = false>
; __device__ __forceinline__ void gemm_phase(PG8_LAS unsigned char* lds, const Gemm g, const Sched& S, const Epi& E) {
;     ...
;         for (int t = 0; t < nt; t += 2) {
;             if constexpr (MIDHOOK) { if (t == nt / 2) E.mid(acc, cur, wr, wc, fr, fq); }
;             const bool last = (t == nt - 2);
;             const char* a1 = cA + (size_t)(t + 1) * kstep;
;             const char* a2 = last ? nA : cA + (size_t)(t + 2) * kstep; const char* b2 = last ? nB : cB + (size_t)(t + 2) * kstep;
;             const char* a3 = a2 + kstep; const char* b3 = b2 + kstep;
;             if (last && has_next) S.a_ready(nxt);
;             if constexpr (SP2) {
;             PG8_LDB(B0, 0, 0); PG8_LDB(B1, 0, 1); PG8_SCHED; PG8_LDA(At, 0, 0); PG8_STAGE(PG8_SA(1, 1), a1 + hstep, voffA);
;             PG8_WAIT_V(8); PG8_WAIT_L(0); PG8_BAR; PG8_MMA(0, 0, At, B0); PG8_MMA(0, 1, At, B1); PG8_BAR; PG8_SCHED;
;     ...
; #pragma unroll
;         for (int a = 0; a < 2; ++a)
; #pragma unroll
;             for (int b = 0; b < 2; ++b)
; #pragma unroll
;                 for (int m = 0; m < 4; ++m)
; #pragma unroll
;                     for (int n = 0; n < 2; ++n) acc[a][b][m][n] = (f32x4){0.f, 0.f, 0.f, 0.f};
;         cur = nxt; cA = nA; cB = nB; ++ui;
.LBB0_4105:
	s_ashr_i32 s31, s30, 31
	s_lshl_b64 s[34:35], s[30:31], 19
	s_add_u32 s34, s14, s34
	s_addc_u32 s35, s15, s35
	s_and_b64 s[36:37], s[4:5], exec
	s_cselect_b32 s31, s35, s41
	s_cselect_b32 s60, s34, s40
	s_ashr_i32 s29, s28, 31
	s_lshl_b64 s[36:37], s[28:29], 19
	v_readlane_b32 s44, v243, 28
	v_readlane_b32 s45, v243, 29
	s_add_u32 s36, s44, s36
	s_addc_u32 s37, s45, s37
	s_and_b64 s[44:45], s[4:5], exec
	s_cselect_b32 s29, s37, s43
	s_cselect_b32 s61, s36, s42
	s_add_u32 s40, s40, 0x40080
	s_addc_u32 s41, s41, 0
	s_add_u32 s62, s42, 0x100
	v_mov_b32_e32 v0, 0
	s_addc_u32 s63, s43, 0
	s_mov_b32 s64, -2
	v_mov_b32_e32 v1, v0
	v_mov_b32_e32 v2, v0
	v_mov_b32_e32 v3, v0
	v_mov_b32_e32 v4, v0
	v_mov_b32_e32 v5, v0
	v_mov_b32_e32 v6, v0
	v_mov_b32_e32 v7, v0
	v_mov_b32_e32 v16, v0
	v_mov_b32_e32 v17, v0
	v_mov_b32_e32 v18, v0
	v_mov_b32_e32 v19, v0
	v_mov_b32_e32 v20, v0
	v_mov_b32_e32 v21, v0
	v_mov_b32_e32 v22, v0
	v_mov_b32_e32 v23, v0
	v_mov_b32_e32 v32, v0
	v_mov_b32_e32 v33, v0
	v_mov_b32_e32 v34, v0
	v_mov_b32_e32 v35, v0
	v_mov_b32_e32 v36, v0
	v_mov_b32_e32 v37, v0
	v_mov_b32_e32 v38, v0
	v_mov_b32_e32 v39, v0
	v_mov_b32_e32 v48, v0
	v_mov_b32_e32 v49, v0
	v_mov_b32_e32 v50, v0
	v_mov_b32_e32 v51, v0
	v_mov_b32_e32 v52, v0
	v_mov_b32_e32 v53, v0
	v_mov_b32_e32 v54, v0
	v_mov_b32_e32 v55, v0
	v_mov_b32_e32 v8, v0
	v_mov_b32_e32 v9, v0
	v_mov_b32_e32 v10, v0
	v_mov_b32_e32 v11, v0
	v_mov_b32_e32 v12, v0
	v_mov_b32_e32 v13, v0
	v_mov_b32_e32 v14, v0
	v_mov_b32_e32 v15, v0
	v_mov_b32_e32 v24, v0
	v_mov_b32_e32 v25, v0
	v_mov_b32_e32 v26, v0
	v_mov_b32_e32 v27, v0
	v_mov_b32_e32 v28, v0
	v_mov_b32_e32 v29, v0
	v_mov_b32_e32 v30, v0
	v_mov_b32_e32 v31, v0
	v_mov_b32_e32 v40, v0
	v_mov_b32_e32 v41, v0
	v_mov_b32_e32 v42, v0
	v_mov_b32_e32 v43, v0
	v_mov_b32_e32 v44, v0
	v_mov_b32_e32 v45, v0
	v_mov_b32_e32 v46, v0
	v_mov_b32_e32 v47, v0
	v_mov_b32_e32 v56, v0
	v_mov_b32_e32 v57, v0
	v_mov_b32_e32 v58, v0
	v_mov_b32_e32 v59, v0
	v_mov_b32_e32 v60, v0
	v_mov_b32_e32 v61, v0
	v_mov_b32_e32 v62, v0
	v_mov_b32_e32 v63, v0
	v_mov_b32_e32 v64, v0
	v_mov_b32_e32 v65, v0
	v_mov_b32_e32 v66, v0
	v_mov_b32_e32 v67, v0
	v_mov_b32_e32 v68, v0
	v_mov_b32_e32 v69, v0
	v_mov_b32_e32 v70, v0
	v_mov_b32_e32 v71, v0
	v_mov_b32_e32 v80, v0
	v_mov_b32_e32 v81, v0
	v_mov_b32_e32 v82, v0
	v_mov_b32_e32 v83, v0
	v_mov_b32_e32 v84, v0
	v_mov_b32_e32 v85, v0
	v_mov_b32_e32 v86, v0
	v_mov_b32_e32 v87, v0
	v_mov_b32_e32 v96, v0
	v_mov_b32_e32 v97, v0
	v_mov_b32_e32 v98, v0
	v_mov_b32_e32 v99, v0
	v_mov_b32_e32 v100, v0
	v_mov_b32_e32 v101, v0
	v_mov_b32_e32 v102, v0
	v_mov_b32_e32 v103, v0
	v_mov_b32_e32 v112, v0
	v_mov_b32_e32 v113, v0
	v_mov_b32_e32 v114, v0
	v_mov_b32_e32 v115, v0
	v_mov_b32_e32 v116, v0
	v_mov_b32_e32 v117, v0
	v_mov_b32_e32 v118, v0
	v_mov_b32_e32 v119, v0
	v_mov_b32_e32 v72, v0
	v_mov_b32_e32 v73, v0
	v_mov_b32_e32 v74, v0
	v_mov_b32_e32 v75, v0
	v_mov_b32_e32 v76, v0
	v_mov_b32_e32 v77, v0
	v_mov_b32_e32 v78, v0
	v_mov_b32_e32 v79, v0
	v_mov_b32_e32 v88, v0
	v_mov_b32_e32 v89, v0
	v_mov_b32_e32 v90, v0
	v_mov_b32_e32 v91, v0
	v_mov_b32_e32 v92, v0
	v_mov_b32_e32 v93, v0
	v_mov_b32_e32 v94, v0
	v_mov_b32_e32 v95, v0
	v_mov_b32_e32 v104, v0
	v_mov_b32_e32 v105, v0
	v_mov_b32_e32 v106, v0
	v_mov_b32_e32 v107, v0
	v_mov_b32_e32 v108, v0
	v_mov_b32_e32 v109, v0
	v_mov_b32_e32 v110, v0
	v_mov_b32_e32 v111, v0
	v_mov_b32_e32 v120, v0
	v_mov_b32_e32 v121, v0
	v_mov_b32_e32 v122, v0
	v_mov_b32_e32 v123, v0
	v_mov_b32_e32 v124, v0
	v_mov_b32_e32 v125, v0
	v_mov_b32_e32 v126, v0
	v_mov_b32_e32 v127, v0
	s_nop 0
	s_nop 0
	s_nop 0
	s_nop 0
	s_nop 0
	s_nop 0
.LBB0_4106:
	ds_read_b128 v[156:159], v149
	ds_read_b128 v[160:163], v149 offset:1024
	ds_read_b128 v[164:167], v149 offset:2048
	ds_read_b128 v[168:171], v149 offset:3072
	ds_read_b128 v[172:175], v150
	ds_read_b128 v[176:179], v150 offset:1024
	ds_read_b128 v[180:183], v150 offset:2048
	ds_read_b128 v[184:187], v150 offset:3072
	s_add_u32 s42, s40, 0xfffc0080
	s_addc_u32 s43, s41, -1
	s_cmp_eq_u32 s64, 12
	s_cselect_b32 s45, s31, s43
	s_cselect_b32 s44, s60, s42
	s_cselect_b32 s43, s29, s63
	s_cselect_b32 s42, s61, s62
	v_lshl_add_u64 v[144:145], s[40:41], 0, v[136:137]
	s_add_i32 m0, s39, 0xc000
	ds_read_b128 v[188:191], v151
	ds_read_b128 v[192:195], v151 offset:1024
	ds_read_b128 v[196:199], v151 offset:2048
	ds_read_b128 v[200:203], v151 offset:3072
	ds_read_b128 v[204:207], v151 offset:4096
	ds_read_b128 v[208:211], v151 offset:5120
	ds_read_b128 v[212:215], v151 offset:6144
	ds_read_b128 v[216:219], v151 offset:7168
	global_load_lds_dwordx4 v[144:145], off
	v_lshl_add_u64 v[144:145], s[40:41], 0, v[138:139]
	s_add_i32 m0, s39, 0xe000
	s_nop 0
	global_load_lds_dwordx4 v[144:145], off
	s_waitcnt vmcnt(8)
	s_waitcnt lgkmcnt(0)
	s_barrier
; #define PG8_STAGE(bufoff, gbase, voff) do { _Pragma("unroll") for (int _i = 0; _i < 2; ++_i) \
;         __builtin_amdgcn_global_load_lds((const unsigned*)((const char*)(gbase) + (voff)[_i]), (PG8_LAS unsigned*)(lds + (bufoff) + ldsw + _i * 8192), 16, 0, 0); } while (0)
; #define PG8_LDA(dst, b, h) do { _Pragma("unroll") for (int m = 0; m < 4; ++m) _Pragma("unroll") for (int k = 0; k < 2; ++k) dst[m][k] = *(const PG8_LAS bf16x8*)(lds + PG8_SA(b, h) + aoff + m * 2048 + k * 1024); } while (0)
; #define PG8_LDB(dst, b, h) do { _Pragma("unroll") for (int n = 0; n < 2; ++n) _Pragma("unroll") for (int k = 0; k < 2; ++k) dst[n][k] = *(const PG8_LAS bf16x8*)(lds + PG8_SB(b, h) + boff + n * 2048 + k * 1024); } while (0)
; #define PG8_MMA(ai, bj, At, Bt) do { __builtin_amdgcn_s_setprio(1); _Pragma("unroll") for (int m = 0; m < 4; ++m) _Pragma("unroll") for (int n = 0; n < 2; ++n) _Pragma("unroll") for (int k = 0; k < 2; ++k) \
;         acc[ai][bj][m][n] = __builtin_amdgcn_mfma_f32_16x16x32_bf16(Bt[n][k], At[m][k], acc[ai][bj][m][n], 0, 0, 0); __builtin_amdgcn_s_setprio(0); } while (0)
; #define PG8_WAIT_V(n) asm volatile("s_waitcnt vmcnt(" #n ")" ::: "memory")
; #define PG8_WAIT_L(n) asm volatile("s_waitcnt lgkmcnt(" #n ")" ::: "memory")
; #define PG8_BAR __builtin_amdgcn_s_barrier()
; #define PG8_SCHED __builtin_amdgcn_sched_barrier(0)
; template <class Epi, class Sched, bool ALIGN_EPI = false, bool SP2 = false, bool MIDHOOK = false>
; __device__ __forceinline__ void gemm_phase(PG8_LAS unsigned char* lds, const Gemm g, const Sched& S, const Epi& E) {
;     ...
;             PG8_LDB(B0, 0, 0); PG8_LDB(B1, 0, 1); PG8_SCHED; PG8_LDA(At, 0, 0); PG8_STAGE(PG8_SA(1, 1), a1 + hstep, voffA);
;             PG8_WAIT_V(8); PG8_WAIT_L(0); PG8_BAR; PG8_MMA(0, 0, At, B0); PG8_MMA(0, 1, At, B1); PG8_BAR; PG8_SCHED;
;             PG8_LDA(At, 0, 1); PG8_STAGE(PG8_SB(0, 0), b2, voffB); PG8_STAGE(PG8_SB(0, 1), b2 + hstep, voffB); PG8_STAGE(PG8_SA(0, 0), a2, voffA);
;             PG8_WAIT_V(8); PG8_WAIT_L(0); PG8_BAR; PG8_MMA(1, 0, At, B0); PG8_MMA(1, 1, At, B1); PG8_BAR; PG8_SCHED;
	s_setprio 1
	s_waitcnt lgkmcnt(0)
	v_mfma_f32_16x16x32_bf16 v[124:127], v[156:159], v[188:191], v[124:127]
	v_mfma_f32_16x16x32_bf16 v[120:123], v[164:167], v[188:191], v[120:123]
	v_mfma_f32_16x16x32_bf16 v[108:111], v[156:159], v[196:199], v[108:111]
	v_mfma_f32_16x16x32_bf16 v[104:107], v[164:167], v[196:199], v[104:107]
	v_mfma_f32_16x16x32_bf16 v[92:95], v[156:159], v[204:207], v[92:95]
	v_mfma_f32_16x16x32_bf16 v[88:91], v[164:167], v[204:207], v[88:91]
	v_mfma_f32_16x16x32_bf16 v[76:79], v[156:159], v[212:215], v[76:79]
	v_mfma_f32_16x16x32_bf16 v[72:75], v[164:167], v[212:215], v[72:75]
	v_mfma_f32_16x16x32_bf16 v[124:127], v[160:163], v[192:195], v[124:127]
	v_mfma_f32_16x16x32_bf16 v[120:123], v[168:171], v[192:195], v[120:123]
	v_mfma_f32_16x16x32_bf16 v[108:111], v[160:163], v[200:203], v[108:111]
	v_mfma_f32_16x16x32_bf16 v[104:107], v[168:171], v[200:203], v[104:107]
	v_mfma_f32_16x16x32_bf16 v[92:95], v[160:163], v[208:211], v[92:95]
	v_mfma_f32_16x16x32_bf16 v[88:91], v[168:171], v[208:211], v[88:91]
	v_mfma_f32_16x16x32_bf16 v[76:79], v[160:163], v[216:219], v[76:79]
	v_mfma_f32_16x16x32_bf16 v[72:75], v[168:171], v[216:219], v[72:75]
	s_setprio 0
	s_setprio 1
	v_mfma_f32_16x16x32_bf16 v[116:119], v[172:175], v[188:191], v[116:119]
	v_mfma_f32_16x16x32_bf16 v[112:115], v[180:183], v[188:191], v[112:115]
	v_mfma_f32_16x16x32_bf16 v[100:103], v[172:175], v[196:199], v[100:103]
	v_mfma_f32_16x16x32_bf16 v[96:99], v[180:183], v[196:199], v[96:99]
	v_mfma_f32_16x16x32_bf16 v[84:87], v[172:175], v[204:207], v[84:87]
	v_mfma_f32_16x16x32_bf16 v[80:83], v[180:183], v[204:207], v[80:83]
	v_mfma_f32_16x16x32_bf16 v[68:71], v[172:175], v[212:215], v[68:71]
	v_mfma_f32_16x16x32_bf16 v[64:67], v[180:183], v[212:215], v[64:67]
	v_mfma_f32_16x16x32_bf16 v[116:119], v[176:179], v[192:195], v[116:119]
	v_mfma_f32_16x16x32_bf16 v[112:115], v[184:187], v[192:195], v[112:115]
	v_mfma_f32_16x16x32_bf16 v[100:103], v[176:179], v[200:203], v[100:103]
	v_mfma_f32_16x16x32_bf16 v[96:99], v[184:187], v[200:203], v[96:99]
	v_mfma_f32_16x16x32_bf16 v[84:87], v[176:179], v[208:211], v[84:87]
	v_mfma_f32_16x16x32_bf16 v[80:83], v[184:187], v[208:211], v[80:83]
	v_mfma_f32_16x16x32_bf16 v[68:71], v[176:179], v[216:219], v[68:71]
	v_mfma_f32_16x16x32_bf16 v[64:67], v[184:187], v[216:219], v[64:67]
	s_setprio 0
	s_barrier
	s_add_i32 s65, s52, s17
	v_lshl_add_u64 v[144:145], s[42:43], 0, v[130:131]
	s_mov_b32 m0, s65
	ds_read_b128 v[188:191], v151 offset:16384
	ds_read_b128 v[192:195], v151 offset:17408
	ds_read_b128 v[196:199], v151 offset:18432
	ds_read_b128 v[200:203], v151 offset:19456
	ds_read_b128 v[204:207], v151 offset:20480
	ds_read_b128 v[208:211], v151 offset:21504
	ds_read_b128 v[212:215], v151 offset:22528
	ds_read_b128 v[216:219], v151 offset:23552
	global_load_lds_dwordx4 v[144:145], off
	s_add_i32 m0, s65, 0x2000
	s_add_u32 s66, s42, 0x40000
	v_lshl_add_u64 v[152:153], s[42:43], 0, v[134:135]
	s_addc_u32 s67, s43, 0
	s_add_i32 s65, s53, s17
	global_load_lds_dwordx4 v[152:153], off
	v_lshl_add_u64 v[222:223], s[66:67], 0, v[130:131]
	s_mov_b32 m0, s65
	v_lshl_add_u64 v[224:225], s[44:45], 0, v[132:133]
	global_load_lds_dwordx4 v[222:223], off
	v_lshl_add_u64 v[222:223], s[66:67], 0, v[134:135]
	s_add_i32 m0, s65, 0x2000
	s_nop 0
	global_load_lds_dwordx4 v[222:223], off
	v_lshl_add_u64 v[222:223], s[44:45], 0, v[128:129]
	s_mov_b32 m0, s39
	s_nop 0
	global_load_lds_dwordx4 v[222:223], off
	s_mov_b32 m0, s46
	s_nop 0
	global_load_lds_dwordx4 v[224:225], off
	s_waitcnt vmcnt(8)
	s_waitcnt lgkmcnt(0)
	s_barrier
	s_setprio 1
	s_waitcnt lgkmcnt(0)
	v_mfma_f32_16x16x32_bf16 v[60:63], v[156:159], v[188:191], v[60:63]
	v_mfma_f32_16x16x32_bf16 v[56:59], v[164:167], v[188:191], v[56:59]
	v_mfma_f32_16x16x32_bf16 v[44:47], v[156:159], v[196:199], v[44:47]
	v_mfma_f32_16x16x32_bf16 v[40:43], v[164:167], v[196:199], v[40:43]
	v_mfma_f32_16x16x32_bf16 v[28:31], v[156:159], v[204:207], v[28:31]
	v_mfma_f32_16x16x32_bf16 v[24:27], v[164:167], v[204:207], v[24:27]
	v_mfma_f32_16x16x32_bf16 v[12:15], v[156:159], v[212:215], v[12:15]
	v_mfma_f32_16x16x32_bf16 v[8:11], v[164:167], v[212:215], v[8:11]
	v_mfma_f32_16x16x32_bf16 v[60:63], v[160:163], v[192:195], v[60:63]
	v_mfma_f32_16x16x32_bf16 v[56:59], v[168:171], v[192:195], v[56:59]
	v_mfma_f32_16x16x32_bf16 v[44:47], v[160:163], v[200:203], v[44:47]
	v_mfma_f32_16x16x32_bf16 v[40:43], v[168:171], v[200:203], v[40:43]
	v_mfma_f32_16x16x32_bf16 v[28:31], v[160:163], v[208:211], v[28:31]
	v_mfma_f32_16x16x32_bf16 v[24:27], v[168:171], v[208:211], v[24:27]
	v_mfma_f32_16x16x32_bf16 v[12:15], v[160:163], v[216:219], v[12:15]
	v_mfma_f32_16x16x32_bf16 v[8:11], v[168:171], v[216:219], v[8:11]
	s_setprio 0
	s_setprio 1
	v_mfma_f32_16x16x32_bf16 v[52:55], v[172:175], v[188:191], v[52:55]
	v_mfma_f32_16x16x32_bf16 v[48:51], v[180:183], v[188:191], v[48:51]
	v_mfma_f32_16x16x32_bf16 v[36:39], v[172:175], v[196:199], v[36:39]
	v_mfma_f32_16x16x32_bf16 v[32:35], v[180:183], v[196:199], v[32:35]
	v_mfma_f32_16x16x32_bf16 v[20:23], v[172:175], v[204:207], v[20:23]
	v_mfma_f32_16x16x32_bf16 v[16:19], v[180:183], v[204:207], v[16:19]
	v_mfma_f32_16x16x32_bf16 v[4:7], v[172:175], v[212:215], v[4:7]
	v_mfma_f32_16x16x32_bf16 v[0:3], v[180:183], v[212:215], v[0:3]
	v_mfma_f32_16x16x32_bf16 v[52:55], v[176:179], v[192:195], v[52:55]
	v_mfma_f32_16x16x32_bf16 v[48:51], v[184:187], v[192:195], v[48:51]
	v_mfma_f32_16x16x32_bf16 v[36:39], v[176:179], v[200:203], v[36:39]
	v_mfma_f32_16x16x32_bf16 v[32:35], v[184:187], v[200:203], v[32:35]
	v_mfma_f32_16x16x32_bf16 v[20:23], v[176:179], v[208:211], v[20:23]
	v_mfma_f32_16x16x32_bf16 v[16:19], v[184:187], v[208:211], v[16:19]
	v_mfma_f32_16x16x32_bf16 v[4:7], v[176:179], v[216:219], v[4:7]
	v_mfma_f32_16x16x32_bf16 v[0:3], v[184:187], v[216:219], v[0:3]
	s_setprio 0
	s_barrier
; #define PG8_STAGE(bufoff, gbase, voff) do { _Pragma("unroll") for (int _i = 0; _i < 2; ++_i) \
;         __builtin_amdgcn_global_load_lds((const unsigned*)((const char*)(gbase) + (voff)[_i]), (PG8_LAS unsigned*)(lds + (bufoff) + ldsw + _i * 8192), 16, 0, 0); } while (0)
; #define PG8_LDA(dst, b, h) do { _Pragma("unroll") for (int m = 0; m < 4; ++m) _Pragma("unroll") for (int k = 0; k < 2; ++k) dst[m][k] = *(const PG8_LAS bf16x8*)(lds + PG8_SA(b, h) + aoff + m * 2048 + k * 1024); } while (0)
; #define PG8_LDB(dst, b, h) do { _Pragma("unroll") for (int n = 0; n < 2; ++n) _Pragma("unroll") for (int k = 0; k < 2; ++k) dst[n][k] = *(const PG8_LAS bf16x8*)(lds + PG8_SB(b, h) + boff + n * 2048 + k * 1024); } while (0)
; #define PG8_MMA(ai, bj, At, Bt) do { __builtin_amdgcn_s_setprio(1); _Pragma("unroll") for (int m = 0; m < 4; ++m) _Pragma("unroll") for (int n = 0; n < 2; ++n) _Pragma("unroll") for (int k = 0; k < 2; ++k) \
;         acc[ai][bj][m][n] = __builtin_amdgcn_mfma_f32_16x16x32_bf16(Bt[n][k], At[m][k], acc[ai][bj][m][n], 0, 0, 0); __builtin_amdgcn_s_setprio(0); } while (0)
; #define PG8_WAIT_V(n) asm volatile("s_waitcnt vmcnt(" #n ")" ::: "memory")
; #define PG8_WAIT_L(n) asm volatile("s_waitcnt lgkmcnt(" #n ")" ::: "memory")
; #define PG8_BAR __builtin_amdgcn_s_barrier()
; #define PG8_SCHED __builtin_amdgcn_sched_barrier(0)
; template <class Epi, class Sched, bool ALIGN_EPI = false, bool SP2 = false, bool MIDHOOK = false>
; __device__ __forceinline__ void gemm_phase(PG8_LAS unsigned char* lds, const Gemm g, const Sched& S, const Epi& E) {
;     ...
;             PG8_WAIT_V(8); PG8_WAIT_L(0); PG8_BAR; PG8_MMA(1, 0, At, B0); PG8_MMA(1, 1, At, B1); PG8_BAR; PG8_SCHED;
;             PG8_LDB(B0, 1, 0); PG8_LDB(B1, 1, 1); PG8_SCHED; PG8_LDA(At, 1, 0); PG8_STAGE(PG8_SA(0, 1), a2 + hstep, voffA);
;             PG8_WAIT_V(8); PG8_WAIT_L(0); PG8_BAR; PG8_MMA(0, 0, At, B0); PG8_MMA(0, 1, At, B1); PG8_BAR; PG8_SCHED;
	s_add_i32 s65, 0, 0x18000
	s_add_i32 s66, 0, 0x1c000
	v_add_u32_e32 v168, s65, v147
	v_add_u32_e32 v184, s66, v147
	ds_read_b128 v[156:159], v168
	ds_read_b128 v[160:163], v168 offset:1024
	ds_read_b128 v[164:167], v168 offset:2048
	ds_read_b128 v[168:171], v168 offset:3072
	ds_read_b128 v[172:175], v184
	ds_read_b128 v[176:179], v184 offset:1024
	ds_read_b128 v[180:183], v184 offset:2048
	ds_read_b128 v[184:187], v184 offset:3072
	s_add_u32 s44, s44, 0x40000
	s_addc_u32 s45, s45, 0
	s_mov_b32 m0, s47
	v_lshl_add_u64 v[226:227], s[44:45], 0, v[128:129]
	ds_read_b128 v[188:191], v151 offset:32768
	ds_read_b128 v[192:195], v151 offset:33792
	ds_read_b128 v[196:199], v151 offset:34816
	ds_read_b128 v[200:203], v151 offset:35840
	ds_read_b128 v[204:207], v151 offset:36864
	ds_read_b128 v[208:211], v151 offset:37888
	ds_read_b128 v[212:215], v151 offset:38912
	ds_read_b128 v[216:219], v151 offset:39936
	global_load_lds_dwordx4 v[226:227], off
	v_lshl_add_u64 v[226:227], s[44:45], 0, v[132:133]
	s_mov_b32 m0, s48
	s_nop 0
	global_load_lds_dwordx4 v[226:227], off
	s_waitcnt vmcnt(8)
	s_waitcnt lgkmcnt(0)
	s_barrier
	s_setprio 1
	s_waitcnt lgkmcnt(0)
	v_mfma_f32_16x16x32_bf16 v[124:127], v[156:159], v[188:191], v[124:127]
	v_mfma_f32_16x16x32_bf16 v[120:123], v[164:167], v[188:191], v[120:123]
	v_mfma_f32_16x16x32_bf16 v[108:111], v[156:159], v[196:199], v[108:111]
	v_mfma_f32_16x16x32_bf16 v[104:107], v[164:167], v[196:199], v[104:107]
	v_mfma_f32_16x16x32_bf16 v[92:95], v[156:159], v[204:207], v[92:95]
	v_mfma_f32_16x16x32_bf16 v[88:91], v[164:167], v[204:207], v[88:91]
	v_mfma_f32_16x16x32_bf16 v[76:79], v[156:159], v[212:215], v[76:79]
	v_mfma_f32_16x16x32_bf16 v[72:75], v[164:167], v[212:215], v[72:75]
	v_mfma_f32_16x16x32_bf16 v[124:127], v[160:163], v[192:195], v[124:127]
	v_mfma_f32_16x16x32_bf16 v[120:123], v[168:171], v[192:195], v[120:123]
	v_mfma_f32_16x16x32_bf16 v[108:111], v[160:163], v[200:203], v[108:111]
	v_mfma_f32_16x16x32_bf16 v[104:107], v[168:171], v[200:203], v[104:107]
	v_mfma_f32_16x16x32_bf16 v[92:95], v[160:163], v[208:211], v[92:95]
	v_mfma_f32_16x16x32_bf16 v[88:91], v[168:171], v[208:211], v[88:91]
	v_mfma_f32_16x16x32_bf16 v[76:79], v[160:163], v[216:219], v[76:79]
	v_mfma_f32_16x16x32_bf16 v[72:75], v[168:171], v[216:219], v[72:75]
	s_setprio 0
	s_setprio 1
	v_mfma_f32_16x16x32_bf16 v[116:119], v[172:175], v[188:191], v[116:119]
	v_mfma_f32_16x16x32_bf16 v[112:115], v[180:183], v[188:191], v[112:115]
	v_mfma_f32_16x16x32_bf16 v[100:103], v[172:175], v[196:199], v[100:103]
	v_mfma_f32_16x16x32_bf16 v[96:99], v[180:183], v[196:199], v[96:99]
	v_mfma_f32_16x16x32_bf16 v[84:87], v[172:175], v[204:207], v[84:87]
	v_mfma_f32_16x16x32_bf16 v[80:83], v[180:183], v[204:207], v[80:83]
	v_mfma_f32_16x16x32_bf16 v[68:71], v[172:175], v[212:215], v[68:71]
	v_mfma_f32_16x16x32_bf16 v[64:67], v[180:183], v[212:215], v[64:67]
	v_mfma_f32_16x16x32_bf16 v[116:119], v[176:179], v[192:195], v[116:119]
	v_mfma_f32_16x16x32_bf16 v[112:115], v[184:187], v[192:195], v[112:115]
	v_mfma_f32_16x16x32_bf16 v[100:103], v[176:179], v[200:203], v[100:103]
	v_mfma_f32_16x16x32_bf16 v[96:99], v[184:187], v[200:203], v[96:99]
	v_mfma_f32_16x16x32_bf16 v[84:87], v[176:179], v[208:211], v[84:87]
	v_mfma_f32_16x16x32_bf16 v[80:83], v[184:187], v[208:211], v[80:83]
	v_mfma_f32_16x16x32_bf16 v[68:71], v[176:179], v[216:219], v[68:71]
	v_mfma_f32_16x16x32_bf16 v[64:67], v[184:187], v[216:219], v[64:67]
	s_setprio 0
	s_barrier
; #define PG8_STAGE(bufoff, gbase, voff) do { _Pragma("unroll") for (int _i = 0; _i < 2; ++_i) \
;         __builtin_amdgcn_global_load_lds((const unsigned*)((const char*)(gbase) + (voff)[_i]), (PG8_LAS unsigned*)(lds + (bufoff) + ldsw + _i * 8192), 16, 0, 0); } while (0)
; #define PG8_LDA(dst, b, h) do { _Pragma("unroll") for (int m = 0; m < 4; ++m) _Pragma("unroll") for (int k = 0; k < 2; ++k) dst[m][k] = *(const PG8_LAS bf16x8*)(lds + PG8_SA(b, h) + aoff + m * 2048 + k * 1024); } while (0)
; #define PG8_MMA(ai, bj, At, Bt) do { __builtin_amdgcn_s_setprio(1); _Pragma("unroll") for (int m = 0; m < 4; ++m) _Pragma("unroll") for (int n = 0; n < 2; ++n) _Pragma("unroll") for (int k = 0; k < 2; ++k) \
;         acc[ai][bj][m][n] = __builtin_amdgcn_mfma_f32_16x16x32_bf16(Bt[n][k], At[m][k], acc[ai][bj][m][n], 0, 0, 0); __builtin_amdgcn_s_setprio(0); } while (0)
; #define PG8_WAIT_V(n) asm volatile("s_waitcnt vmcnt(" #n ")" ::: "memory")
; #define PG8_WAIT_L(n) asm volatile("s_waitcnt lgkmcnt(" #n ")" ::: "memory")
; #define PG8_BAR __builtin_amdgcn_s_barrier()
; #define PG8_SCHED __builtin_amdgcn_sched_barrier(0)
; template <class Epi, class Sched, bool ALIGN_EPI = false, bool SP2 = false, bool MIDHOOK = false>
; __device__ __forceinline__ void gemm_phase(PG8_LAS unsigned char* lds, const Gemm g, const Sched& S, const Epi& E) {
;     ...
;         for (int t = 0; t < nt; t += 2) {
;     ...
;             PG8_LDA(At, 1, 1); PG8_STAGE(PG8_SB(1, 0), b3, voffB); PG8_STAGE(PG8_SB(1, 1), b3 + hstep, voffB); PG8_STAGE(PG8_SA(1, 0), a3, voffA);
;             PG8_WAIT_V(8); PG8_WAIT_L(0); PG8_BAR; PG8_MMA(1, 0, At, B0); PG8_MMA(1, 1, At, B1); PG8_BAR; PG8_SCHED;
;     ...
;         if constexpr (ALIGN_EPI) { if (wr == 0) PG8_BAR; }
	s_add_i32 s44, s65, s17
	v_lshl_add_u64 v[144:145], v[144:145], 0, s[8:9]
	s_mov_b32 m0, s44
	ds_read_b128 v[188:191], v151 offset:49152
	ds_read_b128 v[192:195], v151 offset:50176
	ds_read_b128 v[196:199], v151 offset:51200
	ds_read_b128 v[200:203], v151 offset:52224
	ds_read_b128 v[204:207], v151 offset:53248
	ds_read_b128 v[208:211], v151 offset:54272
	ds_read_b128 v[212:215], v151 offset:55296
	ds_read_b128 v[216:219], v151 offset:56320
	global_load_lds_dwordx4 v[144:145], off
	s_add_i32 m0, s44, 0x2000
	s_add_u32 s42, s42, 0x40080
	v_lshl_add_u64 v[144:145], v[152:153], 0, s[8:9]
	s_addc_u32 s43, s43, 0
	s_add_i32 s44, s66, s17
	global_load_lds_dwordx4 v[144:145], off
	v_lshl_add_u64 v[144:145], s[42:43], 0, v[130:131]
	s_mov_b32 m0, s44
	s_nop 0
	global_load_lds_dwordx4 v[144:145], off
	v_lshl_add_u64 v[144:145], s[42:43], 0, v[134:135]
	s_add_i32 m0, s44, 0x2000
	s_nop 0
	global_load_lds_dwordx4 v[144:145], off
	v_lshl_add_u64 v[144:145], v[222:223], 0, s[8:9]
	s_mov_b32 m0, s50
	s_nop 0
	global_load_lds_dwordx4 v[144:145], off
	v_lshl_add_u64 v[144:145], v[224:225], 0, s[8:9]
	s_mov_b32 m0, s51
	s_nop 0
	global_load_lds_dwordx4 v[144:145], off
	s_waitcnt vmcnt(8)
	s_waitcnt lgkmcnt(0)
	s_barrier
	s_setprio 1
	s_waitcnt lgkmcnt(0)
	v_mfma_f32_16x16x32_bf16 v[60:63], v[156:159], v[188:191], v[60:63]
	v_mfma_f32_16x16x32_bf16 v[56:59], v[164:167], v[188:191], v[56:59]
	v_mfma_f32_16x16x32_bf16 v[44:47], v[156:159], v[196:199], v[44:47]
	v_mfma_f32_16x16x32_bf16 v[40:43], v[164:167], v[196:199], v[40:43]
	v_mfma_f32_16x16x32_bf16 v[28:31], v[156:159], v[204:207], v[28:31]
	v_mfma_f32_16x16x32_bf16 v[24:27], v[164:167], v[204:207], v[24:27]
	v_mfma_f32_16x16x32_bf16 v[12:15], v[156:159], v[212:215], v[12:15]
	v_mfma_f32_16x16x32_bf16 v[8:11], v[164:167], v[212:215], v[8:11]
	v_mfma_f32_16x16x32_bf16 v[60:63], v[160:163], v[192:195], v[60:63]
	v_mfma_f32_16x16x32_bf16 v[56:59], v[168:171], v[192:195], v[56:59]
	v_mfma_f32_16x16x32_bf16 v[44:47], v[160:163], v[200:203], v[44:47]
	v_mfma_f32_16x16x32_bf16 v[40:43], v[168:171], v[200:203], v[40:43]
	v_mfma_f32_16x16x32_bf16 v[28:31], v[160:163], v[208:211], v[28:31]
	v_mfma_f32_16x16x32_bf16 v[24:27], v[168:171], v[208:211], v[24:27]
	v_mfma_f32_16x16x32_bf16 v[12:15], v[160:163], v[216:219], v[12:15]
	v_mfma_f32_16x16x32_bf16 v[8:11], v[168:171], v[216:219], v[8:11]
	s_setprio 0
	s_setprio 1
	v_mfma_f32_16x16x32_bf16 v[52:55], v[172:175], v[188:191], v[52:55]
	v_mfma_f32_16x16x32_bf16 v[48:51], v[180:183], v[188:191], v[48:51]
	v_mfma_f32_16x16x32_bf16 v[36:39], v[172:175], v[196:199], v[36:39]
	v_mfma_f32_16x16x32_bf16 v[32:35], v[180:183], v[196:199], v[32:35]
	v_mfma_f32_16x16x32_bf16 v[20:23], v[172:175], v[204:207], v[20:23]
	v_mfma_f32_16x16x32_bf16 v[16:19], v[180:183], v[204:207], v[16:19]
	v_mfma_f32_16x16x32_bf16 v[4:7], v[172:175], v[212:215], v[4:7]
	v_mfma_f32_16x16x32_bf16 v[0:3], v[180:183], v[212:215], v[0:3]
	v_mfma_f32_16x16x32_bf16 v[52:55], v[176:179], v[192:195], v[52:55]
	v_mfma_f32_16x16x32_bf16 v[48:51], v[184:187], v[192:195], v[48:51]
	v_mfma_f32_16x16x32_bf16 v[36:39], v[176:179], v[200:203], v[36:39]
	v_mfma_f32_16x16x32_bf16 v[32:35], v[184:187], v[200:203], v[32:35]
	v_mfma_f32_16x16x32_bf16 v[20:23], v[176:179], v[208:211], v[20:23]
	v_mfma_f32_16x16x32_bf16 v[16:19], v[184:187], v[208:211], v[16:19]
	v_mfma_f32_16x16x32_bf16 v[4:7], v[176:179], v[216:219], v[4:7]
	v_mfma_f32_16x16x32_bf16 v[0:3], v[184:187], v[216:219], v[0:3]
	s_setprio 0
	s_barrier
	s_add_i32 s64, s64, 2
	s_add_u32 s40, s40, 0x100
	s_addc_u32 s41, s41, 0
	s_add_u32 s62, s62, 0x100
	s_addc_u32 s63, s63, 0
	s_cmp_gt_u32 s64, 13
	s_cbranch_scc0 .LBB0_4106
	s_and_b64 vcc, exec, s[10:11]
	s_cbranch_vccz .LBB0_4109
	s_barrier

; __device__ __forceinline__ unsigned xb_ld(unsigned* p)              { return __hip_atomic_load(p, __ATOMIC_RELAXED, __HIP_MEMORY_SCOPE_AGENT); }
; __device__ __forceinline__ unsigned xb_add(unsigned* p, unsigned v) { return __hip_atomic_fetch_add(p, v, __ATOMIC_RELAXED, __HIP_MEMORY_SCOPE_AGENT); }
; #define XB_SPIN(cond, bar) do { unsigned _sp = 0; while (cond) { __builtin_amdgcn_s_sleep(1); \
;     if ((++_sp & 255u) == 0u) { if (xb_ld(&(bar)[XB_TMO])) break; if (_sp > XB_SPIN_CAP) { atomicAdd(&(bar)[XB_TMO], 1u); break; } } } } while (0)
; __device__ __forceinline__ void xcd_barrier(const XcdBarrier& b) {
;     ...
;         const unsigned old = xb_add(&bar[XB_XSUB(b.x)], 1u);
;         const unsigned gen = old / nloc;
;         if (old + 1u == (gen + 1u) * nloc) {
;             __builtin_amdgcn_fence(__ATOMIC_RELEASE, "agent");
;             asm volatile("s_waitcnt vmcnt(0)" ::: "memory");
;             const unsigned og = xb_add(&bar[XB_TOP], 1u);
;             const unsigned tg = og / nx;
;             if (og + 1u == (tg + 1u) * nx) xb_add(&bar[XB_TOPGEN], 1u);
;             else XB_SPIN(xb_ld(&bar[XB_TOPGEN]) == tg, bar);
;             __builtin_amdgcn_fence(__ATOMIC_ACQUIRE, "agent");
;             xb_add(&bar[XB_XGEN(b.x)], 1u);
.LBB0_4148:
	s_or_b64 exec, exec, s[10:11]
	v_cvt_f32_u32_e32 v3, v0
	s_waitcnt vmcnt(0)
	v_readfirstlane_b32 s8, v2
	s_add_u32 s10, s82, 0x7500
	s_addc_u32 s11, s83, 0
	v_rcp_iflag_f32_e32 v3, v3
	v_add_u32_e32 v1, s8, v1
	v_add_u32_e32 v4, 1, v1
	s_mov_b64 s[18:19], -1
	v_mul_f32_e32 v2, 0x4f7ffffe, v3
	v_cvt_u32_f32_e32 v2, v2
	v_sub_u32_e32 v3, 0, v0
	v_mul_lo_u32 v3, v3, v2
	v_mul_hi_u32 v3, v2, v3
	v_add_u32_e32 v2, v2, v3
	v_mul_hi_u32 v2, v1, v2
	v_mul_lo_u32 v3, v2, v0
	v_sub_u32_e32 v1, v1, v3
	v_add_u32_e32 v5, 1, v2
	v_cmp_ge_u32_e32 vcc, v1, v0
	v_sub_u32_e32 v3, v1, v0
	s_nop 0
	v_cndmask_b32_e32 v2, v2, v5, vcc
	v_cndmask_b32_e32 v1, v1, v3, vcc
	v_add_u32_e32 v3, 1, v2
	v_cmp_ge_u32_e32 vcc, v1, v0
	s_nop 1
	v_cndmask_b32_e32 v2, v2, v3, vcc
	v_mul_lo_u32 v1, v0, v2
	v_add_u32_e32 v0, v1, v0
	v_cmp_ne_u32_e32 vcc, v4, v0
	v_mov_b64_e32 v[0:1], s[10:11]
	s_cbranch_vccnz .Lbar_notlast_8
	v_mov_b32_e32 v3, 0x6400
	v_mov_b32_e32 v5, 1
	global_atomic_add v3, v5, s[82:83]
	global_atomic_add v3, v5, s[82:83] offset:256
	global_atomic_add v3, v5, s[82:83] offset:512
	global_atomic_add v3, v5, s[82:83] offset:768
	global_atomic_add v3, v5, s[82:83] offset:1024
	global_atomic_add v3, v5, s[82:83] offset:1280
	global_atomic_add v3, v5, s[82:83] offset:1536
	global_atomic_add v3, v5, s[82:83] offset:1792
	global_atomic_add v3, v5, s[82:83] offset:2048
	global_atomic_add v3, v5, s[82:83] offset:2304
	global_atomic_add v3, v5, s[82:83] offset:2560
	global_atomic_add v3, v5, s[82:83] offset:2816
	global_atomic_add v3, v5, s[82:83] offset:3072
	global_atomic_add v3, v5, s[82:83] offset:3328
	global_atomic_add v3, v5, s[82:83] offset:3584
	global_atomic_add v3, v5, s[82:83] offset:3840
.Lbar_notlast_8:
	s_and_saveexec_b64 s[8:9], vcc
	s_cbranch_execz .LBB0_4160
	v_mov_b32_e32 v0, 0
	global_load_dword v1, v0, s[10:11] sc1
	s_mov_b64 s[24:25], 0
	s_waitcnt vmcnt(0)
	v_cmp_eq_u32_e32 vcc, v1, v2
	s_and_saveexec_b64 s[22:23], vcc
	s_cbranch_execz .LBB0_4159
	s_add_u32 s18, s82, 0x4200
	s_addc_u32 s19, s83, 0
	s_mov_b32 s17, 1
	s_branch .LBB0_4152

; __device__ __forceinline__ unsigned xb_add(unsigned* p, unsigned v) { return __hip_atomic_fetch_add(p, v, __ATOMIC_RELAXED, __HIP_MEMORY_SCOPE_AGENT); }
; __device__ __forceinline__ void xcd_barrier(const XcdBarrier& b) {
;     ...
;             __builtin_amdgcn_fence(__ATOMIC_ACQUIRE, "agent");
;             xb_add(&bar[XB_XGEN(b.x)], 1u);
;             asm volatile("s_waitcnt vmcnt(0)" ::: "memory");
.LBB0_4162:
	s_or_b64 exec, exec, s[8:9]
	s_mov_b64 s[8:9], exec
	v_mbcnt_lo_u32_b32 v0, s8, 0
	v_mbcnt_hi_u32_b32 v0, s9, v0
	v_cmp_eq_u32_e32 vcc, 0, v0
	s_waitcnt vmcnt(0)
	buffer_inv sc1
	s_and_saveexec_b64 s[10:11], vcc
	s_cbranch_execz .LBB0_4164
	s_bcnt1_i32_b64 s8, s[8:9]
	v_mov_b32_e32 v0, 0x2000
	v_mov_b32_e32 v1, s8
	s_nop 0

;     __device__ bool next(int i, Unit& u) const { if (i != 0) return false; return so.next(round, u); }
;     __device__ __forceinline__ bool next(int i, Unit& u) const { if (i > 0 || !on) return false; u.pm = pm; u.pn = 0; return true; }
; #define PG8_STAGE(bufoff, gbase, voff) do { _Pragma("unroll") for (int _i = 0; _i < 2; ++_i) \
;         __builtin_amdgcn_global_load_lds((const unsigned*)((const char*)(gbase) + (voff)[_i]), (PG8_LAS unsigned*)(lds + (bufoff) + ldsw + _i * 8192), 16, 0, 0); } while (0)
; #define PG8_WAIT_V(n) asm volatile("s_waitcnt vmcnt(" #n ")" ::: "memory")
; template <class Epi, class Sched, bool ALIGN_EPI = false, bool SP2 = false, bool MIDHOOK = false>
; __device__ __forceinline__ void gemm_phase(PG8_LAS unsigned char* lds, const Gemm g, const Sched& S, const Epi& E) {
;     ...
;     unsigned voffA[2], voffB[2];
; #pragma unroll
;     for (int i = 0; i < 2; ++i) { int R, C; stage_rc(tid * 16 + i * 8192, R, C); const int Rb = Epi::PERM ? ((R & ~31) + perm32(R & 31)) : R;
;         voffA[i] = (unsigned)(R * LD + C) * 2u; voffB[i] = (unsigned)(Rb * LD + C) * 2u; }
;     const size_t kstep = (size_t)(BK * 2);
;     const size_t hstep = (size_t)HALF * LD * 2;
;     const size_t tstep = 2 * hstep;
;     const unsigned ldsw = (unsigned)wid * 1024u;
;     const int aoff = lds_byte(wr * 64 + fr, fq * 8), boff = lds_byte(wc * 32 + fr, fq * 8);
;     ...
;     Unit cur, nxt; int ui = 0;
;     if (!S.next(0, cur)) return;
;     f32x4 acc[2][2][4][2];
; #pragma unroll
;     for (int a = 0; a < 2; ++a)
; #pragma unroll
;         for (int b = 0; b < 2; ++b)
; #pragma unroll
;             for (int m = 0; m < 4; ++m)
; #pragma unroll
;                 for (int n = 0; n < 2; ++n) acc[a][b][m][n] = (f32x4){0.f, 0.f, 0.f, 0.f};
;     bf16x8 At[4][2], B0[2][2], B1[2][2];
;     const char* cA = (const char*)g.A + (size_t)cur.pm * tstep; const char* cB = (const char*)g.Bt + (size_t)cur.pn * tstep;
;     S.a_ready(cur);
;     if constexpr (SP2) {
;         PG8_STAGE(PG8_SB(0, 0), cB, voffB); PG8_STAGE(PG8_SB(0, 1), cB + hstep, voffB); PG8_STAGE(PG8_SA(0, 0), cA, voffA); PG8_STAGE(PG8_SA(0, 1), cA + hstep, voffA);
;         if (wr == 1) PG8_BAR;
;         PG8_WAIT_V(2); PG8_BAR;
;         PG8_STAGE(PG8_SB(1, 0), cB + kstep, voffB); PG8_STAGE(PG8_SA(1, 0), cA + kstep, voffA); PG8_STAGE(PG8_SB(1, 1), cB + hstep + kstep, voffB);
;         PG8_WAIT_V(6); PG8_BAR;
.LBB0_4174:
	s_mov_b64 s[8:9], 0x80
	s_add_i32 m0, s30, 0x18000
	v_lshl_add_u64 v[6:7], v[6:7], 0, s[8:9]
	s_and_b32 s3, s84, 3
	s_waitcnt vmcnt(2)
	s_barrier
	global_load_lds_dwordx4 v[6:7], off
	v_lshl_add_u64 v[4:5], v[4:5], 0, s[8:9]
	s_add_i32 m0, s30, 0x1a000
	s_add_i32 s35, s30, 0x8000
	s_add_i32 s36, s30, 0xa000
	global_load_lds_dwordx4 v[4:5], off
	v_lshl_add_u64 v[2:3], v[2:3], 0, s[8:9]
	s_mov_b32 m0, s35
	s_add_u32 s28, s0, 0x100080
	global_load_lds_dwordx4 v[2:3], off
	v_lshl_add_u64 v[0:1], v[0:1], 0, s[8:9]
	s_mov_b32 m0, s36
	s_addc_u32 s29, s1, 0
	global_load_lds_dwordx4 v[0:1], off
	s_add_i32 m0, s30, 0x1c000
	v_lshl_add_u64 v[0:1], s[28:29], 0, v[130:131]
	global_load_lds_dwordx4 v[0:1], off
	v_lshl_add_u64 v[0:1], s[28:29], 0, v[134:135]
	s_add_i32 m0, s30, 0x1e000
	s_add_u32 s22, s82, s22
	global_load_lds_dwordx4 v[0:1], off
	v_lshlrev_b32_e32 v0, 16, v8
	v_and_b32_e32 v0, 0xfffe0000, v0
	v_lshl_add_u32 v0, v9, 13, v0
	v_and_b32_e32 v1, 1, v8
	v_lshl_or_b32 v0, v1, 6, v0
	s_addc_u32 s23, s83, s23
	v_lshl_add_u32 v0, v10, 1, v0
	v_mov_b32_e32 v1, v131
	v_lshl_add_u64 v[0:1], s[22:23], 0, v[0:1]
	s_mov_b64 s[28:29], 0xe100080
	v_lshl_add_u64 v[136:137], v[0:1], 0, s[28:29]
	v_lshlrev_b32_e32 v0, 16, v11
	v_and_b32_e32 v15, 15, v140
	v_and_b32_e32 v16, 48, v140
	v_and_b32_e32 v0, 0xfffe0000, v0
	s_add_u32 s24, s82, s24
	v_lshl_or_b32 v146, s17, 6, v15
	v_and_b32_e32 v14, 0xfffffc00, v14
	v_lshl_or_b32 v15, v15, 6, v16
	v_lshlrev_b32_e32 v16, 2, v140
	v_lshl_add_u32 v0, v12, 13, v0
	v_and_b32_e32 v1, 1, v11
	s_addc_u32 s25, s83, s25
	v_lshl_add_u32 v17, s17, 13, v14
	v_and_b32_e32 v16, 32, v16
	v_lshl_add_u32 v14, s3, 12, v14
	v_lshl_or_b32 v0, v1, 6, v0
	s_add_u32 s37, s24, 0x1800100
	v_bitop3_b32 v14, v15, v14, v16 bitop3:0xde
	s_waitcnt vmcnt(6)
	v_lshl_add_u32 v0, v13, 1, v0
	v_mov_b32_e32 v1, v131
	s_addc_u32 s38, s25, 0
	s_add_i32 s42, 0, 0x10000
	s_add_i32 s44, 0, 0x14000
	s_add_i32 s46, 0, 0x18000
	s_add_i32 s48, 0, 0x1c000
	v_bitop3_b32 v17, v15, v17, v16 bitop3:0xde
	v_lshl_add_u64 v[0:1], s[22:23], 0, v[0:1]
	v_add_u32_e32 v141, s42, v14
	v_add_u32_e32 v142, s44, v14
	s_add_i32 s42, s42, s26
	s_add_i32 s44, s44, s26
	v_add_u32_e32 v144, s46, v14
	v_add_u32_e32 v145, s48, v14
	s_add_i32 s46, s46, s26
	s_add_i32 s48, s48, s26
	v_lshl_add_u64 v[138:139], v[0:1], 0, s[28:29]
	s_mov_b32 s39, -2
	s_mov_b64 s[24:25], 0
	v_add_u32_e32 v143, 0, v17
	s_add_i32 s40, s30, 0xc000
	s_add_i32 s41, s30, 0xe000
	s_add_i32 s43, s42, 0x2000
	s_add_i32 s45, s44, 0x2000
	s_add_i32 s47, s46, 0x2000
	s_add_i32 s49, s48, 0x2000
	v_mov_b32_e32 v72, v131
	v_mov_b32_e32 v73, v131
	v_mov_b32_e32 v74, v131
	v_mov_b32_e32 v75, v131
	v_mov_b32_e32 v76, v131
	v_mov_b32_e32 v77, v131
	v_mov_b32_e32 v78, v131
	v_mov_b32_e32 v79, v131
	v_mov_b32_e32 v56, v131
	v_mov_b32_e32 v57, v131
	v_mov_b32_e32 v58, v131
	v_mov_b32_e32 v59, v131
	v_mov_b32_e32 v60, v131
	v_mov_b32_e32 v61, v131
	v_mov_b32_e32 v62, v131
	v_mov_b32_e32 v63, v131
	v_mov_b32_e32 v40, v131
	v_mov_b32_e32 v41, v131
	v_mov_b32_e32 v42, v131
	v_mov_b32_e32 v43, v131
	v_mov_b32_e32 v44, v131
	v_mov_b32_e32 v45, v131
	v_mov_b32_e32 v46, v131
	v_mov_b32_e32 v47, v131
	v_mov_b32_e32 v32, v131
	v_mov_b32_e32 v33, v131
	v_mov_b32_e32 v34, v131
	v_mov_b32_e32 v35, v131
	v_mov_b32_e32 v36, v131
	v_mov_b32_e32 v37, v131
	v_mov_b32_e32 v38, v131
	v_mov_b32_e32 v39, v131
	v_mov_b32_e32 v116, v131
	v_mov_b32_e32 v117, v131
	v_mov_b32_e32 v118, v131
	v_mov_b32_e32 v119, v131
	v_mov_b32_e32 v120, v131
	v_mov_b32_e32 v121, v131
	v_mov_b32_e32 v122, v131
	v_mov_b32_e32 v123, v131
	v_mov_b32_e32 v112, v131
	v_mov_b32_e32 v113, v131
	v_mov_b32_e32 v114, v131
	v_mov_b32_e32 v115, v131
	v_mov_b32_e32 v124, v131
	v_mov_b32_e32 v125, v131
	v_mov_b32_e32 v126, v131
	v_mov_b32_e32 v127, v131
	v_mov_b32_e32 v104, v131
	v_mov_b32_e32 v105, v131
	v_mov_b32_e32 v106, v131
	v_mov_b32_e32 v107, v131
	v_mov_b32_e32 v108, v131
	v_mov_b32_e32 v109, v131
	v_mov_b32_e32 v110, v131
	v_mov_b32_e32 v111, v131
	v_mov_b32_e32 v96, v131
	v_mov_b32_e32 v97, v131
	v_mov_b32_e32 v98, v131
	v_mov_b32_e32 v99, v131
	v_mov_b32_e32 v100, v131
	v_mov_b32_e32 v101, v131
	v_mov_b32_e32 v102, v131
	v_mov_b32_e32 v103, v131
	v_mov_b32_e32 v24, v131
	v_mov_b32_e32 v25, v131
	v_mov_b32_e32 v26, v131
	v_mov_b32_e32 v27, v131
	v_mov_b32_e32 v28, v131
	v_mov_b32_e32 v29, v131
	v_mov_b32_e32 v30, v131
	v_mov_b32_e32 v31, v131
	v_mov_b32_e32 v16, v131
	v_mov_b32_e32 v17, v131
	v_mov_b32_e32 v18, v131
	v_mov_b32_e32 v19, v131
	v_mov_b32_e32 v20, v131
	v_mov_b32_e32 v21, v131
	v_mov_b32_e32 v22, v131
	v_mov_b32_e32 v23, v131
	v_mov_b32_e32 v8, v131
	v_mov_b32_e32 v9, v131
	v_mov_b32_e32 v10, v131
	v_mov_b32_e32 v11, v131
	v_mov_b32_e32 v12, v131
	v_mov_b32_e32 v13, v131
	v_mov_b32_e32 v14, v131
	v_mov_b32_e32 v15, v131
	v_mov_b32_e32 v0, v131
	v_mov_b32_e32 v1, v131
	v_mov_b32_e32 v2, v131
	v_mov_b32_e32 v3, v131
	v_mov_b32_e32 v4, v131
	v_mov_b32_e32 v5, v131
	v_mov_b32_e32 v6, v131
	v_mov_b32_e32 v7, v131
	v_mov_b32_e32 v88, v131
	v_mov_b32_e32 v89, v131
	v_mov_b32_e32 v90, v131
	v_mov_b32_e32 v91, v131
	v_mov_b32_e32 v92, v131
	v_mov_b32_e32 v93, v131
	v_mov_b32_e32 v94, v131
	v_mov_b32_e32 v95, v131
	v_mov_b32_e32 v80, v131
	v_mov_b32_e32 v81, v131
	v_mov_b32_e32 v82, v131
	v_mov_b32_e32 v83, v131
	v_mov_b32_e32 v84, v131
	v_mov_b32_e32 v85, v131
	v_mov_b32_e32 v86, v131
	v_mov_b32_e32 v87, v131
	v_mov_b32_e32 v64, v131
	v_mov_b32_e32 v65, v131
	v_mov_b32_e32 v66, v131
	v_mov_b32_e32 v67, v131
	v_mov_b32_e32 v68, v131
	v_mov_b32_e32 v69, v131
	v_mov_b32_e32 v70, v131
	v_mov_b32_e32 v71, v131
	v_mov_b32_e32 v48, v131
	v_mov_b32_e32 v49, v131
	v_mov_b32_e32 v50, v131
	v_mov_b32_e32 v51, v131
	v_mov_b32_e32 v52, v131
	v_mov_b32_e32 v53, v131
	v_mov_b32_e32 v54, v131
	v_mov_b32_e32 v55, v131
	s_barrier
	s_nop 0
;     __device__ bool next(int i, Unit& u) const { if (i != 0) return false; return so.next(round, u); }
;     __device__ __forceinline__ bool next(int i, Unit& u) const { if (i > 0 || !on) return false; u.pm = pm; u.pn = 0; return true; }
; #define PG8_STAGE(bufoff, gbase, voff) do { _Pragma("unroll") for (int _i = 0; _i < 2; ++_i) \
;         __builtin_amdgcn_global_load_lds((const unsigned*)((const char*)(gbase) + (voff)[_i]), (PG8_LAS unsigned*)(lds + (bufoff) + ldsw + _i * 8192), 16, 0, 0); } while (0)
; #define PG8_LDA(dst, b, h) do { _Pragma("unroll") for (int m = 0; m < 4; ++m) _Pragma("unroll") for (int k = 0; k < 2; ++k) dst[m][k] = *(const PG8_LAS bf16x8*)(lds + PG8_SA(b, h) + aoff + m * 2048 + k * 1024); } while (0)
; #define PG8_LDB(dst, b, h) do { _Pragma("unroll") for (int n = 0; n < 2; ++n) _Pragma("unroll") for (int k = 0; k < 2; ++k) dst[n][k] = *(const PG8_LAS bf16x8*)(lds + PG8_SB(b, h) + boff + n * 2048 + k * 1024); } while (0)
; #define PG8_BAR __builtin_amdgcn_s_barrier()
; template <class Epi, class Sched, bool ALIGN_EPI = false, bool SP2 = false, bool MIDHOOK = false>
; __device__ __forceinline__ void gemm_phase(PG8_LAS unsigned char* lds, const Gemm g, const Sched& S, const Epi& E) {
;     ...
;         const bool has_next = S.next(ui + 1, nxt);
;         const char* nA = has_next ? (const char*)g.A + (size_t)nxt.pm * tstep : cA; const char* nB = has_next ? (const char*)g.Bt + (size_t)nxt.pn * tstep : cB;
;         for (int t = 0; t < nt; t += 2) {
;             if constexpr (MIDHOOK) { if (t == nt / 2) E.mid(acc, cur, wr, wc, fr, fq); }
;             const bool last = (t == nt - 2);
;             const char* a1 = cA + (size_t)(t + 1) * kstep;
;             const char* a2 = last ? nA : cA + (size_t)(t + 2) * kstep; const char* b2 = last ? nB : cB + (size_t)(t + 2) * kstep;
;             const char* a3 = a2 + kstep; const char* b3 = b2 + kstep;
;             if (last && has_next) S.a_ready(nxt);
;             if constexpr (SP2) {
;             PG8_LDB(B0, 0, 0); PG8_LDB(B1, 0, 1); PG8_SCHED; PG8_LDA(At, 0, 0); PG8_STAGE(PG8_SA(1, 1), a1 + hstep, voffA);
;             PG8_WAIT_V(8); PG8_WAIT_L(0); PG8_BAR; PG8_MMA(0, 0, At, B0); PG8_MMA(0, 1, At, B1); PG8_BAR; PG8_SCHED;
;             PG8_LDA(At, 0, 1); PG8_STAGE(PG8_SB(0, 0), b2, voffB); PG8_STAGE(PG8_SB(0, 1), b2 + hstep, voffB); PG8_STAGE(PG8_SA(0, 0), a2, voffA);
.LBB0_4175:
	ds_read_b128 v[148:151], v141
	ds_read_b128 v[158:161], v141 offset:1024
	ds_read_b128 v[162:165], v141 offset:2048
	ds_read_b128 v[166:169], v141 offset:3072
	ds_read_b128 v[170:173], v142
	ds_read_b128 v[174:177], v142 offset:1024
	ds_read_b128 v[178:181], v142 offset:2048
	ds_read_b128 v[182:185], v142 offset:3072
	s_add_u32 s26, s22, s24
	s_addc_u32 s27, s23, s25
	s_add_u32 s26, s26, 0xe000100
	s_addc_u32 s27, s27, 0
	s_add_u32 s50, s37, s24
	s_addc_u32 s51, s38, s25
	s_cmpk_eq_i32 s24, 0x1f00
	s_cselect_b32 s29, s7, s27
	s_cselect_b32 s28, s6, s26
	s_cselect_b32 s27, s1, s51
	s_cselect_b32 s26, s0, s50
	s_mov_b32 m0, s40
	v_lshl_add_u64 v[152:153], v[136:137], 0, s[24:25]
	ds_read_b128 v[186:189], v143
	ds_read_b128 v[190:193], v143 offset:1024
	ds_read_b128 v[194:197], v143 offset:2048
	ds_read_b128 v[198:201], v143 offset:3072
	ds_read_b128 v[202:205], v143 offset:4096
	ds_read_b128 v[206:209], v143 offset:5120
	ds_read_b128 v[210:213], v143 offset:6144
	ds_read_b128 v[214:217], v143 offset:7168
	global_load_lds_dwordx4 v[152:153], off
	v_lshl_add_u64 v[152:153], v[138:139], 0, s[24:25]
	s_mov_b32 m0, s41
	s_nop 0
	global_load_lds_dwordx4 v[152:153], off
	s_waitcnt vmcnt(8)
	s_waitcnt lgkmcnt(0)
	s_barrier
	s_setprio 1
	s_waitcnt lgkmcnt(0)
	v_mfma_f32_16x16x32_bf16 v[52:55], v[148:151], v[186:189], v[52:55]
	v_mfma_f32_16x16x32_bf16 v[48:51], v[162:165], v[186:189], v[48:51]
	v_mfma_f32_16x16x32_bf16 v[68:71], v[148:151], v[194:197], v[68:71]
	v_mfma_f32_16x16x32_bf16 v[64:67], v[162:165], v[194:197], v[64:67]
	v_mfma_f32_16x16x32_bf16 v[84:87], v[148:151], v[202:205], v[84:87]
	v_mfma_f32_16x16x32_bf16 v[80:83], v[162:165], v[202:205], v[80:83]
	v_mfma_f32_16x16x32_bf16 v[92:95], v[148:151], v[210:213], v[92:95]
	v_mfma_f32_16x16x32_bf16 v[88:91], v[162:165], v[210:213], v[88:91]
	v_mfma_f32_16x16x32_bf16 v[52:55], v[158:161], v[190:193], v[52:55]
	v_mfma_f32_16x16x32_bf16 v[48:51], v[166:169], v[190:193], v[48:51]
	v_mfma_f32_16x16x32_bf16 v[68:71], v[158:161], v[198:201], v[68:71]
	v_mfma_f32_16x16x32_bf16 v[64:67], v[166:169], v[198:201], v[64:67]
	v_mfma_f32_16x16x32_bf16 v[84:87], v[158:161], v[206:209], v[84:87]
	v_mfma_f32_16x16x32_bf16 v[80:83], v[166:169], v[206:209], v[80:83]
	v_mfma_f32_16x16x32_bf16 v[92:95], v[158:161], v[214:217], v[92:95]
	v_mfma_f32_16x16x32_bf16 v[88:91], v[166:169], v[214:217], v[88:91]
	s_setprio 0
	s_setprio 1
	v_mfma_f32_16x16x32_bf16 v[4:7], v[170:173], v[186:189], v[4:7]
	v_mfma_f32_16x16x32_bf16 v[0:3], v[178:181], v[186:189], v[0:3]
	v_mfma_f32_16x16x32_bf16 v[12:15], v[170:173], v[194:197], v[12:15]
	v_mfma_f32_16x16x32_bf16 v[8:11], v[178:181], v[194:197], v[8:11]
	v_mfma_f32_16x16x32_bf16 v[20:23], v[170:173], v[202:205], v[20:23]
	v_mfma_f32_16x16x32_bf16 v[16:19], v[178:181], v[202:205], v[16:19]
	v_mfma_f32_16x16x32_bf16 v[28:31], v[170:173], v[210:213], v[28:31]
	v_mfma_f32_16x16x32_bf16 v[24:27], v[178:181], v[210:213], v[24:27]
	v_mfma_f32_16x16x32_bf16 v[4:7], v[174:177], v[190:193], v[4:7]
	v_mfma_f32_16x16x32_bf16 v[0:3], v[182:185], v[190:193], v[0:3]
	v_mfma_f32_16x16x32_bf16 v[12:15], v[174:177], v[198:201], v[12:15]
	v_mfma_f32_16x16x32_bf16 v[8:11], v[182:185], v[198:201], v[8:11]
	v_mfma_f32_16x16x32_bf16 v[20:23], v[174:177], v[206:209], v[20:23]
	v_mfma_f32_16x16x32_bf16 v[16:19], v[182:185], v[206:209], v[16:19]
	v_mfma_f32_16x16x32_bf16 v[28:31], v[174:177], v[214:217], v[28:31]
	v_mfma_f32_16x16x32_bf16 v[24:27], v[182:185], v[214:217], v[24:27]
	s_setprio 0
	s_barrier
	s_mov_b32 m0, s42
	v_lshl_add_u64 v[152:153], s[26:27], 0, v[130:131]
	s_add_u32 s50, s26, 0x100000
	ds_read_b128 v[186:189], v143 offset:16384
	ds_read_b128 v[190:193], v143 offset:17408
	ds_read_b128 v[194:197], v143 offset:18432
	ds_read_b128 v[198:201], v143 offset:19456
	ds_read_b128 v[202:205], v143 offset:20480
	ds_read_b128 v[206:209], v143 offset:21504
	ds_read_b128 v[210:213], v143 offset:22528
	ds_read_b128 v[214:217], v143 offset:23552
	global_load_lds_dwordx4 v[152:153], off
	v_lshl_add_u64 v[218:219], s[26:27], 0, v[134:135]
	s_mov_b32 m0, s43
	s_addc_u32 s51, s27, 0
	global_load_lds_dwordx4 v[218:219], off
	v_lshl_add_u64 v[222:223], s[50:51], 0, v[130:131]
	s_mov_b32 m0, s44
	v_lshl_add_u64 v[224:225], s[28:29], 0, v[132:133]
	global_load_lds_dwordx4 v[222:223], off
	v_lshl_add_u64 v[222:223], s[50:51], 0, v[134:135]
	s_mov_b32 m0, s45
	s_nop 0
	global_load_lds_dwordx4 v[222:223], off
	v_lshl_add_u64 v[222:223], s[28:29], 0, v[128:129]
	s_mov_b32 m0, s30
	s_nop 0
	global_load_lds_dwordx4 v[222:223], off
	s_mov_b32 m0, s31
	s_nop 0
	global_load_lds_dwordx4 v[224:225], off
	s_waitcnt vmcnt(8)
	s_waitcnt lgkmcnt(0)
	s_barrier
; #define PG8_STAGE(bufoff, gbase, voff) do { _Pragma("unroll") for (int _i = 0; _i < 2; ++_i) \
;         __builtin_amdgcn_global_load_lds((const unsigned*)((const char*)(gbase) + (voff)[_i]), (PG8_LAS unsigned*)(lds + (bufoff) + ldsw + _i * 8192), 16, 0, 0); } while (0)
; #define PG8_LDA(dst, b, h) do { _Pragma("unroll") for (int m = 0; m < 4; ++m) _Pragma("unroll") for (int k = 0; k < 2; ++k) dst[m][k] = *(const PG8_LAS bf16x8*)(lds + PG8_SA(b, h) + aoff + m * 2048 + k * 1024); } while (0)
; #define PG8_LDB(dst, b, h) do { _Pragma("unroll") for (int n = 0; n < 2; ++n) _Pragma("unroll") for (int k = 0; k < 2; ++k) dst[n][k] = *(const PG8_LAS bf16x8*)(lds + PG8_SB(b, h) + boff + n * 2048 + k * 1024); } while (0)
; #define PG8_MMA(ai, bj, At, Bt) do { __builtin_amdgcn_s_setprio(1); _Pragma("unroll") for (int m = 0; m < 4; ++m) _Pragma("unroll") for (int n = 0; n < 2; ++n) _Pragma("unroll") for (int k = 0; k < 2; ++k) \
;         acc[ai][bj][m][n] = __builtin_amdgcn_mfma_f32_16x16x32_bf16(Bt[n][k], At[m][k], acc[ai][bj][m][n], 0, 0, 0); __builtin_amdgcn_s_setprio(0); } while (0)
; #define PG8_WAIT_V(n) asm volatile("s_waitcnt vmcnt(" #n ")" ::: "memory")
; #define PG8_WAIT_L(n) asm volatile("s_waitcnt lgkmcnt(" #n ")" ::: "memory")
; #define PG8_BAR __builtin_amdgcn_s_barrier()
; #define PG8_SCHED __builtin_amdgcn_sched_barrier(0)
; template <class Epi, class Sched, bool ALIGN_EPI = false, bool SP2 = false, bool MIDHOOK = false>
; __device__ __forceinline__ void gemm_phase(PG8_LAS unsigned char* lds, const Gemm g, const Sched& S, const Epi& E) {
;     ...
;             PG8_WAIT_V(8); PG8_WAIT_L(0); PG8_BAR; PG8_MMA(1, 0, At, B0); PG8_MMA(1, 1, At, B1); PG8_BAR; PG8_SCHED;
;             PG8_LDB(B0, 1, 0); PG8_LDB(B1, 1, 1); PG8_SCHED; PG8_LDA(At, 1, 0); PG8_STAGE(PG8_SA(0, 1), a2 + hstep, voffA);
;             PG8_WAIT_V(8); PG8_WAIT_L(0); PG8_BAR; PG8_MMA(0, 0, At, B0); PG8_MMA(0, 1, At, B1); PG8_BAR; PG8_SCHED;
	s_setprio 1
	s_waitcnt lgkmcnt(0)
	v_mfma_f32_16x16x32_bf16 v[100:103], v[148:151], v[186:189], v[100:103]
	v_mfma_f32_16x16x32_bf16 v[96:99], v[162:165], v[186:189], v[96:99]
	v_mfma_f32_16x16x32_bf16 v[108:111], v[148:151], v[194:197], v[108:111]
	v_mfma_f32_16x16x32_bf16 v[104:107], v[162:165], v[194:197], v[104:107]
	v_mfma_f32_16x16x32_bf16 v[124:127], v[148:151], v[202:205], v[124:127]
	v_mfma_f32_16x16x32_bf16 v[112:115], v[162:165], v[202:205], v[112:115]
	v_mfma_f32_16x16x32_bf16 v[120:123], v[148:151], v[210:213], v[120:123]
	v_mfma_f32_16x16x32_bf16 v[116:119], v[162:165], v[210:213], v[116:119]
	v_mfma_f32_16x16x32_bf16 v[100:103], v[158:161], v[190:193], v[100:103]
	v_mfma_f32_16x16x32_bf16 v[96:99], v[166:169], v[190:193], v[96:99]
	v_mfma_f32_16x16x32_bf16 v[108:111], v[158:161], v[198:201], v[108:111]
	v_mfma_f32_16x16x32_bf16 v[104:107], v[166:169], v[198:201], v[104:107]
	v_mfma_f32_16x16x32_bf16 v[124:127], v[158:161], v[206:209], v[124:127]
	v_mfma_f32_16x16x32_bf16 v[112:115], v[166:169], v[206:209], v[112:115]
	v_mfma_f32_16x16x32_bf16 v[120:123], v[158:161], v[214:217], v[120:123]
	v_mfma_f32_16x16x32_bf16 v[116:119], v[166:169], v[214:217], v[116:119]
	s_setprio 0
	s_setprio 1
	v_mfma_f32_16x16x32_bf16 v[36:39], v[170:173], v[186:189], v[36:39]
	v_mfma_f32_16x16x32_bf16 v[32:35], v[178:181], v[186:189], v[32:35]
	v_mfma_f32_16x16x32_bf16 v[44:47], v[170:173], v[194:197], v[44:47]
	v_mfma_f32_16x16x32_bf16 v[40:43], v[178:181], v[194:197], v[40:43]
	v_mfma_f32_16x16x32_bf16 v[60:63], v[170:173], v[202:205], v[60:63]
	v_mfma_f32_16x16x32_bf16 v[56:59], v[178:181], v[202:205], v[56:59]
	v_mfma_f32_16x16x32_bf16 v[76:79], v[170:173], v[210:213], v[76:79]
	v_mfma_f32_16x16x32_bf16 v[72:75], v[178:181], v[210:213], v[72:75]
	v_mfma_f32_16x16x32_bf16 v[36:39], v[174:177], v[190:193], v[36:39]
	v_mfma_f32_16x16x32_bf16 v[32:35], v[182:185], v[190:193], v[32:35]
	v_mfma_f32_16x16x32_bf16 v[44:47], v[174:177], v[198:201], v[44:47]
	v_mfma_f32_16x16x32_bf16 v[40:43], v[182:185], v[198:201], v[40:43]
	v_mfma_f32_16x16x32_bf16 v[60:63], v[174:177], v[206:209], v[60:63]
	v_mfma_f32_16x16x32_bf16 v[56:59], v[182:185], v[206:209], v[56:59]
	v_mfma_f32_16x16x32_bf16 v[76:79], v[174:177], v[214:217], v[76:79]
	v_mfma_f32_16x16x32_bf16 v[72:75], v[182:185], v[214:217], v[72:75]
	s_setprio 0
	s_barrier
	ds_read_b128 v[148:151], v144
	ds_read_b128 v[158:161], v144 offset:1024
	ds_read_b128 v[162:165], v144 offset:2048
	ds_read_b128 v[166:169], v144 offset:3072
	ds_read_b128 v[170:173], v145
	ds_read_b128 v[174:177], v145 offset:1024
	ds_read_b128 v[178:181], v145 offset:2048
	ds_read_b128 v[182:185], v145 offset:3072
	s_add_u32 s28, s28, 0x100000
	s_addc_u32 s29, s29, 0
	s_mov_b32 m0, s33
	v_lshl_add_u64 v[226:227], s[28:29], 0, v[128:129]
	ds_read_b128 v[186:189], v143 offset:32768
	ds_read_b128 v[190:193], v143 offset:33792
	ds_read_b128 v[194:197], v143 offset:34816
	ds_read_b128 v[198:201], v143 offset:35840
	ds_read_b128 v[202:205], v143 offset:36864
	ds_read_b128 v[206:209], v143 offset:37888
	ds_read_b128 v[210:213], v143 offset:38912
	ds_read_b128 v[214:217], v143 offset:39936
	global_load_lds_dwordx4 v[226:227], off
	v_lshl_add_u64 v[226:227], s[28:29], 0, v[132:133]
	s_mov_b32 m0, s34
	s_nop 0
	global_load_lds_dwordx4 v[226:227], off
	s_waitcnt vmcnt(8)
	s_waitcnt lgkmcnt(0)
	s_barrier
	s_setprio 1
	s_waitcnt lgkmcnt(0)
	v_mfma_f32_16x16x32_bf16 v[52:55], v[148:151], v[186:189], v[52:55]
	v_mfma_f32_16x16x32_bf16 v[48:51], v[162:165], v[186:189], v[48:51]
	v_mfma_f32_16x16x32_bf16 v[68:71], v[148:151], v[194:197], v[68:71]
	v_mfma_f32_16x16x32_bf16 v[64:67], v[162:165], v[194:197], v[64:67]
	v_mfma_f32_16x16x32_bf16 v[84:87], v[148:151], v[202:205], v[84:87]
	v_mfma_f32_16x16x32_bf16 v[80:83], v[162:165], v[202:205], v[80:83]
	v_mfma_f32_16x16x32_bf16 v[92:95], v[148:151], v[210:213], v[92:95]
	v_mfma_f32_16x16x32_bf16 v[88:91], v[162:165], v[210:213], v[88:91]
	v_mfma_f32_16x16x32_bf16 v[52:55], v[158:161], v[190:193], v[52:55]
	v_mfma_f32_16x16x32_bf16 v[48:51], v[166:169], v[190:193], v[48:51]
	v_mfma_f32_16x16x32_bf16 v[68:71], v[158:161], v[198:201], v[68:71]
	v_mfma_f32_16x16x32_bf16 v[64:67], v[166:169], v[198:201], v[64:67]
	v_mfma_f32_16x16x32_bf16 v[84:87], v[158:161], v[206:209], v[84:87]
	v_mfma_f32_16x16x32_bf16 v[80:83], v[166:169], v[206:209], v[80:83]
	v_mfma_f32_16x16x32_bf16 v[92:95], v[158:161], v[214:217], v[92:95]
	v_mfma_f32_16x16x32_bf16 v[88:91], v[166:169], v[214:217], v[88:91]
	s_setprio 0
	s_setprio 1
	v_mfma_f32_16x16x32_bf16 v[4:7], v[170:173], v[186:189], v[4:7]
	v_mfma_f32_16x16x32_bf16 v[0:3], v[178:181], v[186:189], v[0:3]
	v_mfma_f32_16x16x32_bf16 v[12:15], v[170:173], v[194:197], v[12:15]
	v_mfma_f32_16x16x32_bf16 v[8:11], v[178:181], v[194:197], v[8:11]
	v_mfma_f32_16x16x32_bf16 v[20:23], v[170:173], v[202:205], v[20:23]
	v_mfma_f32_16x16x32_bf16 v[16:19], v[178:181], v[202:205], v[16:19]
	v_mfma_f32_16x16x32_bf16 v[28:31], v[170:173], v[210:213], v[28:31]
	v_mfma_f32_16x16x32_bf16 v[24:27], v[178:181], v[210:213], v[24:27]
	v_mfma_f32_16x16x32_bf16 v[4:7], v[174:177], v[190:193], v[4:7]
	v_mfma_f32_16x16x32_bf16 v[0:3], v[182:185], v[190:193], v[0:3]
	v_mfma_f32_16x16x32_bf16 v[12:15], v[174:177], v[198:201], v[12:15]
	v_mfma_f32_16x16x32_bf16 v[8:11], v[182:185], v[198:201], v[8:11]
	v_mfma_f32_16x16x32_bf16 v[20:23], v[174:177], v[206:209], v[20:23]
	v_mfma_f32_16x16x32_bf16 v[16:19], v[182:185], v[206:209], v[16:19]
	v_mfma_f32_16x16x32_bf16 v[28:31], v[174:177], v[214:217], v[28:31]
	v_mfma_f32_16x16x32_bf16 v[24:27], v[182:185], v[214:217], v[24:27]
	s_setprio 0
	s_barrier
; #define PG8_STAGE(bufoff, gbase, voff) do { _Pragma("unroll") for (int _i = 0; _i < 2; ++_i) \
;         __builtin_amdgcn_global_load_lds((const unsigned*)((const char*)(gbase) + (voff)[_i]), (PG8_LAS unsigned*)(lds + (bufoff) + ldsw + _i * 8192), 16, 0, 0); } while (0)
; #define PG8_LDA(dst, b, h) do { _Pragma("unroll") for (int m = 0; m < 4; ++m) _Pragma("unroll") for (int k = 0; k < 2; ++k) dst[m][k] = *(const PG8_LAS bf16x8*)(lds + PG8_SA(b, h) + aoff + m * 2048 + k * 1024); } while (0)
; #define PG8_MMA(ai, bj, At, Bt) do { __builtin_amdgcn_s_setprio(1); _Pragma("unroll") for (int m = 0; m < 4; ++m) _Pragma("unroll") for (int n = 0; n < 2; ++n) _Pragma("unroll") for (int k = 0; k < 2; ++k) \
;         acc[ai][bj][m][n] = __builtin_amdgcn_mfma_f32_16x16x32_bf16(Bt[n][k], At[m][k], acc[ai][bj][m][n], 0, 0, 0); __builtin_amdgcn_s_setprio(0); } while (0)
; #define PG8_WAIT_V(n) asm volatile("s_waitcnt vmcnt(" #n ")" ::: "memory")
; #define PG8_WAIT_L(n) asm volatile("s_waitcnt lgkmcnt(" #n ")" ::: "memory")
; #define PG8_BAR __builtin_amdgcn_s_barrier()
; #define PG8_SCHED __builtin_amdgcn_sched_barrier(0)
; template <class Epi, class Sched, bool ALIGN_EPI = false, bool SP2 = false, bool MIDHOOK = false>
; __device__ __forceinline__ void gemm_phase(PG8_LAS unsigned char* lds, const Gemm g, const Sched& S, const Epi& E) {
;     ...
;             PG8_LDA(At, 1, 1); PG8_STAGE(PG8_SB(1, 0), b3, voffB); PG8_STAGE(PG8_SB(1, 1), b3 + hstep, voffB); PG8_STAGE(PG8_SA(1, 0), a3, voffA);
;             PG8_WAIT_V(8); PG8_WAIT_L(0); PG8_BAR; PG8_MMA(1, 0, At, B0); PG8_MMA(1, 1, At, B1); PG8_BAR; PG8_SCHED;
;     ...
;     PG8_WAIT_V(0);
;     if constexpr (!ALIGN_EPI) { if (wr == 0) PG8_BAR; }
;     PG8_BAR;
	s_mov_b32 m0, s46
	v_lshl_add_u64 v[152:153], v[152:153], 0, s[8:9]
	s_add_u32 s26, s26, 0x100080
	ds_read_b128 v[186:189], v143 offset:49152
	ds_read_b128 v[190:193], v143 offset:50176
	ds_read_b128 v[194:197], v143 offset:51200
	ds_read_b128 v[198:201], v143 offset:52224
	ds_read_b128 v[202:205], v143 offset:53248
	ds_read_b128 v[206:209], v143 offset:54272
	ds_read_b128 v[210:213], v143 offset:55296
	ds_read_b128 v[214:217], v143 offset:56320
	global_load_lds_dwordx4 v[152:153], off
	v_lshl_add_u64 v[152:153], v[218:219], 0, s[8:9]
	s_mov_b32 m0, s47
	s_addc_u32 s27, s27, 0
	global_load_lds_dwordx4 v[152:153], off
	v_lshl_add_u64 v[152:153], s[26:27], 0, v[130:131]
	s_mov_b32 m0, s48
	s_nop 0
	global_load_lds_dwordx4 v[152:153], off
	v_lshl_add_u64 v[152:153], s[26:27], 0, v[134:135]
	s_mov_b32 m0, s49
	s_nop 0
	global_load_lds_dwordx4 v[152:153], off
	v_lshl_add_u64 v[152:153], v[222:223], 0, s[8:9]
	s_mov_b32 m0, s35
	s_nop 0
	global_load_lds_dwordx4 v[152:153], off
	v_lshl_add_u64 v[152:153], v[224:225], 0, s[8:9]
	s_mov_b32 m0, s36
	s_nop 0
	global_load_lds_dwordx4 v[152:153], off
	s_waitcnt vmcnt(8)
	s_waitcnt lgkmcnt(0)
	s_barrier
	s_setprio 1
	s_waitcnt lgkmcnt(0)
	v_mfma_f32_16x16x32_bf16 v[100:103], v[148:151], v[186:189], v[100:103]
	v_mfma_f32_16x16x32_bf16 v[96:99], v[162:165], v[186:189], v[96:99]
	v_mfma_f32_16x16x32_bf16 v[108:111], v[148:151], v[194:197], v[108:111]
	v_mfma_f32_16x16x32_bf16 v[104:107], v[162:165], v[194:197], v[104:107]
	v_mfma_f32_16x16x32_bf16 v[124:127], v[148:151], v[202:205], v[124:127]
	v_mfma_f32_16x16x32_bf16 v[112:115], v[162:165], v[202:205], v[112:115]
	v_mfma_f32_16x16x32_bf16 v[120:123], v[148:151], v[210:213], v[120:123]
	v_mfma_f32_16x16x32_bf16 v[116:119], v[162:165], v[210:213], v[116:119]
	v_mfma_f32_16x16x32_bf16 v[100:103], v[158:161], v[190:193], v[100:103]
	v_mfma_f32_16x16x32_bf16 v[96:99], v[166:169], v[190:193], v[96:99]
	v_mfma_f32_16x16x32_bf16 v[108:111], v[158:161], v[198:201], v[108:111]
	v_mfma_f32_16x16x32_bf16 v[104:107], v[166:169], v[198:201], v[104:107]
	v_mfma_f32_16x16x32_bf16 v[124:127], v[158:161], v[206:209], v[124:127]
	v_mfma_f32_16x16x32_bf16 v[112:115], v[166:169], v[206:209], v[112:115]
	v_mfma_f32_16x16x32_bf16 v[120:123], v[158:161], v[214:217], v[120:123]
	v_mfma_f32_16x16x32_bf16 v[116:119], v[166:169], v[214:217], v[116:119]
	s_setprio 0
	s_setprio 1
	v_mfma_f32_16x16x32_bf16 v[36:39], v[170:173], v[186:189], v[36:39]
	v_mfma_f32_16x16x32_bf16 v[32:35], v[178:181], v[186:189], v[32:35]
	v_mfma_f32_16x16x32_bf16 v[44:47], v[170:173], v[194:197], v[44:47]
	v_mfma_f32_16x16x32_bf16 v[40:43], v[178:181], v[194:197], v[40:43]
	v_mfma_f32_16x16x32_bf16 v[60:63], v[170:173], v[202:205], v[60:63]
	v_mfma_f32_16x16x32_bf16 v[56:59], v[178:181], v[202:205], v[56:59]
	v_mfma_f32_16x16x32_bf16 v[76:79], v[170:173], v[210:213], v[76:79]
	v_mfma_f32_16x16x32_bf16 v[72:75], v[178:181], v[210:213], v[72:75]
	v_mfma_f32_16x16x32_bf16 v[36:39], v[174:177], v[190:193], v[36:39]
	v_mfma_f32_16x16x32_bf16 v[32:35], v[182:185], v[190:193], v[32:35]
	v_mfma_f32_16x16x32_bf16 v[44:47], v[174:177], v[198:201], v[44:47]
	v_mfma_f32_16x16x32_bf16 v[40:43], v[182:185], v[198:201], v[40:43]
	v_mfma_f32_16x16x32_bf16 v[60:63], v[174:177], v[206:209], v[60:63]
	v_mfma_f32_16x16x32_bf16 v[56:59], v[182:185], v[206:209], v[56:59]
	v_mfma_f32_16x16x32_bf16 v[76:79], v[174:177], v[214:217], v[76:79]
	v_mfma_f32_16x16x32_bf16 v[72:75], v[182:185], v[214:217], v[72:75]
	s_setprio 0
	s_barrier
	s_add_i32 s39, s39, 2
	s_add_u32 s24, s24, 0x100
	s_addc_u32 s25, s25, 0
	s_cmp_lt_u32 s39, 62
	s_cbranch_scc1 .LBB0_4175
	s_waitcnt vmcnt(0)
	s_cmp_gt_u32 s84, 3
	s_cbranch_scc1 .LBB0_4178
	s_barrier
